# scan operand arrays head-major ([head][row][128]): in-proj epilogue store addresses and scan loader; 16 KB contiguous per chunk and head
# speedup vs baseline: 1.0131x; 1.0116x over previous
;     __device__ __forceinline__ void operator()(const f32x4 (&acc)[2][2][4][2], const pg8::Unit& u, int wr, int wc, int fr, int fq) const {
;     ...
;         const int row0 = u.pm * 256 + wr * 64 + fr, pn = u.pn;
;         if (pn < 8) {
;             bf16_t* QF = (bf16_t*)(ws + WS_QF); bf16_t* QB = (bf16_t*)(ws + WS_QB); bf16_t* KF = (bf16_t*)(ws + WS_KF); bf16_t* KB = (bf16_t*)(ws + WS_KB); bf16_t* V = (bf16_t*)(ws + WS_V);
;             float* RT = (float*)(ws + WS_RT);
;             const int ch0 = 64 * pn + 16 * wc + 4 * fq;
;             float lbF[4], lbB[4];
; #pragma unroll
;             for (int j = 0; j < 4; ++j) { lbF[j] = 1.f / (1.f + __expf(lb_logits[1024 + ch0 + j] - lb_logits[ch0 + j])); lbB[j] = 1.f / (1.f + __expf(lb_logits[1536 + ch0 + j] - lb_logits[512 + ch0 + j])); }
; #pragma unroll
;             for (int ai = 0; ai < 2; ++ai) {
;                 const int rowc = u.pm * 256 + 128 * ai + 64 * wr;
;                 const int cid = rowc >> 6;
;                 unsigned oQF[4][2], oQB[4][2], oKF[4][2], oKB[4][2]; f32x4 rtv[4];
; #pragma unroll
;                 for (int jp = 0; jp < 2; ++jp) {
;                     float vQF[4][2], vQB[4][2], vKF[4][2], vKB[4][2];
; #pragma unroll
;                     for (int jj = 0; jj < 2; ++jj) {
;                         const int j = 2 * jp + jj;
;                         float lfF[4], kkF[4], lfB[4], kkB[4], pF[4], pB[4], tF[4], tB[4];
; #pragma unroll
;                         for (int m = 0; m < 4; ++m) {
;                             { const float z = acc[ai][0][m][1][j]; const float e = __expf(fminf(-z, 30.f)); const float s = __builtin_amdgcn_rcpf(1.f + e); lfF[m] = __logf(lbF[j] + (1.f - lbF[j]) * s); kkF[m] = (1.f - lbF[j]) * e * s; }
;                             { const float z = acc[ai][1][m][0][j]; const float e = __expf(fminf(-z, 30.f)); const float s = __builtin_amdgcn_rcpf(1.f + e); lfB[m] = __logf(lbB[j] + (1.f - lbB[j]) * s); kkB[m] = (1.f - lbB[j]) * e * s; }
.LBB0_193:
	v_lshl_or_b32 v176, s10, 6, v185
	s_and_b32 s4, s10, 1
	s_lshr_b32 s5, s10, 1
	s_mul_i32 s5, s5, 0x440000
	v_lshl_or_b32 v254, s4, 6, v185
	v_add_u32_e32 v254, s5, v254
	v_ashrrev_i32_e32 v177, 31, v176
	v_lshlrev_b64 v[146:147], 2, v[176:177]
	v_lshl_add_u64 v[134:135], s[52:53], 0, v[146:147]
	v_add_co_u32_e32 v138, vcc, 0x1000, v134
	s_nop 0
	s_nop 0
	v_addc_co_u32_e32 v139, vcc, 0, v135, vcc
	global_load_dwordx4 v[130:133], v[134:135], off
	s_nop 0
	global_load_dwordx4 v[134:137], v[134:135], off offset:2048
	s_nop 0
	global_load_dwordx4 v[142:145], v[138:139], off
	s_nop 0
	global_load_dwordx4 v[138:141], v[138:139], off offset:2048
	v_max_f32_e32 v126, 0xc1f00000, v126
	v_mul_f32_e32 v126, 0xbfb8aa3b, v126
	v_exp_f32_e32 v126, v126
	v_max_f32_e32 v122, 0xc1f00000, v122
	v_mul_f32_e32 v122, 0xbfb8aa3b, v122
	v_exp_f32_e32 v122, v122
	v_max_f32_e32 v118, 0xc1f00000, v118
	v_mul_f32_e32 v118, 0xbfb8aa3b, v118
	v_max_f32_e32 v114, 0xc1f00000, v114
	v_mul_f32_e32 v114, 0xbfb8aa3b, v114
	v_max_f32_e32 v110, 0xc1f00000, v110
	v_mul_f32_e32 v110, 0xbfb8aa3b, v110
	v_exp_f32_e32 v110, v110
	v_max_f32_e32 v106, 0xc1f00000, v106
	v_mul_f32_e32 v106, 0xbfb8aa3b, v106
	v_exp_f32_e32 v106, v106
	v_max_f32_e32 v102, 0xc1f00000, v102
	v_mul_f32_e32 v102, 0xbfb8aa3b, v102
	v_max_f32_e32 v98, 0xc1f00000, v98
	v_mul_f32_e32 v98, 0xbfb8aa3b, v98
	v_exp_f32_e32 v98, v98
	v_max_f32_e32 v123, 0xc1f00000, v123
	v_mul_f32_e32 v123, 0xbfb8aa3b, v123
	v_exp_f32_e32 v123, v123
	v_max_f32_e32 v119, 0xc1f00000, v119
	v_mul_f32_e32 v119, 0xbfb8aa3b, v119
	v_max_f32_e32 v115, 0xc1f00000, v115
	v_mul_f32_e32 v115, 0xbfb8aa3b, v115
	v_exp_f32_e32 v115, v115
	v_max_f32_e32 v111, 0xc1f00000, v111
	v_mul_f32_e32 v111, 0xbfb8aa3b, v111
	v_add_f32_e32 v201, 1.0, v115
	v_rcp_f32_e32 v202, v201
	v_exp_f32_e32 v111, v111
	v_max_f32_e32 v107, 0xc1f00000, v107
	v_mul_f32_e32 v107, 0xbfb8aa3b, v107
	v_exp_f32_e32 v107, v107
	v_max_f32_e32 v103, 0xc1f00000, v103
	v_mul_f32_e32 v103, 0xbfb8aa3b, v103
	v_add_f32_e32 v206, 1.0, v107
	v_rcp_f32_e32 v207, v206
	v_exp_f32_e32 v103, v103
	v_max_f32_e32 v99, 0xc1f00000, v99
	v_mul_f32_e32 v99, 0xbfb8aa3b, v99
	v_exp_f32_e32 v99, v99
	v_max_f32_e32 v116, 0xc1f00000, v116
	v_mul_f32_e32 v116, 0xbfb8aa3b, v116
	v_add_f32_e32 v211, 1.0, v99
	v_rcp_f32_e32 v211, v211
	v_exp_f32_e32 v116, v116
	v_max_f32_e32 v108, 0xc1f00000, v108
	v_mul_f32_e32 v108, 0xbfb8aa3b, v108
	v_exp_f32_e32 v108, v108
	v_max_f32_e32 v100, 0xc1f00000, v100
	v_mul_f32_e32 v100, 0xbfb8aa3b, v100
	v_exp_f32_e32 v100, v100
	v_max_f32_e32 v117, 0xc1f00000, v117
	v_mul_f32_e32 v117, 0xbfb8aa3b, v117
	v_exp_f32_e32 v117, v117
	s_waitcnt vmcnt(0)
	v_sub_f32_e32 v130, v142, v130
	v_sub_f32_e32 v134, v138, v134
	v_mul_f32_e32 v130, 0x3fb8aa3b, v130
	v_sub_f32_e32 v131, v143, v131
	v_mul_f32_e32 v134, 0x3fb8aa3b, v134
	v_exp_f32_e32 v130, v130
	v_sub_f32_e32 v135, v139, v135
	v_mul_f32_e32 v131, 0x3fb8aa3b, v131
	v_exp_f32_e32 v134, v134
	v_sub_f32_e32 v132, v144, v132
	v_mul_f32_e32 v135, 0x3fb8aa3b, v135
	v_exp_f32_e32 v131, v131
	v_mul_f32_e32 v132, 0x3fb8aa3b, v132
	v_exp_f32_e32 v135, v135
	v_exp_f32_e32 v132, v132
	v_add_f32_e32 v130, 1.0, v130
	v_add_f32_e32 v134, 1.0, v134
	v_div_scale_f32 v138, s[10:11], v130, v130, 1.0
	v_sub_f32_e32 v136, v140, v136
	v_add_f32_e32 v131, 1.0, v131
	v_div_scale_f32 v140, s[10:11], v134, v134, 1.0
	v_rcp_f32_e32 v153, v138
	v_add_f32_e32 v135, 1.0, v135
	v_div_scale_f32 v143, s[12:13], v131, v131, 1.0
	v_rcp_f32_e32 v154, v140
	v_add_f32_e32 v132, 1.0, v132
	v_div_scale_f32 v148, s[14:15], v135, v135, 1.0
	v_rcp_f32_e32 v155, v143
	v_div_scale_f32 v150, s[16:17], v132, v132, 1.0
	v_rcp_f32_e32 v156, v148
	v_rcp_f32_e32 v157, v150
	v_fma_f32 v174, -v138, v153, 1.0
	v_div_scale_f32 v139, vcc, 1.0, v130, 1.0
	v_fma_f32 v175, -v140, v154, 1.0
	v_fmac_f32_e32 v153, v174, v153
	v_div_scale_f32 v142, s[10:11], 1.0, v134, 1.0
	v_fma_f32 v177, -v143, v155, 1.0
	v_fmac_f32_e32 v154, v175, v154
	v_mul_f32_e32 v174, v139, v153
	v_mul_f32_e32 v136, 0x3fb8aa3b, v136
	v_div_scale_f32 v144, s[12:13], 1.0, v131, 1.0
	v_fma_f32 v191, -v148, v156, 1.0
	v_fmac_f32_e32 v155, v177, v155
	v_mul_f32_e32 v175, v142, v154
	v_fma_f32 v193, -v138, v174, v139
	v_exp_f32_e32 v136, v136
	v_div_scale_f32 v149, s[14:15], 1.0, v135, 1.0
	v_fma_f32 v192, -v150, v157, 1.0
	v_fmac_f32_e32 v156, v191, v156
	v_mul_f32_e32 v177, v144, v155
	v_fma_f32 v194, -v140, v175, v142
	v_fmac_f32_e32 v174, v193, v153
	v_div_scale_f32 v151, s[16:17], 1.0, v132, 1.0
	v_fmac_f32_e32 v157, v192, v157
	v_mul_f32_e32 v191, v149, v156
	v_fma_f32 v195, -v143, v177, v144
	v_fmac_f32_e32 v175, v194, v154
	v_fma_f32 v138, -v138, v174, v139
	v_mul_f32_e32 v192, v151, v157
	v_fma_f32 v196, -v148, v191, v149
	v_fmac_f32_e32 v177, v195, v155
	v_fma_f32 v139, -v140, v175, v142
	v_div_fmas_f32 v138, v138, v153, v174
	s_mov_b64 vcc, s[10:11]
	v_fma_f32 v197, -v150, v192, v151
	v_fmac_f32_e32 v191, v196, v156
	v_fma_f32 v140, -v143, v177, v144
	v_div_fixup_f32 v196, v138, v130, 1.0
	v_div_fmas_f32 v130, v139, v154, v175
	s_mov_b64 vcc, s[12:13]
	v_add_f32_e32 v136, 1.0, v136
	v_fmac_f32_e32 v192, v197, v157
	v_fma_f32 v142, -v148, v191, v149
	v_div_fixup_f32 v195, v130, v134, 1.0
	v_div_fmas_f32 v130, v140, v155, v177
	s_mov_b64 vcc, s[14:15]
	v_div_scale_f32 v152, s[98:99], v136, v136, 1.0
	v_fma_f32 v143, -v150, v192, v151
	v_div_fixup_f32 v194, v130, v131, 1.0
	v_div_fmas_f32 v130, v142, v156, v191
	s_mov_b64 vcc, s[16:17]
	v_rcp_f32_e32 v173, v152
	v_div_fixup_f32 v193, v130, v135, 1.0
	v_div_fmas_f32 v130, v143, v157, v192
	v_div_fixup_f32 v177, v130, v132, 1.0
	v_sub_f32_e32 v132, v145, v133
; __device__ __forceinline__ float scan16(float x) { x += dpp_shr<1>(x); x += dpp_shr<2>(x); x += dpp_shr<4>(x); x += dpp_shr<8>(x); return x; }
;     __device__ __forceinline__ void operator()(const f32x4 (&acc)[2][2][4][2], const pg8::Unit& u, int wr, int wc, int fr, int fq) const {
;     ...
;                             { const float z = acc[ai][0][m][1][j]; const float e = __expf(fminf(-z, 30.f)); const float s = __builtin_amdgcn_rcpf(1.f + e); lfF[m] = __logf(lbF[j] + (1.f - lbF[j]) * s); kkF[m] = (1.f - lbF[j]) * e * s; }
;                             { const float z = acc[ai][1][m][0][j]; const float e = __expf(fminf(-z, 30.f)); const float s = __builtin_amdgcn_rcpf(1.f + e); lfB[m] = __logf(lbB[j] + (1.f - lbB[j]) * s); kkB[m] = (1.f - lbB[j]) * e * s; }
;                             pF[m] = scan16(lfF[m]); pB[m] = scan16(lfB[m]);
;                             tF[m] = __int_as_float(__builtin_amdgcn_update_dpp(0, __float_as_int(pF[m]), 0x15F, 0xf, 0xf, true));
;                             tB[m] = __int_as_float(__builtin_amdgcn_update_dpp(0, __float_as_int(pB[m]), 0x15F, 0xf, 0xf, true));
	v_mul_f32_e32 v132, 0x3fb8aa3b, v132
	v_exp_f32_e32 v132, v132
	v_fma_f32 v130, -v152, v173, 1.0
	v_fmac_f32_e32 v173, v130, v173
	v_div_scale_f32 v130, vcc, 1.0, v136, 1.0
	v_mul_f32_e32 v131, v130, v173
	v_fma_f32 v133, -v152, v131, v130
	v_add_f32_e32 v132, 1.0, v132
	v_fmac_f32_e32 v131, v133, v173
	v_div_scale_f32 v133, s[10:11], v132, v132, 1.0
	v_rcp_f32_e32 v134, v133
	v_fma_f32 v130, -v152, v131, v130
	v_div_fmas_f32 v130, v130, v173, v131
	v_sub_f32_e32 v135, v141, v137
	v_div_fixup_f32 v192, v130, v136, 1.0
	v_fma_f32 v130, -v133, v134, 1.0
	v_mul_f32_e32 v135, 0x3fb8aa3b, v135
	v_fmac_f32_e32 v134, v130, v134
	v_div_scale_f32 v130, vcc, 1.0, v132, 1.0
	v_exp_f32_e32 v135, v135
	v_mul_f32_e32 v131, v130, v134
	v_fma_f32 v136, -v133, v131, v130
	v_fmac_f32_e32 v131, v136, v134
	v_fma_f32 v130, -v133, v131, v130
	v_add_f32_e32 v133, 1.0, v135
	v_div_scale_f32 v135, s[10:11], v133, v133, 1.0
	v_rcp_f32_e32 v136, v135
	v_div_fmas_f32 v130, v130, v134, v131
	v_div_fixup_f32 v173, v130, v132, 1.0
	v_sub_f32_e32 v197, 1.0, v196
	v_fma_f32 v130, -v135, v136, 1.0
	v_fmac_f32_e32 v136, v130, v136
	v_div_scale_f32 v130, vcc, 1.0, v133, 1.0
	v_mul_f32_e32 v131, v130, v136
	v_fma_f32 v132, -v135, v131, v130
	v_fmac_f32_e32 v131, v132, v136
	v_add_f32_e32 v132, 1.0, v126
	v_rcp_f32_e32 v132, v132
	v_fma_f32 v130, -v135, v131, v130
	v_div_fmas_f32 v130, v130, v136, v131
	v_div_fixup_f32 v191, v130, v133, 1.0
	v_fma_f32 v131, v132, v197, v196
	v_add_f32_e32 v133, 1.0, v122
	v_rcp_f32_e32 v133, v133
	v_log_f32_e32 v131, v131
	v_sub_f32_e32 v198, 1.0, v195
	v_fma_f32 v134, v133, v198, v195
	v_mul_f32_e32 v126, v126, v197
	v_mul_f32_e32 v138, v132, v126
	v_mul_f32_e32 v122, v122, v198
	v_mul_f32_e32 v130, 0x3f317218, v131
	v_mul_f32_e32 v136, v133, v122
	v_log_f32_e32 v134, v134
	v_add_f32_dpp v122, v130, v130 row_shr:1 row_mask:0xf bank_mask:0xf bound_ctrl:1
	v_add_f32_e32 v142, 1.0, v106
	v_rcp_f32_e32 v142, v142
	v_mul_f32_e32 v106, v106, v198
	v_mul_f32_e32 v126, 0x3f317218, v134
	v_mov_b32_e32 v137, v126
	v_exp_f32_e32 v126, v118
	v_add_f32_dpp v118, v122, v122 row_shr:2 row_mask:0xf bank_mask:0xf bound_ctrl:1
	v_exp_f32_e32 v134, v114
	v_fma_f32 v144, v142, v198, v195
	v_add_f32_dpp v118, v118, v118 row_shr:4 row_mask:0xf bank_mask:0xf bound_ctrl:1
	v_mul_f32_e32 v142, v142, v106
	v_add_f32_e32 v148, 1.0, v98
	v_add_f32_dpp v131, v118, v118 row_shr:8 row_mask:0xf bank_mask:0xf bound_ctrl:1
	v_add_f32_e32 v118, 1.0, v126
	v_rcp_f32_e32 v130, v118
	v_rcp_f32_e32 v149, v148
	v_lshl_add_u64 v[174:175], s[38:39], 0, v[146:147]
	v_mul_f32_e32 v98, v98, v198
	v_fma_f32 v122, v130, v197, v196
	v_fma_f32 v148, v149, v198, v195
	v_sub_f32_e32 v199, 1.0, v194
	v_log_f32_e32 v132, v122
	v_add_f32_dpp v118, v137, v137 row_shr:1 row_mask:0xf bank_mask:0xf bound_ctrl:1
	v_mov_b32_dpp v122, v131 row_newbcast:15 row_mask:0xf bank_mask:0xf bound_ctrl:1
	v_sub_f32_e32 v200, 1.0, v193
	v_add_f32_e32 v133, 1.0, v134
	v_rcp_f32_e32 v133, v133
	s_nop 0
	v_fma_f32 v139, v133, v198, v195
	v_add_f32_dpp v118, v118, v118 row_shr:2 row_mask:0xf bank_mask:0xf bound_ctrl:1
	v_mul_f32_e32 v114, 0x3f317218, v132
	v_mov_b32_e32 v132, v114
	v_mul_f32_e32 v114, v126, v197
	v_log_f32_e32 v139, v139
	v_mul_f32_e32 v114, v130, v114
	v_add_f32_dpp v118, v118, v118 row_shr:4 row_mask:0xf bank_mask:0xf bound_ctrl:1
	s_nop 1
	v_add_f32_dpp v135, v118, v118 row_shr:8 row_mask:0xf bank_mask:0xf bound_ctrl:1
	v_add_f32_e32 v154, 0, v135
	v_mul_f32_e32 v126, 0x3f317218, v139
	v_mov_b32_e32 v140, v126
	v_mul_f32_e32 v126, v134, v198
	v_mul_f32_e32 v139, v133, v126
	v_mov_b32_dpp v118, v135 row_newbcast:15 row_mask:0xf bank_mask:0xf bound_ctrl:1
	v_add_f32_dpp v126, v132, v132 row_shr:1 row_mask:0xf bank_mask:0xf bound_ctrl:1
	v_add_f32_e32 v135, 1.0, v123
	v_rcp_f32_e32 v135, v135
	v_add_f32_dpp v126, v126, v126 row_shr:2 row_mask:0xf bank_mask:0xf bound_ctrl:1
	v_fma_f32 v201, v202, v200, v193
	v_fma_f32 v206, v207, v200, v193
	v_add_f32_dpp v126, v126, v126 row_shr:4 row_mask:0xf bank_mask:0xf bound_ctrl:1
	v_fma_f32 v153, v135, v200, v193
	v_fma_f32 v212, v211, v200, v193
	v_add_f32_dpp v143, v126, v126 row_shr:8 row_mask:0xf bank_mask:0xf bound_ctrl:1
	v_add_f32_e32 v126, 1.0, v110
	v_rcp_f32_e32 v132, v126
	v_mul_f32_e32 v110, v110, v197
	v_add_f32_dpp v126, v140, v140 row_shr:1 row_mask:0xf bank_mask:0xf bound_ctrl:1
	v_max_f32_e32 v109, 0xc1f00000, v109
	v_fma_f32 v130, v132, v197, v196
	v_add_f32_dpp v126, v126, v126 row_shr:2 row_mask:0xf bank_mask:0xf bound_ctrl:1
	v_mul_f32_e32 v109, 0xbfb8aa3b, v109
	v_log_f32_e32 v133, v130
	v_add_f32_dpp v126, v126, v126 row_shr:4 row_mask:0xf bank_mask:0xf bound_ctrl:1
	v_mov_b32_dpp v130, v143 row_newbcast:15 row_mask:0xf bank_mask:0xf bound_ctrl:1
	v_exp_f32_e32 v109, v109
	v_add_f32_dpp v141, v126, v126 row_shr:8 row_mask:0xf bank_mask:0xf bound_ctrl:1
	v_mul_f32_e32 v133, 0x3f317218, v133
	s_nop 0
	v_mov_b32_dpp v126, v141 row_newbcast:15 row_mask:0xf bank_mask:0xf bound_ctrl:1
	v_log_f32_e32 v144, v144
	v_mul_f32_e32 v145, v132, v110
	v_add_f32_dpp v106, v133, v133 row_shr:1 row_mask:0xf bank_mask:0xf bound_ctrl:1
	v_max_f32_e32 v105, 0xc1f00000, v105
	v_mul_f32_e32 v105, 0xbfb8aa3b, v105
	v_mul_f32_e32 v110, 0x3f317218, v144
	v_mov_b32_e32 v144, v110
	v_exp_f32_e32 v110, v102
	v_add_f32_dpp v102, v106, v106 row_shr:2 row_mask:0xf bank_mask:0xf bound_ctrl:1
	v_exp_f32_e32 v105, v105
	v_add_f32_e32 v106, 1.0, v110
	v_rcp_f32_e32 v133, v106
	v_mul_f32_e32 v110, v110, v197
	v_add_f32_dpp v106, v144, v144 row_shr:1 row_mask:0xf bank_mask:0xf bound_ctrl:1
	v_add_f32_dpp v102, v102, v102 row_shr:4 row_mask:0xf bank_mask:0xf bound_ctrl:1
; __device__ __forceinline__ float scan16(float x) { x += dpp_shr<1>(x); x += dpp_shr<2>(x); x += dpp_shr<4>(x); x += dpp_shr<8>(x); return x; }
;     __device__ __forceinline__ void operator()(const f32x4 (&acc)[2][2][4][2], const pg8::Unit& u, int wr, int wc, int fr, int fq) const {
;     ...
;                             { const float z = acc[ai][0][m][1][j]; const float e = __expf(fminf(-z, 30.f)); const float s = __builtin_amdgcn_rcpf(1.f + e); lfF[m] = __logf(lbF[j] + (1.f - lbF[j]) * s); kkF[m] = (1.f - lbF[j]) * e * s; }
;                             { const float z = acc[ai][1][m][0][j]; const float e = __expf(fminf(-z, 30.f)); const float s = __builtin_amdgcn_rcpf(1.f + e); lfB[m] = __logf(lbB[j] + (1.f - lbB[j]) * s); kkB[m] = (1.f - lbB[j]) * e * s; }
;                             pF[m] = scan16(lfF[m]); pB[m] = scan16(lfB[m]);
;                             tF[m] = __int_as_float(__builtin_amdgcn_update_dpp(0, __float_as_int(pF[m]), 0x15F, 0xf, 0xf, true));
;                             tB[m] = __int_as_float(__builtin_amdgcn_update_dpp(0, __float_as_int(pB[m]), 0x15F, 0xf, 0xf, true));
;                         }
;                         const float rF = tF[0] + tF[1], blF = rF + tF[2] + tF[3];
;                         const float rB = tB[2] + tB[3], blB = rB + tB[0] + tB[1];
	v_fma_f32 v132, v133, v197, v196
	v_add_f32_dpp v106, v106, v106 row_shr:2 row_mask:0xf bank_mask:0xf bound_ctrl:1
	v_add_f32_dpp v102, v102, v102 row_shr:8 row_mask:0xf bank_mask:0xf bound_ctrl:1
	v_log_f32_e32 v134, v132
	v_add_f32_dpp v106, v106, v106 row_shr:4 row_mask:0xf bank_mask:0xf bound_ctrl:1
	v_max_f32_e32 v101, 0xc1f00000, v101
	v_mul_f32_e32 v101, 0xbfb8aa3b, v101
	v_add_f32_dpp v146, v106, v106 row_shr:8 row_mask:0xf bank_mask:0xf bound_ctrl:1
	v_mov_b32_dpp v106, v102 row_newbcast:15 row_mask:0xf bank_mask:0xf bound_ctrl:1
	v_mul_f32_e32 v134, 0x3f317218, v134
	v_mul_f32_e32 v147, v149, v98
	v_log_f32_e32 v148, v148
	v_mul_f32_e32 v150, v133, v110
	v_add_f32_dpp v98, v134, v134 row_shr:1 row_mask:0xf bank_mask:0xf bound_ctrl:1
	s_nop 1
	v_add_f32_dpp v98, v98, v98 row_shr:2 row_mask:0xf bank_mask:0xf bound_ctrl:1
	v_mov_b32_dpp v132, v146 row_newbcast:15 row_mask:0xf bank_mask:0xf bound_ctrl:1
	v_mul_f32_e32 v110, 0x3f317218, v148
	v_mov_b32_e32 v148, v110
	v_max_f32_e32 v110, 0xc1f00000, v127
	v_mul_f32_e32 v110, 0xbfb8aa3b, v110
	v_add_f32_dpp v98, v98, v98 row_shr:4 row_mask:0xf bank_mask:0xf bound_ctrl:1
	v_exp_f32_e32 v127, v110
	v_exp_f32_e32 v101, v101
	v_add_f32_dpp v151, v98, v98 row_shr:8 row_mask:0xf bank_mask:0xf bound_ctrl:1
	v_add_f32_dpp v98, v148, v148 row_shr:1 row_mask:0xf bank_mask:0xf bound_ctrl:1
	s_nop 0
	v_mov_b32_dpp v110, v151 row_newbcast:15 row_mask:0xf bank_mask:0xf bound_ctrl:1
	v_add_f32_dpp v98, v98, v98 row_shr:2 row_mask:0xf bank_mask:0xf bound_ctrl:1
	s_nop 1
	v_add_f32_dpp v98, v98, v98 row_shr:4 row_mask:0xf bank_mask:0xf bound_ctrl:1
	s_nop 1
	v_add_f32_dpp v149, v98, v98 row_shr:8 row_mask:0xf bank_mask:0xf bound_ctrl:1
	v_add_f32_e32 v98, 1.0, v127
	v_rcp_f32_e32 v98, v98
	v_mul_f32_e32 v127, v127, v199
	v_mov_b32_dpp v134, v149 row_newbcast:15 row_mask:0xf bank_mask:0xf bound_ctrl:1
	v_fma_f32 v133, v98, v199, v194
	s_nop 1
	v_log_f32_e32 v152, v133
	v_add_f32_e32 v133, 0, v131
	s_nop 1
	v_mul_f32_e32 v131, 0x3f317218, v152
	v_mul_f32_e32 v152, v98, v127
	v_log_f32_e32 v153, v153
	s_nop 1
	v_mul_f32_e32 v98, 0x3f317218, v153
	v_mov_b32_e32 v155, v98
	v_mul_f32_e32 v98, v123, v200
	v_exp_f32_e32 v127, v119
	v_mul_f32_e32 v153, v135, v98
	v_add_f32_dpp v98, v131, v131 row_shr:1 row_mask:0xf bank_mask:0xf bound_ctrl:1
	v_add_f32_dpp v119, v155, v155 row_shr:1 row_mask:0xf bank_mask:0xf bound_ctrl:1
	s_nop 0
	v_add_f32_dpp v98, v98, v98 row_shr:2 row_mask:0xf bank_mask:0xf bound_ctrl:1
	v_add_f32_dpp v119, v119, v119 row_shr:2 row_mask:0xf bank_mask:0xf bound_ctrl:1
	s_nop 0
	v_add_f32_dpp v98, v98, v98 row_shr:4 row_mask:0xf bank_mask:0xf bound_ctrl:1
	v_add_f32_dpp v119, v119, v119 row_shr:4 row_mask:0xf bank_mask:0xf bound_ctrl:1
	s_nop 0
	v_add_f32_dpp v156, v98, v98 row_shr:8 row_mask:0xf bank_mask:0xf bound_ctrl:1
	v_add_f32_e32 v98, 1.0, v127
	v_rcp_f32_e32 v98, v98
	v_mul_f32_e32 v127, v127, v199
	v_add_f32_dpp v157, v119, v119 row_shr:8 row_mask:0xf bank_mask:0xf bound_ctrl:1
	v_fma_f32 v123, v98, v199, v194
	s_nop 0
	v_mov_b32_dpp v119, v157 row_newbcast:15 row_mask:0xf bank_mask:0xf bound_ctrl:1
	s_nop 0
	v_log_f32_e32 v131, v123
	s_nop 0
	v_mov_b32_dpp v123, v156 row_newbcast:15 row_mask:0xf bank_mask:0xf bound_ctrl:1
	s_nop 1
	v_mul_f32_e32 v131, 0x3f317218, v131
	s_nop 0
	v_log_f32_e32 v203, v201
	v_mul_f32_e32 v201, v98, v127
	s_nop 1
	v_mul_f32_e32 v98, 0x3f317218, v203
	v_mov_b32_e32 v203, v98
	v_mul_f32_e32 v98, v115, v200
	v_mul_f32_e32 v202, v202, v98
	v_add_f32_dpp v115, v203, v203 row_shr:1 row_mask:0xf bank_mask:0xf bound_ctrl:1
	v_add_f32_dpp v98, v131, v131 row_shr:1 row_mask:0xf bank_mask:0xf bound_ctrl:1
	s_nop 0
	v_add_f32_dpp v115, v115, v115 row_shr:2 row_mask:0xf bank_mask:0xf bound_ctrl:1
	v_add_f32_dpp v98, v98, v98 row_shr:2 row_mask:0xf bank_mask:0xf bound_ctrl:1
	s_nop 0
	v_add_f32_dpp v115, v115, v115 row_shr:4 row_mask:0xf bank_mask:0xf bound_ctrl:1
	v_add_f32_dpp v98, v98, v98 row_shr:4 row_mask:0xf bank_mask:0xf bound_ctrl:1
	s_nop 0
	v_add_f32_dpp v205, v115, v115 row_shr:8 row_mask:0xf bank_mask:0xf bound_ctrl:1
	v_add_f32_dpp v204, v98, v98 row_shr:8 row_mask:0xf bank_mask:0xf bound_ctrl:1
	v_add_f32_e32 v98, 1.0, v111
	v_rcp_f32_e32 v98, v98
	v_mul_f32_e32 v111, v111, v199
	v_fma_f32 v127, v98, v199, v194
	s_nop 1
	v_log_f32_e32 v135, v127
	v_mov_b32_dpp v131, v204 row_newbcast:15 row_mask:0xf bank_mask:0xf bound_ctrl:1
	v_mov_b32_dpp v127, v205 row_newbcast:15 row_mask:0xf bank_mask:0xf bound_ctrl:1
	s_nop 1
	v_mul_f32_e32 v115, 0x3f317218, v135
	s_nop 0
	v_log_f32_e32 v208, v206
	v_mul_f32_e32 v206, v98, v111
	s_nop 1
	v_mul_f32_e32 v98, 0x3f317218, v208
	v_mov_b32_e32 v208, v98
	v_mul_f32_e32 v98, v107, v200
	v_mul_f32_e32 v207, v207, v98
	v_add_f32_dpp v107, v208, v208 row_shr:1 row_mask:0xf bank_mask:0xf bound_ctrl:1
	v_add_f32_dpp v98, v115, v115 row_shr:1 row_mask:0xf bank_mask:0xf bound_ctrl:1
	s_nop 0
	v_add_f32_dpp v107, v107, v107 row_shr:2 row_mask:0xf bank_mask:0xf bound_ctrl:1
	v_add_f32_dpp v98, v98, v98 row_shr:2 row_mask:0xf bank_mask:0xf bound_ctrl:1
	s_nop 0
	v_add_f32_dpp v107, v107, v107 row_shr:4 row_mask:0xf bank_mask:0xf bound_ctrl:1
	v_add_f32_dpp v98, v98, v98 row_shr:4 row_mask:0xf bank_mask:0xf bound_ctrl:1
	s_nop 0
	v_add_f32_dpp v210, v107, v107 row_shr:8 row_mask:0xf bank_mask:0xf bound_ctrl:1
	v_add_f32_dpp v209, v98, v98 row_shr:8 row_mask:0xf bank_mask:0xf bound_ctrl:1
	v_add_f32_e32 v98, 1.0, v103
	v_rcp_f32_e32 v98, v98
	v_mul_f32_e32 v103, v103, v199
	v_mov_b32_dpp v135, v210 row_newbcast:15 row_mask:0xf bank_mask:0xf bound_ctrl:1
	v_mov_b32_dpp v107, v209 row_newbcast:15 row_mask:0xf bank_mask:0xf bound_ctrl:1
; __device__ __forceinline__ float scan16(float x) { x += dpp_shr<1>(x); x += dpp_shr<2>(x); x += dpp_shr<4>(x); x += dpp_shr<8>(x); return x; }
; __device__ __forceinline__ float clamp80(float x) { return fminf(fmaxf(x, -80.f), 80.f); }
;     __device__ __forceinline__ void operator()(const f32x4 (&acc)[2][2][4][2], const pg8::Unit& u, int wr, int wc, int fr, int fq) const {
;     ...
;                             { const float z = acc[ai][0][m][1][j]; const float e = __expf(fminf(-z, 30.f)); const float s = __builtin_amdgcn_rcpf(1.f + e); lfF[m] = __logf(lbF[j] + (1.f - lbF[j]) * s); kkF[m] = (1.f - lbF[j]) * e * s; }
;                             { const float z = acc[ai][1][m][0][j]; const float e = __expf(fminf(-z, 30.f)); const float s = __builtin_amdgcn_rcpf(1.f + e); lfB[m] = __logf(lbB[j] + (1.f - lbB[j]) * s); kkB[m] = (1.f - lbB[j]) * e * s; }
;                             pF[m] = scan16(lfF[m]); pB[m] = scan16(lfB[m]);
;                             tF[m] = __int_as_float(__builtin_amdgcn_update_dpp(0, __float_as_int(pF[m]), 0x15F, 0xf, 0xf, true));
;                             tB[m] = __int_as_float(__builtin_amdgcn_update_dpp(0, __float_as_int(pB[m]), 0x15F, 0xf, 0xf, true));
;                         }
;                         const float rF = tF[0] + tF[1], blF = rF + tF[2] + tF[3];
;                         const float rB = tB[2] + tB[3], blB = rB + tB[0] + tB[1];
;                         float cF = 0.f, cB = 0.f;
; #pragma unroll
;                         for (int m = 0; m < 4; ++m) {
;                             const float bF = pF[m] + cF; cF += tF[m];
;                             const float bB = blB - (pB[m] + cB) + lfB[m]; cB += tB[m];
;                             const float xF = clamp80(bF - rF), xB = clamp80(bB - rB);
;                             const float q = acc[ai][0][m][0][j];
;                             vQF[m][jj] = q * __expf(xF); vKF[m][jj] = kkF[m] * __expf(-xF);
;                             vQB[m][jj] = q * __expf(xB); vKB[m][jj] = kkB[m] * __expf(-xB);
;                         }
	v_fma_f32 v111, v98, v199, v194
	s_nop 1
	v_log_f32_e32 v111, v111
	s_nop 0
	s_nop 1
	v_mul_f32_e32 v111, 0x3f317218, v111
	s_nop 0
	v_log_f32_e32 v212, v212
	v_mul_f32_e32 v213, v98, v103
	s_nop 1
	v_mul_f32_e32 v98, 0x3f317218, v212
	v_mov_b32_e32 v212, v98
	v_mul_f32_e32 v98, v99, v200
	v_mul_f32_e32 v211, v211, v98
	s_nop 0
	v_add_f32_dpp v98, v111, v111 row_shr:1 row_mask:0xf bank_mask:0xf bound_ctrl:1
	s_nop 1
	v_add_f32_dpp v98, v98, v98 row_shr:2 row_mask:0xf bank_mask:0xf bound_ctrl:1
	s_nop 1
	v_add_f32_dpp v98, v98, v98 row_shr:4 row_mask:0xf bank_mask:0xf bound_ctrl:1
	s_nop 1
	v_add_f32_dpp v214, v98, v98 row_shr:8 row_mask:0xf bank_mask:0xf bound_ctrl:1
	v_add_f32_dpp v98, v212, v212 row_shr:1 row_mask:0xf bank_mask:0xf bound_ctrl:1
	s_nop 1
	v_add_f32_dpp v98, v98, v98 row_shr:2 row_mask:0xf bank_mask:0xf bound_ctrl:1
	s_nop 1
	v_add_f32_dpp v98, v98, v98 row_shr:4 row_mask:0xf bank_mask:0xf bound_ctrl:1
	s_nop 1
	v_add_f32_dpp v215, v98, v98 row_shr:8 row_mask:0xf bank_mask:0xf bound_ctrl:1
	v_pk_add_f32 v[98:99], v[122:123], v[130:131]
	v_add_f32_e32 v122, 0, v122
	v_sub_f32_e32 v103, v133, v98
	v_med3_f32 v103, v103, s96, v190
	v_mul_f32_e32 v111, 0x3fb8aa3b, v103
	v_exp_f32_e32 v115, v111
	v_mul_f32_e32 v103, 0xbfb8aa3b, v103
	v_exp_f32_e32 v103, v103
	v_mov_b32_dpp v133, v215 row_newbcast:15 row_mask:0xf bank_mask:0xf bound_ctrl:1
	v_mul_f32_e32 v216, v94, v115
	v_add_f32_e32 v115, v122, v143
	v_sub_f32_e32 v115, v115, v98
	v_med3_f32 v115, v115, s96, v190
	v_mul_f32_e32 v143, 0x3fb8aa3b, v115
	v_mul_f32_e32 v115, 0xbfb8aa3b, v115
	v_mul_f32_e32 v138, v138, v103
	v_add_f32_e32 v103, v122, v130
	v_exp_f32_e32 v115, v115
	v_add_f32_e32 v102, v103, v102
	v_add_f32_e32 v103, v103, v106
	v_add_f32_e32 v103, v103, v151
	v_sub_f32_e32 v102, v102, v98
	v_sub_f32_e32 v103, v103, v98
	v_med3_f32 v102, v102, s96, v190
	v_med3_f32 v103, v103, s96, v190
	v_mul_f32_e32 v130, v114, v115
	v_mul_f32_e32 v114, 0x3fb8aa3b, v102
	v_mul_f32_e32 v102, 0xbfb8aa3b, v102
	v_mul_f32_e32 v115, 0x3fb8aa3b, v103
	v_mul_f32_e32 v103, 0xbfb8aa3b, v103
	v_exp_f32_e32 v143, v143
	v_exp_f32_e32 v114, v114
	v_exp_f32_e32 v102, v102
	v_exp_f32_e32 v103, v103
	v_exp_f32_e32 v115, v115
	v_mul_f32_e32 v122, v90, v143
	v_mul_f32_e32 v143, v86, v114
	v_mul_f32_e32 v145, v145, v102
	v_mul_f32_e32 v217, v150, v103
	v_pk_add_f32 v[102:103], v[134:135], v[132:133]
	v_add_f32_e32 v114, 0, v118
	v_mul_f32_e32 v151, v82, v115
	v_add_f32_e32 v133, v114, v141
	v_add_f32_e32 v134, v114, v126
	v_pk_add_f32 v[114:115], v[102:103], v[118:119]
	v_add_f32_e32 v141, v134, v146
	v_pk_add_f32 v[114:115], v[114:115], v[126:127]
	v_add_f32_e32 v132, v134, v132
	v_sub_f32_e32 v118, v114, v154
	v_sub_f32_e32 v133, v114, v133
	v_add_f32_e32 v118, v137, v118
	v_add_f32_e32 v133, v140, v133
	v_sub_f32_e32 v118, v118, v102
	v_sub_f32_e32 v133, v133, v102
	v_med3_f32 v118, v118, s96, v190
	v_med3_f32 v133, v133, s96, v190
	v_mul_f32_e32 v126, 0x3fb8aa3b, v118
	v_mul_f32_e32 v137, 0x3fb8aa3b, v133
	v_mul_f32_e32 v133, 0xbfb8aa3b, v133
	v_exp_f32_e32 v126, v126
	v_exp_f32_e32 v133, v133
	v_mul_f32_e32 v118, 0xbfb8aa3b, v118
	v_add_f32_e32 v132, v132, v149
	v_mul_f32_e32 v94, v94, v126
	v_mul_f32_e32 v126, v139, v133
	v_sub_f32_e32 v133, v114, v141
	v_add_f32_e32 v133, v144, v133
	v_exp_f32_e32 v118, v118
	v_sub_f32_e32 v133, v133, v102
	v_sub_f32_e32 v132, v114, v132
	v_med3_f32 v133, v133, s96, v190
	v_add_f32_e32 v132, v148, v132
	v_mul_f32_e32 v134, 0x3fb8aa3b, v133
	v_sub_f32_e32 v132, v132, v102
	v_exp_f32_e32 v134, v134
	v_med3_f32 v132, v132, s96, v190
	v_mul_f32_e32 v118, v136, v118
	v_mul_f32_e32 v136, 0x3fb8aa3b, v132
	v_mul_f32_e32 v132, 0xbfb8aa3b, v132
	v_exp_f32_e32 v137, v137
	v_exp_f32_e32 v132, v132
	v_mul_f32_e32 v86, v86, v134
	v_add_f32_e32 v134, 0, v157
	v_exp_f32_e32 v136, v136
	v_sub_f32_e32 v134, v115, v134
	v_mul_f32_e32 v90, v90, v137
	v_mul_f32_e32 v137, v147, v132
	v_add_f32_e32 v132, 0, v156
	v_add_f32_e32 v134, v155, v134
	v_sub_f32_e32 v132, v132, v99
	v_sub_f32_e32 v134, v134, v103
	v_med3_f32 v132, v132, s96, v190
	v_med3_f32 v134, v134, s96, v190
	v_mul_f32_e32 v82, v82, v136
	v_mul_f32_e32 v136, 0x3fb8aa3b, v132
	v_mul_f32_e32 v139, 0x3fb8aa3b, v134
	v_exp_f32_e32 v136, v136
	v_exp_f32_e32 v139, v139
	v_add_f32_e32 v123, 0, v123
	v_add_f32_e32 v119, 0, v119
	v_mul_f32_e32 v136, v95, v136
	v_mul_f32_e32 v95, v95, v139
	v_add_f32_e32 v139, v123, v204
	v_add_f32_e32 v123, v123, v131
	v_add_f32_e32 v131, v119, v205
	v_sub_f32_e32 v131, v115, v131
	v_add_f32_e32 v131, v203, v131
	v_add_f32_e32 v119, v119, v127
	v_sub_f32_e32 v127, v139, v99
	v_sub_f32_e32 v131, v131, v103
	v_med3_f32 v127, v127, s96, v190
	v_med3_f32 v131, v131, s96, v190
	v_mul_f32_e32 v139, 0x3fb8aa3b, v127
	v_mul_f32_e32 v140, 0x3fb8aa3b, v131
	v_exp_f32_e32 v139, v139
	v_exp_f32_e32 v140, v140
	v_mul_f32_e32 v133, 0xbfb8aa3b, v133
	v_add_f32_e32 v141, v119, v210
	v_exp_f32_e32 v133, v133
	v_sub_f32_e32 v141, v115, v141
	v_mul_f32_e32 v139, v91, v139
	v_mul_f32_e32 v91, v91, v140
	v_add_f32_e32 v140, v123, v209
	v_add_f32_e32 v141, v208, v141
	v_add_f32_e32 v119, v119, v135
	v_sub_f32_e32 v135, v140, v99
	v_sub_f32_e32 v140, v141, v103
	v_med3_f32 v135, v135, s96, v190
	v_med3_f32 v140, v140, s96, v190
	v_mul_f32_e32 v133, v142, v133
	v_mul_f32_e32 v141, 0x3fb8aa3b, v135
	v_mul_f32_e32 v142, 0x3fb8aa3b, v140
	v_add_f32_e32 v123, v123, v107
	v_exp_f32_e32 v141, v141
	v_exp_f32_e32 v142, v142
	v_add_f32_e32 v123, v123, v214
	v_sub_f32_e32 v123, v123, v99
	v_med3_f32 v123, v123, s96, v190
	v_mul_f32_e32 v132, 0xbfb8aa3b, v132
	v_mul_f32_e32 v134, 0xbfb8aa3b, v134
	v_mul_f32_e32 v141, v87, v141
; __device__ __forceinline__ unsigned cvt_pk_bf16(float lo, float hi) { unsigned r; asm volatile("v_cvt_pk_bf16_f32 %0, %1, %2" : "=v"(r) : "v"(lo), "v"(hi)); return r; }
;     __device__ __forceinline__ void operator()(const f32x4 (&acc)[2][2][4][2], const pg8::Unit& u, int wr, int wc, int fr, int fq) const {
;     ...
;                             { const float z = acc[ai][0][m][1][j]; const float e = __expf(fminf(-z, 30.f)); const float s = __builtin_amdgcn_rcpf(1.f + e); lfF[m] = __logf(lbF[j] + (1.f - lbF[j]) * s); kkF[m] = (1.f - lbF[j]) * e * s; }
;                             { const float z = acc[ai][1][m][0][j]; const float e = __expf(fminf(-z, 30.f)); const float s = __builtin_amdgcn_rcpf(1.f + e); lfB[m] = __logf(lbB[j] + (1.f - lbB[j]) * s); kkB[m] = (1.f - lbB[j]) * e * s; }
;                             pF[m] = scan16(lfF[m]); pB[m] = scan16(lfB[m]);
;                             tF[m] = __int_as_float(__builtin_amdgcn_update_dpp(0, __float_as_int(pF[m]), 0x15F, 0xf, 0xf, true));
;                             tB[m] = __int_as_float(__builtin_amdgcn_update_dpp(0, __float_as_int(pB[m]), 0x15F, 0xf, 0xf, true));
;                         }
;                         const float rF = tF[0] + tF[1], blF = rF + tF[2] + tF[3];
;                         const float rB = tB[2] + tB[3], blB = rB + tB[0] + tB[1];
;                         float cF = 0.f, cB = 0.f;
; #pragma unroll
;                         for (int m = 0; m < 4; ++m) {
;                             const float bF = pF[m] + cF; cF += tF[m];
;                             const float bB = blB - (pB[m] + cB) + lfB[m]; cB += tB[m];
;                             const float xF = clamp80(bF - rF), xB = clamp80(bB - rB);
;                             const float q = acc[ai][0][m][0][j];
;                             vQF[m][jj] = q * __expf(xF); vKF[m][jj] = kkF[m] * __expf(-xF);
;                             vQB[m][jj] = q * __expf(xB); vKB[m][jj] = kkB[m] * __expf(-xB);
;                         }
;                         rtv[0][j] = rF; rtv[1][j] = rB; rtv[2][j] = blF - rF; rtv[3][j] = blB - rB;
;                     }
; #pragma unroll
;                     for (int m = 0; m < 4; ++m) { oQF[m][jp] = cvt_pk_bf16(vQF[m][0], vQF[m][1]); oQB[m][jp] = cvt_pk_bf16(vQB[m][0], vQB[m][1]); oKF[m][jp] = cvt_pk_bf16(vKF[m][0], vKF[m][1]); oKB[m][jp] = cvt_pk_bf16(vKB[m][0], vKB[m][1]); }
	v_mul_f32_e32 v87, v87, v142
	v_mul_f32_e32 v142, 0x3fb8aa3b, v123
	v_exp_f32_e32 v132, v132
	v_exp_f32_e32 v134, v134
	v_exp_f32_e32 v142, v142
	v_add_f32_e32 v119, v119, v215
	v_sub_f32_e32 v119, v115, v119
	v_add_f32_e32 v119, v212, v119
	v_mul_f32_e32 v132, v152, v132
	v_mul_f32_e32 v134, v153, v134
	v_sub_f32_e32 v119, v119, v103
	v_mul_f32_e32 v147, v83, v142
	v_cvt_pk_bf16_f32 v154, v216, v136
	v_cvt_pk_bf16_f32 v150, v94, v95
	v_cvt_pk_bf16_f32 v146, v138, v132
	v_cvt_pk_bf16_f32 v142, v118, v134
	v_cvt_pk_bf16_f32 v156, v122, v139
	v_cvt_pk_bf16_f32 v152, v90, v91
	v_med3_f32 v119, v119, s96, v190
	v_max_f32_e32 v90, 0xc1f00000, v128
	v_mul_f32_e32 v127, 0xbfb8aa3b, v127
	v_mul_f32_e32 v131, 0xbfb8aa3b, v131
	v_mul_f32_e32 v144, 0x3fb8aa3b, v119
	v_mul_f32_e32 v90, 0xbfb8aa3b, v90
	v_exp_f32_e32 v127, v127
	v_exp_f32_e32 v131, v131
	v_exp_f32_e32 v144, v144
	v_exp_f32_e32 v90, v90
	v_mul_f32_e32 v140, 0xbfb8aa3b, v140
	v_mul_f32_e32 v127, v201, v127
	v_mul_f32_e32 v131, v202, v131
	v_mul_f32_e32 v135, 0xbfb8aa3b, v135
	v_exp_f32_e32 v140, v140
	v_mul_f32_e32 v83, v83, v144
	v_cvt_pk_bf16_f32 v148, v130, v127
	v_cvt_pk_bf16_f32 v144, v126, v131
	v_cvt_pk_bf16_f32 v130, v143, v141
	v_cvt_pk_bf16_f32 v138, v86, v87
	v_add_f32_e32 v86, 1.0, v90
	v_exp_f32_e32 v135, v135
	v_rcp_f32_e32 v86, v86
	v_mul_f32_e32 v140, v207, v140
	v_sub_f32_e32 v122, 1.0, v177
	v_mul_f32_e32 v135, v206, v135
	v_cvt_pk_bf16_f32 v134, v145, v135
	v_cvt_pk_bf16_f32 v126, v133, v140
	v_cvt_pk_bf16_f32 v132, v151, v147
	v_cvt_pk_bf16_f32 v140, v82, v83
	v_fma_f32 v82, v86, v122, v177
	v_max_f32_e32 v87, 0xc1f00000, v124
	v_mul_f32_e32 v87, 0xbfb8aa3b, v87
	v_exp_f32_e32 v87, v87
	v_mul_f32_e32 v123, 0xbfb8aa3b, v123
	v_log_f32_e32 v82, v82
	v_exp_f32_e32 v123, v123
	v_add_f32_e32 v91, 1.0, v87
	v_rcp_f32_e32 v91, v91
	v_mul_f32_e32 v123, v213, v123
	v_cvt_pk_bf16_f32 v136, v217, v123
	v_sub_f32_e32 v123, 1.0, v192
	v_fma_f32 v94, v91, v123, v192
	v_mul_f32_e32 v119, 0xbfb8aa3b, v119
	v_mul_f32_e32 v82, 0x3f317218, v82
	v_mul_f32_e32 v83, v90, v122
	v_log_f32_e32 v94, v94
	v_mul_f32_e32 v133, v86, v83
	v_add_f32_dpp v82, v82, v82 row_shr:1 row_mask:0xf bank_mask:0xf bound_ctrl:1
	s_nop 1
	v_add_f32_dpp v82, v82, v82 row_shr:2 row_mask:0xf bank_mask:0xf bound_ctrl:1
	v_exp_f32_e32 v119, v119
	v_mul_f32_e32 v83, 0x3f317218, v94
	v_mov_b32_e32 v131, v83
	v_mul_f32_e32 v83, v87, v123
	v_mul_f32_e32 v127, v91, v83
	v_max_f32_e32 v83, 0xc1f00000, v120
	v_mul_f32_e32 v83, 0xbfb8aa3b, v83
	v_exp_f32_e32 v90, v83
	v_add_f32_dpp v82, v82, v82 row_shr:4 row_mask:0xf bank_mask:0xf bound_ctrl:1
	v_add_f32_e32 v118, 1.0, v116
	v_rcp_f32_e32 v118, v118
	v_add_f32_dpp v83, v82, v82 row_shr:8 row_mask:0xf bank_mask:0xf bound_ctrl:1
	v_add_f32_e32 v82, 1.0, v90
	v_rcp_f32_e32 v91, v82
	v_mul_f32_e32 v119, v211, v119
	v_cvt_pk_bf16_f32 v128, v137, v119
	v_fma_f32 v119, v118, v123, v192
	v_fma_f32 v86, v91, v122, v177
	v_mul_f32_e32 v90, v90, v122
	v_add_f32_dpp v82, v131, v131 row_shr:1 row_mask:0xf bank_mask:0xf bound_ctrl:1
	v_log_f32_e32 v94, v86
	s_nop 0
	v_add_f32_dpp v82, v82, v82 row_shr:2 row_mask:0xf bank_mask:0xf bound_ctrl:1
	v_mov_b32_dpp v86, v83 row_newbcast:15 row_mask:0xf bank_mask:0xf bound_ctrl:1
	v_add_f32_e32 v207, 0, v83
	v_add_f32_dpp v82, v82, v82 row_shr:4 row_mask:0xf bank_mask:0xf bound_ctrl:1
	v_sub_f32_e32 v201, 1.0, v191
	v_mul_f32_e32 v94, 0x3f317218, v94
	v_add_f32_dpp v87, v82, v82 row_shr:8 row_mask:0xf bank_mask:0xf bound_ctrl:1
	v_log_f32_e32 v119, v119
	v_mul_f32_e32 v120, v91, v90
	v_mov_b32_dpp v82, v87 row_newbcast:15 row_mask:0xf bank_mask:0xf bound_ctrl:1
	v_add_f32_e32 v203, 0, v87
	v_mul_f32_e32 v90, 0x3f317218, v119
	v_mov_b32_e32 v137, v90
	v_max_f32_e32 v91, 0xc1f00000, v112
	v_mul_f32_e32 v91, 0xbfb8aa3b, v91
	v_mul_f32_e32 v90, v116, v123
	v_exp_f32_e32 v91, v91
	v_mul_f32_e32 v135, v118, v90
	v_add_f32_dpp v90, v94, v94 row_shr:1 row_mask:0xf bank_mask:0xf bound_ctrl:1
	v_add_f32_e32 v118, 1.0, v108
	v_rcp_f32_e32 v118, v118
	v_add_f32_dpp v90, v90, v90 row_shr:2 row_mask:0xf bank_mask:0xf bound_ctrl:1
	v_max_f32_e32 v87, 0xc1f00000, v125
	v_mul_f32_e32 v87, 0xbfb8aa3b, v87
	v_add_f32_dpp v90, v90, v90 row_shr:4 row_mask:0xf bank_mask:0xf bound_ctrl:1
	v_fma_f32 v119, v118, v123, v192
	v_exp_f32_e32 v87, v87
	v_add_f32_dpp v143, v90, v90 row_shr:8 row_mask:0xf bank_mask:0xf bound_ctrl:1
	v_add_f32_e32 v90, 1.0, v91
	v_rcp_f32_e32 v95, v90
	v_mul_f32_e32 v91, v91, v122
	v_mov_b32_dpp v111, v214 row_newbcast:15 row_mask:0xf bank_mask:0xf bound_ctrl:1
	v_add_f32_dpp v90, v137, v137 row_shr:1 row_mask:0xf bank_mask:0xf bound_ctrl:1
	v_fma_f32 v94, v95, v122, v177
	v_mul_f32_e32 v147, v95, v91
	v_add_f32_dpp v90, v90, v90 row_shr:2 row_mask:0xf bank_mask:0xf bound_ctrl:1
	v_log_f32_e32 v112, v94
	s_nop 0
	v_add_f32_dpp v90, v90, v90 row_shr:4 row_mask:0xf bank_mask:0xf bound_ctrl:1
	v_mov_b32_dpp v94, v143 row_newbcast:15 row_mask:0xf bank_mask:0xf bound_ctrl:1
	s_nop 0
	v_add_f32_dpp v139, v90, v90 row_shr:8 row_mask:0xf bank_mask:0xf bound_ctrl:1
	s_nop 0
	v_mul_f32_e32 v112, 0x3f317218, v112
	v_mov_b32_dpp v90, v139 row_newbcast:15 row_mask:0xf bank_mask:0xf bound_ctrl:1
	v_log_f32_e32 v119, v119
	s_nop 1
	v_mul_f32_e32 v91, 0x3f317218, v119
	v_mov_b32_e32 v145, v91
	v_max_f32_e32 v95, 0xc1f00000, v104
	v_mul_f32_e32 v95, 0xbfb8aa3b, v95
	v_mul_f32_e32 v91, v108, v123
	v_exp_f32_e32 v95, v95
	v_mul_f32_e32 v141, v118, v91
	v_add_f32_dpp v91, v112, v112 row_shr:1 row_mask:0xf bank_mask:0xf bound_ctrl:1
	v_add_f32_e32 v119, 1.0, v100
	v_rcp_f32_e32 v119, v119
	v_add_f32_dpp v91, v91, v91 row_shr:2 row_mask:0xf bank_mask:0xf bound_ctrl:1
; __device__ __forceinline__ float scan16(float x) { x += dpp_shr<1>(x); x += dpp_shr<2>(x); x += dpp_shr<4>(x); x += dpp_shr<8>(x); return x; }
;     __device__ __forceinline__ void operator()(const f32x4 (&acc)[2][2][4][2], const pg8::Unit& u, int wr, int wc, int fr, int fq) const {
;     ...
;                             { const float z = acc[ai][0][m][1][j]; const float e = __expf(fminf(-z, 30.f)); const float s = __builtin_amdgcn_rcpf(1.f + e); lfF[m] = __logf(lbF[j] + (1.f - lbF[j]) * s); kkF[m] = (1.f - lbF[j]) * e * s; }
;                             { const float z = acc[ai][1][m][0][j]; const float e = __expf(fminf(-z, 30.f)); const float s = __builtin_amdgcn_rcpf(1.f + e); lfB[m] = __logf(lbB[j] + (1.f - lbB[j]) * s); kkB[m] = (1.f - lbB[j]) * e * s; }
;                             pF[m] = scan16(lfF[m]); pB[m] = scan16(lfB[m]);
;                             tF[m] = __int_as_float(__builtin_amdgcn_update_dpp(0, __float_as_int(pF[m]), 0x15F, 0xf, 0xf, true));
;                             tB[m] = __int_as_float(__builtin_amdgcn_update_dpp(0, __float_as_int(pB[m]), 0x15F, 0xf, 0xf, true));
	v_add_f32_dpp v108, v145, v145 row_shr:1 row_mask:0xf bank_mask:0xf bound_ctrl:1
	v_fma_f32 v124, v119, v123, v192
	v_add_f32_dpp v91, v91, v91 row_shr:4 row_mask:0xf bank_mask:0xf bound_ctrl:1
	v_add_f32_dpp v108, v108, v108 row_shr:2 row_mask:0xf bank_mask:0xf bound_ctrl:1
	s_nop 0
	v_add_f32_dpp v104, v91, v91 row_shr:8 row_mask:0xf bank_mask:0xf bound_ctrl:1
	v_add_f32_e32 v91, 1.0, v95
	v_rcp_f32_e32 v91, v91
	v_mul_f32_e32 v95, v95, v122
	v_add_f32_dpp v108, v108, v108 row_shr:4 row_mask:0xf bank_mask:0xf bound_ctrl:1
	v_fma_f32 v112, v91, v122, v177
	v_mul_f32_e32 v155, v91, v95
	v_add_f32_dpp v149, v108, v108 row_shr:8 row_mask:0xf bank_mask:0xf bound_ctrl:1
	v_log_f32_e32 v112, v112
	v_mov_b32_dpp v108, v104 row_newbcast:15 row_mask:0xf bank_mask:0xf bound_ctrl:1
	v_mov_b32_dpp v116, v149 row_newbcast:15 row_mask:0xf bank_mask:0xf bound_ctrl:1
	s_nop 1
	v_mul_f32_e32 v112, 0x3f317218, v112
	s_nop 0
	v_log_f32_e32 v124, v124
	s_nop 1
	v_mul_f32_e32 v91, 0x3f317218, v124
	v_mov_b32_e32 v153, v91
	v_mul_f32_e32 v91, v100, v123
	v_mul_f32_e32 v151, v119, v91
	s_nop 0
	v_add_f32_dpp v91, v112, v112 row_shr:1 row_mask:0xf bank_mask:0xf bound_ctrl:1
	v_max_f32_e32 v95, 0xc1f00000, v129
	v_mul_f32_e32 v95, 0xbfb8aa3b, v95
	v_add_f32_dpp v91, v91, v91 row_shr:2 row_mask:0xf bank_mask:0xf bound_ctrl:1
	v_exp_f32_e32 v95, v95
	v_sub_f32_e32 v124, 1.0, v173
	v_add_f32_dpp v91, v91, v91 row_shr:4 row_mask:0xf bank_mask:0xf bound_ctrl:1
	s_nop 1
	v_add_f32_dpp v157, v91, v91 row_shr:8 row_mask:0xf bank_mask:0xf bound_ctrl:1
	v_add_f32_dpp v91, v153, v153 row_shr:1 row_mask:0xf bank_mask:0xf bound_ctrl:1
	s_nop 0
	v_mov_b32_dpp v112, v157 row_newbcast:15 row_mask:0xf bank_mask:0xf bound_ctrl:1
	v_add_f32_dpp v91, v91, v91 row_shr:2 row_mask:0xf bank_mask:0xf bound_ctrl:1
	s_nop 1
	v_add_f32_dpp v91, v91, v91 row_shr:4 row_mask:0xf bank_mask:0xf bound_ctrl:1
	s_nop 1
	v_add_f32_dpp v129, v91, v91 row_shr:8 row_mask:0xf bank_mask:0xf bound_ctrl:1
	v_add_f32_e32 v91, 1.0, v95
	v_rcp_f32_e32 v91, v91
	v_mul_f32_e32 v95, v95, v124
	v_mov_b32_dpp v118, v129 row_newbcast:15 row_mask:0xf bank_mask:0xf bound_ctrl:1
	v_fma_f32 v100, v91, v124, v173
	s_nop 1
	v_log_f32_e32 v100, v100
	v_add_f32_e32 v119, 1.0, v87
	v_rcp_f32_e32 v119, v119
	v_mul_f32_e32 v87, v87, v201
	v_fma_f32 v125, v119, v201, v191
	s_nop 0
	v_mul_f32_e32 v83, 0x3f317218, v100
	s_nop 0
	v_log_f32_e32 v202, v125
	v_mul_f32_e32 v125, v91, v95
	v_add_f32_dpp v83, v83, v83 row_shr:1 row_mask:0xf bank_mask:0xf bound_ctrl:1
	s_nop 1
	v_add_f32_dpp v83, v83, v83 row_shr:2 row_mask:0xf bank_mask:0xf bound_ctrl:1
	s_nop 0
	v_mul_f32_e32 v91, 0x3f317218, v202
	v_mul_f32_e32 v202, v119, v87
	v_max_f32_e32 v87, 0xc1f00000, v121
	v_mul_f32_e32 v87, 0xbfb8aa3b, v87
	v_mov_b32_e32 v204, v91
	v_exp_f32_e32 v91, v87
	v_add_f32_dpp v83, v83, v83 row_shr:4 row_mask:0xf bank_mask:0xf bound_ctrl:1
	v_add_f32_e32 v121, 1.0, v117
	v_rcp_f32_e32 v121, v121
	v_add_f32_dpp v205, v83, v83 row_shr:8 row_mask:0xf bank_mask:0xf bound_ctrl:1
	v_add_f32_e32 v83, 1.0, v91
	v_rcp_f32_e32 v95, v83
	v_fma_f32 v208, v121, v201, v191
	v_mul_f32_e32 v91, v91, v124
	v_add_f32_dpp v83, v204, v204 row_shr:1 row_mask:0xf bank_mask:0xf bound_ctrl:1
	v_fma_f32 v87, v95, v124, v173
	s_nop 0
	v_add_f32_dpp v83, v83, v83 row_shr:2 row_mask:0xf bank_mask:0xf bound_ctrl:1
	s_nop 0
	v_log_f32_e32 v100, v87
	v_add_f32_dpp v83, v83, v83 row_shr:4 row_mask:0xf bank_mask:0xf bound_ctrl:1
	v_mov_b32_dpp v87, v205 row_newbcast:15 row_mask:0xf bank_mask:0xf bound_ctrl:1
	s_nop 0
	v_add_f32_dpp v206, v83, v83 row_shr:8 row_mask:0xf bank_mask:0xf bound_ctrl:1
	s_nop 0
	v_mul_f32_e32 v100, 0x3f317218, v100
	v_mov_b32_dpp v83, v206 row_newbcast:15 row_mask:0xf bank_mask:0xf bound_ctrl:1
	v_log_f32_e32 v209, v208
	v_mul_f32_e32 v208, v95, v91
	s_nop 1
	v_mul_f32_e32 v91, 0x3f317218, v209
	v_mov_b32_e32 v210, v91
	v_max_f32_e32 v95, 0xc1f00000, v113
	v_mul_f32_e32 v91, v117, v201
	v_mul_f32_e32 v95, 0xbfb8aa3b, v95
	v_mul_f32_e32 v209, v121, v91
	v_add_f32_dpp v91, v100, v100 row_shr:1 row_mask:0xf bank_mask:0xf bound_ctrl:1
	v_exp_f32_e32 v100, v95
	v_add_f32_e32 v121, 1.0, v109
	v_add_f32_dpp v91, v91, v91 row_shr:2 row_mask:0xf bank_mask:0xf bound_ctrl:1
	v_rcp_f32_e32 v121, v121
	s_nop 0
	v_add_f32_dpp v91, v91, v91 row_shr:4 row_mask:0xf bank_mask:0xf bound_ctrl:1
	v_fma_f32 v213, v121, v201, v191
	s_nop 0
	v_add_f32_dpp v211, v91, v91 row_shr:8 row_mask:0xf bank_mask:0xf bound_ctrl:1
	v_add_f32_e32 v91, 1.0, v100
	v_rcp_f32_e32 v113, v91
	v_mul_f32_e32 v100, v100, v124
	v_add_f32_dpp v91, v210, v210 row_shr:1 row_mask:0xf bank_mask:0xf bound_ctrl:1
	v_fma_f32 v95, v113, v124, v173
	s_nop 0
	v_add_f32_dpp v91, v91, v91 row_shr:2 row_mask:0xf bank_mask:0xf bound_ctrl:1
	s_nop 0
	v_log_f32_e32 v117, v95
	v_add_f32_dpp v91, v91, v91 row_shr:4 row_mask:0xf bank_mask:0xf bound_ctrl:1
	v_mov_b32_dpp v95, v211 row_newbcast:15 row_mask:0xf bank_mask:0xf bound_ctrl:1
	s_nop 0
	v_add_f32_dpp v212, v91, v91 row_shr:8 row_mask:0xf bank_mask:0xf bound_ctrl:1
	s_nop 0
	v_mul_f32_e32 v117, 0x3f317218, v117
	v_mov_b32_dpp v91, v212 row_newbcast:15 row_mask:0xf bank_mask:0xf bound_ctrl:1
	v_log_f32_e32 v214, v213
	v_mul_f32_e32 v213, v113, v100
	s_nop 1
	v_mul_f32_e32 v100, 0x3f317218, v214
	v_mov_b32_e32 v215, v100
	v_mul_f32_e32 v100, v109, v201
	v_mul_f32_e32 v214, v121, v100
	v_add_f32_e32 v121, 1.0, v101
	v_add_f32_dpp v100, v117, v117 row_shr:1 row_mask:0xf bank_mask:0xf bound_ctrl:1
	v_rcp_f32_e32 v121, v121
	v_add_f32_dpp v109, v215, v215 row_shr:1 row_mask:0xf bank_mask:0xf bound_ctrl:1
	v_add_f32_dpp v100, v100, v100 row_shr:2 row_mask:0xf bank_mask:0xf bound_ctrl:1
; __device__ __forceinline__ float scan16(float x) { x += dpp_shr<1>(x); x += dpp_shr<2>(x); x += dpp_shr<4>(x); x += dpp_shr<8>(x); return x; }
; __device__ __forceinline__ float clamp80(float x) { return fminf(fmaxf(x, -80.f), 80.f); }
;     __device__ __forceinline__ void operator()(const f32x4 (&acc)[2][2][4][2], const pg8::Unit& u, int wr, int wc, int fr, int fq) const {
;     ...
;                             { const float z = acc[ai][0][m][1][j]; const float e = __expf(fminf(-z, 30.f)); const float s = __builtin_amdgcn_rcpf(1.f + e); lfF[m] = __logf(lbF[j] + (1.f - lbF[j]) * s); kkF[m] = (1.f - lbF[j]) * e * s; }
;                             { const float z = acc[ai][1][m][0][j]; const float e = __expf(fminf(-z, 30.f)); const float s = __builtin_amdgcn_rcpf(1.f + e); lfB[m] = __logf(lbB[j] + (1.f - lbB[j]) * s); kkB[m] = (1.f - lbB[j]) * e * s; }
;                             pF[m] = scan16(lfF[m]); pB[m] = scan16(lfB[m]);
;                             tF[m] = __int_as_float(__builtin_amdgcn_update_dpp(0, __float_as_int(pF[m]), 0x15F, 0xf, 0xf, true));
;                             tB[m] = __int_as_float(__builtin_amdgcn_update_dpp(0, __float_as_int(pB[m]), 0x15F, 0xf, 0xf, true));
;                         }
;                         const float rF = tF[0] + tF[1], blF = rF + tF[2] + tF[3];
;                         const float rB = tB[2] + tB[3], blB = rB + tB[0] + tB[1];
;                         float cF = 0.f, cB = 0.f;
; #pragma unroll
;                         for (int m = 0; m < 4; ++m) {
;                             const float bF = pF[m] + cF; cF += tF[m];
;                             const float bB = blB - (pB[m] + cB) + lfB[m]; cB += tB[m];
;                             const float xF = clamp80(bF - rF), xB = clamp80(bB - rB);
;                             const float q = acc[ai][0][m][0][j];
;                             vQF[m][jj] = q * __expf(xF); vKF[m][jj] = kkF[m] * __expf(-xF);
;                             vQB[m][jj] = q * __expf(xB); vKB[m][jj] = kkB[m] * __expf(-xB);
;                         }
	v_fma_f32 v218, v121, v201, v191
	s_nop 0
	v_add_f32_dpp v100, v100, v100 row_shr:4 row_mask:0xf bank_mask:0xf bound_ctrl:1
	v_add_f32_dpp v109, v109, v109 row_shr:2 row_mask:0xf bank_mask:0xf bound_ctrl:1
	s_nop 0
	v_add_f32_dpp v216, v100, v100 row_shr:8 row_mask:0xf bank_mask:0xf bound_ctrl:1
	v_add_f32_e32 v100, 1.0, v105
	v_rcp_f32_e32 v100, v100
	v_mul_f32_e32 v105, v105, v124
	v_add_f32_dpp v109, v109, v109 row_shr:4 row_mask:0xf bank_mask:0xf bound_ctrl:1
	v_fma_f32 v113, v100, v124, v173
	s_nop 0
	v_add_f32_dpp v217, v109, v109 row_shr:8 row_mask:0xf bank_mask:0xf bound_ctrl:1
	v_mov_b32_dpp v109, v216 row_newbcast:15 row_mask:0xf bank_mask:0xf bound_ctrl:1
	v_log_f32_e32 v113, v113
	v_mov_b32_dpp v119, v217 row_newbcast:15 row_mask:0xf bank_mask:0xf bound_ctrl:1
	s_nop 1
	v_mul_f32_e32 v113, 0x3f317218, v113
	s_nop 0
	v_log_f32_e32 v218, v218
	v_mul_f32_e32 v219, v100, v105
	s_nop 1
	v_mul_f32_e32 v100, 0x3f317218, v218
	v_mov_b32_e32 v218, v100
	v_mul_f32_e32 v100, v101, v201
	v_mul_f32_e32 v220, v121, v100
	s_nop 0
	v_add_f32_dpp v100, v113, v113 row_shr:1 row_mask:0xf bank_mask:0xf bound_ctrl:1
	s_nop 1
	v_add_f32_dpp v100, v100, v100 row_shr:2 row_mask:0xf bank_mask:0xf bound_ctrl:1
	s_nop 1
	v_add_f32_dpp v100, v100, v100 row_shr:4 row_mask:0xf bank_mask:0xf bound_ctrl:1
	s_nop 1
	v_add_f32_dpp v221, v100, v100 row_shr:8 row_mask:0xf bank_mask:0xf bound_ctrl:1
	v_add_f32_dpp v100, v218, v218 row_shr:1 row_mask:0xf bank_mask:0xf bound_ctrl:1
	s_nop 1
	v_add_f32_dpp v100, v100, v100 row_shr:2 row_mask:0xf bank_mask:0xf bound_ctrl:1
	s_nop 1
	v_add_f32_dpp v100, v100, v100 row_shr:4 row_mask:0xf bank_mask:0xf bound_ctrl:1
	s_nop 1
	v_add_f32_dpp v222, v100, v100 row_shr:8 row_mask:0xf bank_mask:0xf bound_ctrl:1
	v_pk_add_f32 v[100:101], v[86:87], v[94:95]
	v_add_f32_e32 v86, 0, v86
	v_sub_f32_e32 v105, v207, v100
	v_med3_f32 v105, v105, s96, v190
	v_mul_f32_e32 v113, 0x3fb8aa3b, v105
	v_exp_f32_e32 v121, v113
	v_mul_f32_e32 v105, 0xbfb8aa3b, v105
	v_exp_f32_e32 v105, v105
	v_mov_b32_dpp v117, v222 row_newbcast:15 row_mask:0xf bank_mask:0xf bound_ctrl:1
	v_mul_f32_e32 v207, v96, v121
	v_add_f32_e32 v121, v86, v143
	v_sub_f32_e32 v121, v121, v100
	v_med3_f32 v121, v121, s96, v190
	v_mul_f32_e32 v143, 0x3fb8aa3b, v121
	v_mul_f32_e32 v121, 0xbfb8aa3b, v121
	v_add_f32_e32 v86, v86, v94
	v_exp_f32_e32 v121, v121
	v_add_f32_e32 v104, v86, v104
	v_add_f32_e32 v86, v86, v108
	v_sub_f32_e32 v104, v104, v100
	v_add_f32_e32 v86, v86, v157
	v_med3_f32 v104, v104, s96, v190
	v_sub_f32_e32 v86, v86, v100
	v_mul_f32_e32 v133, v133, v105
	v_mul_f32_e32 v105, 0x3fb8aa3b, v104
	v_mul_f32_e32 v104, 0xbfb8aa3b, v104
	v_med3_f32 v86, v86, s96, v190
	v_mul_f32_e32 v223, v120, v121
	v_exp_f32_e32 v105, v105
	v_exp_f32_e32 v104, v104
	v_mul_f32_e32 v120, 0x3fb8aa3b, v86
	v_exp_f32_e32 v120, v120
	v_mul_f32_e32 v224, v88, v105
	v_mul_f32_e32 v225, v147, v104
	v_pk_add_f32 v[104:105], v[118:119], v[116:117]
	v_mul_f32_e32 v226, v84, v120
	v_add_f32_e32 v117, 0, v82
	v_pk_add_f32 v[120:121], v[104:105], v[82:83]
	v_add_f32_e32 v118, v117, v139
	v_pk_add_f32 v[120:121], v[120:121], v[90:91]
	v_add_f32_e32 v117, v117, v90
	v_sub_f32_e32 v82, v120, v203
	v_sub_f32_e32 v118, v120, v118
	v_add_f32_e32 v82, v131, v82
	v_add_f32_e32 v118, v137, v118
	v_sub_f32_e32 v82, v82, v104
	v_sub_f32_e32 v118, v118, v104
	v_med3_f32 v82, v82, s96, v190
	v_med3_f32 v118, v118, s96, v190
	v_mul_f32_e32 v90, 0x3fb8aa3b, v82
	v_mul_f32_e32 v131, 0x3fb8aa3b, v118
	v_mul_f32_e32 v118, 0xbfb8aa3b, v118
	v_exp_f32_e32 v90, v90
	v_exp_f32_e32 v118, v118
	v_add_f32_e32 v116, v117, v116
	v_mul_f32_e32 v82, 0xbfb8aa3b, v82
	v_add_f32_e32 v116, v116, v129
	v_exp_f32_e32 v82, v82
	v_sub_f32_e32 v116, v120, v116
	v_add_f32_e32 v139, v117, v149
	v_add_f32_e32 v116, v153, v116
	v_mul_f32_e32 v90, v96, v90
	v_mul_f32_e32 v96, v135, v118
	v_sub_f32_e32 v118, v120, v139
	v_sub_f32_e32 v116, v116, v104
	v_add_f32_e32 v118, v145, v118
	v_med3_f32 v116, v116, s96, v190
	v_mul_f32_e32 v82, v127, v82
	v_sub_f32_e32 v117, v118, v104
	v_mul_f32_e32 v127, 0x3fb8aa3b, v116
	v_med3_f32 v117, v117, s96, v190
	v_exp_f32_e32 v127, v127
	v_mul_f32_e32 v118, 0x3fb8aa3b, v117
	v_exp_f32_e32 v118, v118
	v_exp_f32_e32 v143, v143
	v_mul_f32_e32 v84, v84, v127
	v_add_f32_e32 v127, 0, v206
	v_exp_f32_e32 v131, v131
	v_sub_f32_e32 v127, v121, v127
	v_mul_f32_e32 v88, v88, v118
	v_add_f32_e32 v118, 0, v205
	v_add_f32_e32 v127, v204, v127
	v_sub_f32_e32 v118, v118, v101
	v_sub_f32_e32 v127, v127, v105
	v_med3_f32 v118, v118, s96, v190
	v_med3_f32 v127, v127, s96, v190
	v_mul_f32_e32 v94, v92, v143
	v_mul_f32_e32 v92, v92, v131
	v_mul_f32_e32 v129, 0x3fb8aa3b, v118
	v_mul_f32_e32 v118, 0xbfb8aa3b, v118
	v_mul_f32_e32 v131, 0x3fb8aa3b, v127
	v_mul_f32_e32 v127, 0xbfb8aa3b, v127
	v_exp_f32_e32 v118, v118
	v_exp_f32_e32 v127, v127
	v_add_f32_e32 v87, 0, v87
	v_add_f32_e32 v83, 0, v83
	v_mul_f32_e32 v118, v125, v118
	v_mul_f32_e32 v125, v202, v127
	v_add_f32_e32 v127, v87, v211
	v_add_f32_e32 v87, v87, v95
	v_add_f32_e32 v95, v83, v212
	v_exp_f32_e32 v129, v129
	v_exp_f32_e32 v131, v131
	v_sub_f32_e32 v95, v121, v95
	v_add_f32_e32 v95, v210, v95
	v_add_f32_e32 v83, v83, v91
	v_sub_f32_e32 v91, v127, v101
	v_sub_f32_e32 v95, v95, v105
	v_med3_f32 v91, v91, s96, v190
	v_med3_f32 v95, v95, s96, v190
	v_mul_f32_e32 v129, v97, v129
	v_mul_f32_e32 v97, v97, v131
	v_mul_f32_e32 v127, 0x3fb8aa3b, v91
	v_mul_f32_e32 v131, 0x3fb8aa3b, v95
	v_exp_f32_e32 v127, v127
	v_exp_f32_e32 v131, v131
	v_add_f32_e32 v135, v83, v217
	v_sub_f32_e32 v135, v121, v135
	v_mul_f32_e32 v127, v93, v127
	v_mul_f32_e32 v93, v93, v131
; __device__ __forceinline__ float clamp80(float x) { return fminf(fmaxf(x, -80.f), 80.f); }
;     __device__ __forceinline__ void operator()(const f32x4 (&acc)[2][2][4][2], const pg8::Unit& u, int wr, int wc, int fr, int fq) const {
;     ...
;                         const float rF = tF[0] + tF[1], blF = rF + tF[2] + tF[3];
;                         const float rB = tB[2] + tB[3], blB = rB + tB[0] + tB[1];
;                         float cF = 0.f, cB = 0.f;
; #pragma unroll
;                         for (int m = 0; m < 4; ++m) {
;                             const float bF = pF[m] + cF; cF += tF[m];
;                             const float bB = blB - (pB[m] + cB) + lfB[m]; cB += tB[m];
;                             const float xF = clamp80(bF - rF), xB = clamp80(bB - rB);
;                             const float q = acc[ai][0][m][0][j];
;                             vQF[m][jj] = q * __expf(xF); vKF[m][jj] = kkF[m] * __expf(-xF);
;                             vQB[m][jj] = q * __expf(xB); vKB[m][jj] = kkB[m] * __expf(-xB);
;                         }
;                         rtv[0][j] = rF; rtv[1][j] = rB; rtv[2][j] = blF - rF; rtv[3][j] = blB - rB;
;                     }
; #pragma unroll
;                     for (int m = 0; m < 4; ++m) { oQF[m][jp] = cvt_pk_bf16(vQF[m][0], vQF[m][1]); oQB[m][jp] = cvt_pk_bf16(vQB[m][0], vQB[m][1]); oKF[m][jp] = cvt_pk_bf16(vKF[m][0], vKF[m][1]); oKB[m][jp] = cvt_pk_bf16(vKB[m][0], vKB[m][1]); }
;                 }
;                 if (fr == 0) {
; #pragma unroll
;                     for (int t = 0; t < 4; ++t) *(f32x4*)(RT + (size_t)t * NCHUNK * 512 + (size_t)cid * 512 + ch0) = rtv[t];
;                 }
; #pragma unroll
;                 for (int mp = 0; mp < 2; ++mp) {
;                     const int a = 2 * mp, bb = 2 * mp + 1, odd = fq & 1;
;                     const size_t off = (size_t)(rowc + 16 * (odd ? bb : a) + fr) * 512 + (ch0 - 4 * odd);
;                     const f32x4 va = acc[ai][1][a][1], vb = acc[ai][1][bb][1];
;                     const unsigned oVa0 = cvt_pk_bf16(va[0], va[1]), oVa1 = cvt_pk_bf16(va[2], va[3]), oVb0 = cvt_pk_bf16(vb[0], vb[1]), oVb1 = cvt_pk_bf16(vb[2], vb[3]);
;                     asm volatile("s_nop 1" ::: "memory");
;     ...
;                     WIDE_ST(QF, oQF[a][0], oQF[a][1], oQF[bb][0], oQF[bb][1]); WIDE_ST(QB, oQB[a][0], oQB[a][1], oQB[bb][0], oQB[bb][1]);
	v_add_f32_e32 v131, v87, v216
	v_add_f32_e32 v135, v215, v135
	v_add_f32_e32 v83, v83, v119
	v_sub_f32_e32 v119, v131, v101
	v_sub_f32_e32 v131, v135, v105
	v_med3_f32 v119, v119, s96, v190
	v_med3_f32 v131, v131, s96, v190
	v_mul_f32_e32 v135, 0x3fb8aa3b, v119
	v_mul_f32_e32 v137, 0x3fb8aa3b, v131
	v_mul_f32_e32 v131, 0xbfb8aa3b, v131
	v_add_f32_e32 v87, v87, v109
	v_exp_f32_e32 v135, v135
	v_exp_f32_e32 v137, v137
	v_exp_f32_e32 v131, v131
	v_add_f32_e32 v83, v83, v222
	v_add_f32_e32 v87, v87, v221
	v_sub_f32_e32 v83, v121, v83
	v_add_f32_e32 v83, v218, v83
	v_sub_f32_e32 v87, v87, v101
	v_med3_f32 v87, v87, s96, v190
	v_sub_f32_e32 v83, v83, v105
	v_mul_f32_e32 v117, 0xbfb8aa3b, v117
	v_mul_f32_e32 v135, v89, v135
	v_mul_f32_e32 v89, v89, v137
	v_mul_f32_e32 v137, v214, v131
	v_med3_f32 v83, v83, s96, v190
	v_mul_f32_e32 v131, 0x3fb8aa3b, v87
	v_mul_f32_e32 v86, 0xbfb8aa3b, v86
	v_exp_f32_e32 v117, v117
	v_mul_f32_e32 v116, 0xbfb8aa3b, v116
	v_mul_f32_e32 v91, 0xbfb8aa3b, v91
	v_mul_f32_e32 v95, 0xbfb8aa3b, v95
	v_mul_f32_e32 v119, 0xbfb8aa3b, v119
	v_exp_f32_e32 v131, v131
	v_mul_f32_e32 v87, 0xbfb8aa3b, v87
	v_mul_f32_e32 v139, 0x3fb8aa3b, v83
	v_mul_f32_e32 v83, 0xbfb8aa3b, v83
	v_exp_f32_e32 v86, v86
	v_exp_f32_e32 v116, v116
	v_exp_f32_e32 v91, v91
	v_exp_f32_e32 v95, v95
	v_exp_f32_e32 v119, v119
	v_exp_f32_e32 v87, v87
	v_exp_f32_e32 v139, v139
	v_exp_f32_e32 v83, v83
	v_mov_b32_dpp v113, v221 row_newbcast:15 row_mask:0xf bank_mask:0xf bound_ctrl:1
	v_mul_f32_e32 v117, v141, v117
	v_mul_f32_e32 v141, v85, v131
	v_mul_f32_e32 v86, v155, v86
	v_mul_f32_e32 v116, v151, v116
	v_mul_f32_e32 v91, v208, v91
	v_mul_f32_e32 v95, v209, v95
	v_mul_f32_e32 v119, v213, v119
	v_mul_f32_e32 v87, v219, v87
	v_mul_f32_e32 v85, v85, v139
	v_mul_f32_e32 v83, v220, v83
	v_cvt_pk_bf16_f32 v155, v207, v129
	v_cvt_pk_bf16_f32 v151, v90, v97
	v_cvt_pk_bf16_f32 v147, v133, v118
	v_cvt_pk_bf16_f32 v143, v82, v125
	v_cvt_pk_bf16_f32 v157, v94, v127
	v_cvt_pk_bf16_f32 v153, v92, v93
	v_cvt_pk_bf16_f32 v149, v223, v91
	v_cvt_pk_bf16_f32 v145, v96, v95
	v_cvt_pk_bf16_f32 v131, v224, v135
	v_cvt_pk_bf16_f32 v139, v88, v89
	v_cvt_pk_bf16_f32 v135, v225, v119
	v_cvt_pk_bf16_f32 v127, v117, v137
	v_cvt_pk_bf16_f32 v133, v226, v141
	v_cvt_pk_bf16_f32 v141, v84, v85
	v_cvt_pk_bf16_f32 v137, v86, v87
	v_cvt_pk_bf16_f32 v129, v116, v83
	s_and_saveexec_b64 s[10:11], s[6:7]
	s_cbranch_execz .LBB0_195
	s_ashr_i32 s12, s45, 6
	s_ashr_i32 s13, s12, 31
	s_lshl_b64 s[12:13], s[12:13], 11
	v_lshl_add_u64 v[86:87], v[174:175], 0, s[12:13]
	v_add_co_u32_e32 v82, vcc, 0x110000, v86
	v_pk_add_f32 v[84:85], v[98:99], v[106:107]
	s_nop 0
	v_addc_co_u32_e32 v83, vcc, 0, v87, vcc
	global_store_dwordx4 v[82:83], v[102:105], off
	v_pk_add_f32 v[82:83], v[100:101], v[108:109]
	v_pk_add_f32 v[88:89], v[84:85], v[110:111]
	v_pk_add_f32 v[82:83], v[82:83], v[112:113]
	global_store_dwordx4 v[86:87], v[98:101], off
	v_sub_f32_e32 v84, v82, v100
	v_sub_f32_e32 v82, v88, v98
	v_add_co_u32_e32 v88, vcc, 0x220000, v86
	v_sub_f32_e32 v85, v83, v101
	v_sub_f32_e32 v83, v89, v99
	v_addc_co_u32_e32 v89, vcc, 0, v87, vcc
	v_add_co_u32_e32 v86, vcc, 0x330000, v86
	global_store_dwordx4 v[88:89], v[82:85], off
	s_nop 0
	v_addc_co_u32_e32 v87, vcc, 0, v87, vcc
	v_pk_add_f32 v[82:83], v[114:115], v[102:103] neg_lo:[0,1] neg_hi:[0,1]
	v_pk_add_f32 v[84:85], v[120:121], v[104:105] neg_lo:[0,1] neg_hi:[0,1]
	global_store_dwordx4 v[86:87], v[82:85], off
.LBB0_195:
	s_or_b64 exec, exec, s[10:11]
	s_nop 0
	v_or_b32_e32 v82, v172, v181
	v_sub_u32_e32 v94, v254, v180
	v_ashrrev_i32_e32 v83, 31, v82
	v_ashrrev_i32_e32 v95, 31, v94
	v_lshlrev_b64 v[82:83], 7, v[82:83]
	v_lshl_add_u64 v[82:83], v[82:83], 0, v[94:95]
	v_cvt_pk_bf16_f32 v78, v78, v79
	v_cvt_pk_bf16_f32 v79, v80, v81
	v_cvt_pk_bf16_f32 v80, v74, v75
	v_lshlrev_b64 v[74:75], 1, v[82:83]
	v_cvt_pk_bf16_f32 v81, v76, v77
	v_permlane16_swap_b32_e32 v154, v156
	v_permlane16_swap_b32_e32 v155, v157
	v_lshl_add_u64 v[76:77], s[24:25], 0, v[74:75]
	s_nop 1
	global_store_dwordx4 v[76:77], v[154:157], off
	v_permlane16_swap_b32_e32 v150, v152
	v_permlane16_swap_b32_e32 v151, v153
	v_lshl_add_u64 v[76:77], s[30:31], 0, v[74:75]
	global_store_dwordx4 v[76:77], v[150:153], off
	v_permlane16_swap_b32_e32 v146, v148
	v_permlane16_swap_b32_e32 v147, v149
	v_lshl_add_u64 v[76:77], s[26:27], 0, v[74:75]
	global_store_dwordx4 v[76:77], v[146:149], off
	v_lshl_add_u64 v[76:77], s[34:35], 0, v[74:75]
	v_permlane16_swap_b32_e32 v78, v80
	v_permlane16_swap_b32_e32 v79, v81
	v_lshl_add_u64 v[74:75], s[28:29], 0, v[74:75]
	global_store_dwordx4 v[74:75], v[78:81], off
	v_or_b32_e32 v74, v172, v179
	v_ashrrev_i32_e32 v75, 31, v74
	v_lshlrev_b64 v[74:75], 7, v[74:75]
	v_permlane16_swap_b32_e32 v142, v144
	v_permlane16_swap_b32_e32 v143, v145
	v_lshl_add_u64 v[74:75], v[74:75], 0, v[94:95]
	v_max_f32_e32 v62, 0xc1f00000, v62
	global_store_dwordx4 v[76:77], v[142:145], off
	v_cvt_pk_bf16_f32 v70, v70, v71
	v_cvt_pk_bf16_f32 v71, v72, v73
	v_cvt_pk_bf16_f32 v72, v66, v67
	v_lshlrev_b64 v[66:67], 1, v[74:75]
	v_mul_f32_e32 v62, 0xbfb8aa3b, v62
	v_cvt_pk_bf16_f32 v73, v68, v69
	v_permlane16_swap_b32_e32 v130, v132
	v_permlane16_swap_b32_e32 v131, v133
	v_lshl_add_u64 v[68:69], s[24:25], 0, v[66:67]
	v_exp_f32_e32 v62, v62
	s_nop 1
	global_store_dwordx4 v[68:69], v[130:133], off
	v_permlane16_swap_b32_e32 v138, v140
	v_permlane16_swap_b32_e32 v139, v141
	v_lshl_add_u64 v[68:69], s[30:31], 0, v[66:67]
	global_store_dwordx4 v[68:69], v[138:141], off
	v_permlane16_swap_b32_e32 v134, v136
	v_permlane16_swap_b32_e32 v135, v137
	v_lshl_add_u64 v[68:69], s[26:27], 0, v[66:67]
; __device__ __forceinline__ unsigned cvt_pk_bf16(float lo, float hi) { unsigned r; asm volatile("v_cvt_pk_bf16_f32 %0, %1, %2" : "=v"(r) : "v"(lo), "v"(hi)); return r; }
; __device__ __forceinline__ float scan16(float x) { x += dpp_shr<1>(x); x += dpp_shr<2>(x); x += dpp_shr<4>(x); x += dpp_shr<8>(x); return x; }
; #define WIDE_ST(P, x0a, x1a, x0b, x1b) do { const u32x2 s0 = __builtin_amdgcn_permlane16_swap((x0a), (x0b), false, false), s1 = __builtin_amdgcn_permlane16_swap((x1a), (x1b), false, false); \
;                         *(u32x4*)((P) + off) = (u32x4){s0[0], s1[0], s0[1], s1[1]}; } while (0)
;     __device__ __forceinline__ void operator()(const f32x4 (&acc)[2][2][4][2], const pg8::Unit& u, int wr, int wc, int fr, int fq) const {
;     ...
;                             { const float z = acc[ai][0][m][1][j]; const float e = __expf(fminf(-z, 30.f)); const float s = __builtin_amdgcn_rcpf(1.f + e); lfF[m] = __logf(lbF[j] + (1.f - lbF[j]) * s); kkF[m] = (1.f - lbF[j]) * e * s; }
;                             { const float z = acc[ai][1][m][0][j]; const float e = __expf(fminf(-z, 30.f)); const float s = __builtin_amdgcn_rcpf(1.f + e); lfB[m] = __logf(lbB[j] + (1.f - lbB[j]) * s); kkB[m] = (1.f - lbB[j]) * e * s; }
;                             pF[m] = scan16(lfF[m]); pB[m] = scan16(lfB[m]);
;     ...
;                     const unsigned oVa0 = cvt_pk_bf16(va[0], va[1]), oVa1 = cvt_pk_bf16(va[2], va[3]), oVb0 = cvt_pk_bf16(vb[0], vb[1]), oVb1 = cvt_pk_bf16(vb[2], vb[3]);
;                     asm volatile("s_nop 1" ::: "memory");
;     ...
;                     WIDE_ST(QF, oQF[a][0], oQF[a][1], oQF[bb][0], oQF[bb][1]); WIDE_ST(QB, oQB[a][0], oQB[a][1], oQB[bb][0], oQB[bb][1]);
;                     WIDE_ST(KF, oKF[a][0], oKF[a][1], oKF[bb][0], oKF[bb][1]); WIDE_ST(KB, oKB[a][0], oKB[a][1], oKB[bb][0], oKB[bb][1]);
;                     WIDE_ST(V, oVa0, oVa1, oVb0, oVb1);
	global_store_dwordx4 v[68:69], v[134:137], off
	v_permlane16_swap_b32_e32 v126, v128
	v_permlane16_swap_b32_e32 v127, v129
	v_lshl_add_u64 v[68:69], s[34:35], 0, v[66:67]
	global_store_dwordx4 v[68:69], v[126:129], off
	v_add_f32_e32 v68, 1.0, v62
	v_rcp_f32_e32 v68, v68
	v_max_f32_e32 v58, 0xc1f00000, v58
	v_mul_f32_e32 v58, 0xbfb8aa3b, v58
	v_fma_f32 v69, v68, v197, v196
	v_exp_f32_e32 v58, v58
	v_permlane16_swap_b32_e32 v70, v72
	v_log_f32_e32 v69, v69
	v_permlane16_swap_b32_e32 v71, v73
	v_lshl_add_u64 v[66:67], s[28:29], 0, v[66:67]
	global_store_dwordx4 v[66:67], v[70:73], off
	v_add_f32_e32 v67, 1.0, v58
	v_rcp_f32_e32 v67, v67
	s_nop 0
	v_fma_f32 v70, v67, v198, v195
	v_mul_f32_e32 v62, v62, v197
	v_mul_f32_e32 v66, 0x3f317218, v69
	v_mul_f32_e32 v74, v68, v62
	v_log_f32_e32 v70, v70
	v_max_f32_e32 v54, 0xc1f00000, v54
	v_mul_f32_e32 v54, 0xbfb8aa3b, v54
	v_mul_f32_e32 v58, v58, v198
	v_mul_f32_e32 v62, 0x3f317218, v70
	v_mov_b32_e32 v73, v62
	v_exp_f32_e32 v62, v54
	v_mul_f32_e32 v72, v67, v58
	v_add_f32_dpp v58, v66, v66 row_shr:1 row_mask:0xf bank_mask:0xf bound_ctrl:1
	v_max_f32_e32 v50, 0xc1f00000, v50
	s_nop 0
	v_add_f32_dpp v54, v58, v58 row_shr:2 row_mask:0xf bank_mask:0xf bound_ctrl:1
	v_mul_f32_e32 v50, 0xbfb8aa3b, v50
	v_exp_f32_e32 v50, v50
	v_add_f32_dpp v54, v54, v54 row_shr:4 row_mask:0xf bank_mask:0xf bound_ctrl:1
	v_max_f32_e32 v46, 0xc1f00000, v46
	s_nop 0
	v_add_f32_dpp v67, v54, v54 row_shr:8 row_mask:0xf bank_mask:0xf bound_ctrl:1
	v_add_f32_e32 v54, 1.0, v62
	v_rcp_f32_e32 v66, v54
	v_add_f32_e32 v71, 1.0, v50
	v_rcp_f32_e32 v71, v71
	v_mul_f32_e32 v62, v62, v197
	v_fma_f32 v58, v66, v197, v196
	v_fma_f32 v75, v71, v198, v195
	v_mul_f32_e32 v77, v66, v62
	v_log_f32_e32 v68, v58
	v_mul_f32_e32 v46, 0xbfb8aa3b, v46
	v_exp_f32_e32 v46, v46
	v_mul_f32_e32 v50, v50, v198
	v_max_f32_e32 v42, 0xc1f00000, v42
	v_mul_f32_e32 v68, 0x3f317218, v68
	v_mul_f32_e32 v42, 0xbfb8aa3b, v42
	v_log_f32_e32 v75, v75
	v_exp_f32_e32 v42, v42
	s_nop 0
	v_add_f32_e32 v79, 1.0, v42
	v_rcp_f32_e32 v79, v79
	v_mul_f32_e32 v62, 0x3f317218, v75
	v_mov_b32_e32 v76, v62
	v_add_f32_e32 v62, 1.0, v46
	v_mul_f32_e32 v75, v71, v50
	v_add_f32_dpp v50, v68, v68 row_shr:1 row_mask:0xf bank_mask:0xf bound_ctrl:1
	v_rcp_f32_e32 v68, v62
	v_fma_f32 v80, v79, v198, v195
	v_max_f32_e32 v38, 0xc1f00000, v38
	v_mul_f32_e32 v46, v46, v197
	v_fma_f32 v66, v68, v197, v196
	v_mul_f32_e32 v38, 0xbfb8aa3b, v38
	v_mul_f32_e32 v42, v42, v198
	v_log_f32_e32 v70, v66
	v_exp_f32_e32 v38, v38
	v_mul_f32_e32 v79, v79, v42
	v_max_f32_e32 v34, 0xc1f00000, v34
	v_mul_f32_e32 v34, 0xbfb8aa3b, v34
	v_mul_f32_e32 v70, 0x3f317218, v70
	v_exp_f32_e32 v34, v34
	v_log_f32_e32 v80, v80
	v_mul_f32_e32 v81, v68, v46
	v_add_f32_dpp v42, v70, v70 row_shr:1 row_mask:0xf bank_mask:0xf bound_ctrl:1
	s_nop 1
	v_add_f32_dpp v42, v42, v42 row_shr:2 row_mask:0xf bank_mask:0xf bound_ctrl:1
	s_nop 1
	v_add_f32_dpp v42, v42, v42 row_shr:4 row_mask:0xf bank_mask:0xf bound_ctrl:1
	v_add_f32_e32 v84, 1.0, v34
	v_mul_f32_e32 v46, 0x3f317218, v80
	v_add_f32_dpp v82, v42, v42 row_shr:8 row_mask:0xf bank_mask:0xf bound_ctrl:1
	v_add_f32_e32 v42, 1.0, v38
	v_mov_b32_e32 v80, v46
	v_rcp_f32_e32 v46, v42
	v_rcp_f32_e32 v84, v84
	v_mul_f32_e32 v38, v38, v197
	v_mul_f32_e32 v34, v34, v198
	v_fmac_f32_e32 v196, v46, v197
	v_fmac_f32_e32 v195, v84, v198
	v_mul_f32_e32 v38, v46, v38
	v_log_f32_e32 v68, v196
	v_mul_f32_e32 v84, v84, v34
	v_max_f32_e32 v59, 0xc1f00000, v59
	v_mul_f32_e32 v59, 0xbfb8aa3b, v59
	v_add_f32_dpp v54, v73, v73 row_shr:1 row_mask:0xf bank_mask:0xf bound_ctrl:1
	v_mul_f32_e32 v68, 0x3f317218, v68
	v_exp_f32_e32 v59, v59
	v_log_f32_e32 v85, v195
	v_add_f32_dpp v34, v68, v68 row_shr:1 row_mask:0xf bank_mask:0xf bound_ctrl:1
	v_add_f32_dpp v54, v54, v54 row_shr:2 row_mask:0xf bank_mask:0xf bound_ctrl:1
	s_nop 0
	v_add_f32_dpp v34, v34, v34 row_shr:2 row_mask:0xf bank_mask:0xf bound_ctrl:1
	v_add_f32_dpp v54, v54, v54 row_shr:4 row_mask:0xf bank_mask:0xf bound_ctrl:1
	v_mul_f32_e32 v46, 0x3f317218, v85
	v_mov_b32_e32 v85, v46
	v_max_f32_e32 v46, 0xc1f00000, v63
	v_mul_f32_e32 v46, 0xbfb8aa3b, v46
	v_exp_f32_e32 v63, v46
	v_add_f32_dpp v34, v34, v34 row_shr:4 row_mask:0xf bank_mask:0xf bound_ctrl:1
	v_add_f32_dpp v69, v54, v54 row_shr:8 row_mask:0xf bank_mask:0xf bound_ctrl:1
	v_add_f32_e32 v89, 0, v69
	v_add_f32_e32 v46, 1.0, v63
	v_rcp_f32_e32 v71, v46
	v_add_f32_dpp v86, v34, v34 row_shr:8 row_mask:0xf bank_mask:0xf bound_ctrl:1
	v_add_f32_dpp v34, v85, v85 row_shr:1 row_mask:0xf bank_mask:0xf bound_ctrl:1
	v_mov_b32_dpp v54, v69 row_newbcast:15 row_mask:0xf bank_mask:0xf bound_ctrl:1
	v_add_f32_e32 v69, 1.0, v59
	v_add_f32_dpp v34, v34, v34 row_shr:2 row_mask:0xf bank_mask:0xf bound_ctrl:1
	v_rcp_f32_e32 v69, v69
	v_mov_b32_dpp v58, v67 row_newbcast:15 row_mask:0xf bank_mask:0xf bound_ctrl:1
	v_add_f32_dpp v34, v34, v34 row_shr:4 row_mask:0xf bank_mask:0xf bound_ctrl:1
	v_add_f32_e32 v88, 0, v67
	v_fma_f32 v90, v69, v200, v193
	v_add_f32_dpp v87, v34, v34 row_shr:8 row_mask:0xf bank_mask:0xf bound_ctrl:1
	v_fma_f32 v34, v71, v199, v194
	v_mul_f32_e32 v63, v63, v199
	v_log_f32_e32 v34, v34
	v_max_f32_e32 v55, 0xc1f00000, v55
	v_mul_f32_e32 v55, 0xbfb8aa3b, v55
	v_mul_f32_e32 v59, v59, v200
	v_mul_f32_e32 v92, v69, v59
	v_mul_f32_e32 v34, 0x3f317218, v34
	v_max_f32_e32 v51, 0xc1f00000, v51
	v_log_f32_e32 v90, v90
	v_mul_f32_e32 v91, v71, v63
	v_add_f32_dpp v34, v34, v34 row_shr:1 row_mask:0xf bank_mask:0xf bound_ctrl:1
	s_nop 1
	v_add_f32_dpp v34, v34, v34 row_shr:2 row_mask:0xf bank_mask:0xf bound_ctrl:1
	v_mul_f32_e32 v51, 0xbfb8aa3b, v51
	v_mul_f32_e32 v63, 0x3f317218, v90
; __device__ __forceinline__ float scan16(float x) { x += dpp_shr<1>(x); x += dpp_shr<2>(x); x += dpp_shr<4>(x); x += dpp_shr<8>(x); return x; }
;     __device__ __forceinline__ void operator()(const f32x4 (&acc)[2][2][4][2], const pg8::Unit& u, int wr, int wc, int fr, int fq) const {
;     ...
;                             { const float z = acc[ai][0][m][1][j]; const float e = __expf(fminf(-z, 30.f)); const float s = __builtin_amdgcn_rcpf(1.f + e); lfF[m] = __logf(lbF[j] + (1.f - lbF[j]) * s); kkF[m] = (1.f - lbF[j]) * e * s; }
;                             { const float z = acc[ai][1][m][0][j]; const float e = __expf(fminf(-z, 30.f)); const float s = __builtin_amdgcn_rcpf(1.f + e); lfB[m] = __logf(lbB[j] + (1.f - lbB[j]) * s); kkB[m] = (1.f - lbB[j]) * e * s; }
;                             pF[m] = scan16(lfF[m]); pB[m] = scan16(lfB[m]);
;                             tF[m] = __int_as_float(__builtin_amdgcn_update_dpp(0, __float_as_int(pF[m]), 0x15F, 0xf, 0xf, true));
;                             tB[m] = __int_as_float(__builtin_amdgcn_update_dpp(0, __float_as_int(pB[m]), 0x15F, 0xf, 0xf, true));
	v_mov_b32_e32 v90, v63
	v_exp_f32_e32 v63, v55
	v_add_f32_dpp v34, v34, v34 row_shr:4 row_mask:0xf bank_mask:0xf bound_ctrl:1
	v_exp_f32_e32 v51, v51
	s_nop 0
	v_add_f32_dpp v93, v34, v34 row_shr:8 row_mask:0xf bank_mask:0xf bound_ctrl:1
	v_add_f32_e32 v34, 1.0, v63
	v_rcp_f32_e32 v34, v34
	v_add_f32_e32 v71, 1.0, v51
	v_rcp_f32_e32 v71, v71
	v_mul_f32_e32 v63, v63, v199
	v_fma_f32 v59, v34, v199, v194
	v_fma_f32 v97, v71, v200, v193
	v_max_f32_e32 v47, 0xc1f00000, v47
	v_log_f32_e32 v67, v59
	v_mul_f32_e32 v47, 0xbfb8aa3b, v47
	v_exp_f32_e32 v47, v47
	v_max_f32_e32 v43, 0xc1f00000, v43
	v_mul_f32_e32 v43, 0xbfb8aa3b, v43
	v_mul_f32_e32 v67, 0x3f317218, v67
	v_exp_f32_e32 v43, v43
	v_log_f32_e32 v97, v97
	v_mul_f32_e32 v98, v34, v63
	v_max_f32_e32 v39, 0xc1f00000, v39
	v_mul_f32_e32 v39, 0xbfb8aa3b, v39
	v_mul_f32_e32 v34, 0x3f317218, v97
	v_mov_b32_e32 v97, v34
	v_mul_f32_e32 v34, v51, v200
	v_mul_f32_e32 v99, v71, v34
	v_add_f32_dpp v51, v97, v97 row_shr:1 row_mask:0xf bank_mask:0xf bound_ctrl:1
	v_add_f32_dpp v34, v67, v67 row_shr:1 row_mask:0xf bank_mask:0xf bound_ctrl:1
	v_add_f32_e32 v71, 1.0, v43
	v_add_f32_dpp v51, v51, v51 row_shr:2 row_mask:0xf bank_mask:0xf bound_ctrl:1
	v_add_f32_dpp v34, v34, v34 row_shr:2 row_mask:0xf bank_mask:0xf bound_ctrl:1
	v_rcp_f32_e32 v71, v71
	v_add_f32_dpp v51, v51, v51 row_shr:4 row_mask:0xf bank_mask:0xf bound_ctrl:1
	v_add_f32_dpp v34, v34, v34 row_shr:4 row_mask:0xf bank_mask:0xf bound_ctrl:1
	v_exp_f32_e32 v39, v39
	v_add_f32_dpp v101, v51, v51 row_shr:8 row_mask:0xf bank_mask:0xf bound_ctrl:1
	v_add_f32_dpp v100, v34, v34 row_shr:8 row_mask:0xf bank_mask:0xf bound_ctrl:1
	v_add_f32_e32 v34, 1.0, v47
	v_rcp_f32_e32 v34, v34
	v_fma_f32 v102, v71, v200, v193
	v_mul_f32_e32 v47, v47, v199
	v_fma_f32 v63, v34, v199, v194
	v_max_f32_e32 v35, 0xc1f00000, v35
	v_mul_f32_e32 v35, 0xbfb8aa3b, v35
	v_log_f32_e32 v69, v63
	v_exp_f32_e32 v35, v35
	v_add_f32_dpp v50, v50, v50 row_shr:2 row_mask:0xf bank_mask:0xf bound_ctrl:1
	v_mov_b32_dpp v59, v93 row_newbcast:15 row_mask:0xf bank_mask:0xf bound_ctrl:1
	s_nop 0
	v_add_f32_dpp v50, v50, v50 row_shr:4 row_mask:0xf bank_mask:0xf bound_ctrl:1
	v_mov_b32_dpp v67, v100 row_newbcast:15 row_mask:0xf bank_mask:0xf bound_ctrl:1
	v_mul_f32_e32 v51, 0x3f317218, v69
	v_add_f32_dpp v50, v50, v50 row_shr:8 row_mask:0xf bank_mask:0xf bound_ctrl:1
	v_log_f32_e32 v102, v102
	v_mul_f32_e32 v103, v34, v47
	v_mov_b32_dpp v66, v50 row_newbcast:15 row_mask:0xf bank_mask:0xf bound_ctrl:1
	v_add_f32_dpp v42, v80, v80 row_shr:1 row_mask:0xf bank_mask:0xf bound_ctrl:1
	v_add_f32_dpp v62, v76, v76 row_shr:1 row_mask:0xf bank_mask:0xf bound_ctrl:1
	v_mul_f32_e32 v34, 0x3f317218, v102
	v_mov_b32_e32 v102, v34
	v_mul_f32_e32 v34, v43, v200
	v_mul_f32_e32 v104, v71, v34
	v_add_f32_e32 v71, 1.0, v35
	v_add_f32_dpp v34, v51, v51 row_shr:1 row_mask:0xf bank_mask:0xf bound_ctrl:1
	v_rcp_f32_e32 v71, v71
	v_add_f32_dpp v42, v42, v42 row_shr:2 row_mask:0xf bank_mask:0xf bound_ctrl:1
	v_add_f32_dpp v34, v34, v34 row_shr:2 row_mask:0xf bank_mask:0xf bound_ctrl:1
	v_add_f32_dpp v43, v102, v102 row_shr:1 row_mask:0xf bank_mask:0xf bound_ctrl:1
	v_fmac_f32_e32 v193, v71, v200
	v_add_f32_dpp v34, v34, v34 row_shr:4 row_mask:0xf bank_mask:0xf bound_ctrl:1
	v_add_f32_dpp v42, v42, v42 row_shr:4 row_mask:0xf bank_mask:0xf bound_ctrl:1
	v_add_f32_dpp v55, v90, v90 row_shr:1 row_mask:0xf bank_mask:0xf bound_ctrl:1
	v_add_f32_dpp v105, v34, v34 row_shr:8 row_mask:0xf bank_mask:0xf bound_ctrl:1
	v_add_f32_e32 v34, 1.0, v39
	v_rcp_f32_e32 v34, v34
	v_mul_f32_e32 v39, v39, v199
	v_add_f32_dpp v83, v42, v42 row_shr:8 row_mask:0xf bank_mask:0xf bound_ctrl:1
	v_mov_b32_dpp v42, v82 row_newbcast:15 row_mask:0xf bank_mask:0xf bound_ctrl:1
	v_fmac_f32_e32 v194, v34, v199
	v_mul_f32_e32 v108, v34, v39
	v_add_f32_dpp v43, v43, v43 row_shr:2 row_mask:0xf bank_mask:0xf bound_ctrl:1
	v_log_f32_e32 v47, v194
	v_add_f32_dpp v62, v62, v62 row_shr:2 row_mask:0xf bank_mask:0xf bound_ctrl:1
	v_add_f32_dpp v55, v55, v55 row_shr:2 row_mask:0xf bank_mask:0xf bound_ctrl:1
	v_add_f32_dpp v43, v43, v43 row_shr:4 row_mask:0xf bank_mask:0xf bound_ctrl:1
	v_add_f32_dpp v62, v62, v62 row_shr:4 row_mask:0xf bank_mask:0xf bound_ctrl:1
	v_add_f32_dpp v55, v55, v55 row_shr:4 row_mask:0xf bank_mask:0xf bound_ctrl:1
	v_mul_f32_e32 v47, 0x3f317218, v47
	v_add_f32_dpp v106, v43, v43 row_shr:8 row_mask:0xf bank_mask:0xf bound_ctrl:1
	v_log_f32_e32 v107, v193
	v_add_f32_dpp v78, v62, v62 row_shr:8 row_mask:0xf bank_mask:0xf bound_ctrl:1
	v_mov_b32_dpp v70, v83 row_newbcast:15 row_mask:0xf bank_mask:0xf bound_ctrl:1
	v_mov_b32_dpp v68, v87 row_newbcast:15 row_mask:0xf bank_mask:0xf bound_ctrl:1
	v_add_f32_dpp v96, v55, v55 row_shr:8 row_mask:0xf bank_mask:0xf bound_ctrl:1
	v_mul_f32_e32 v34, 0x3f317218, v107
	v_mov_b32_e32 v107, v34
	v_mul_f32_e32 v34, v35, v200
	v_mul_f32_e32 v109, v71, v34
	v_mov_b32_dpp v69, v106 row_newbcast:15 row_mask:0xf bank_mask:0xf bound_ctrl:1
	v_add_f32_dpp v34, v47, v47 row_shr:1 row_mask:0xf bank_mask:0xf bound_ctrl:1
	v_mov_b32_dpp v62, v78 row_newbcast:15 row_mask:0xf bank_mask:0xf bound_ctrl:1
	v_mov_b32_dpp v55, v96 row_newbcast:15 row_mask:0xf bank_mask:0xf bound_ctrl:1
	v_add_f32_dpp v34, v34, v34 row_shr:2 row_mask:0xf bank_mask:0xf bound_ctrl:1
	v_mov_b32_dpp v63, v101 row_newbcast:15 row_mask:0xf bank_mask:0xf bound_ctrl:1
	v_mov_b32_dpp v43, v105 row_newbcast:15 row_mask:0xf bank_mask:0xf bound_ctrl:1
	v_add_f32_dpp v34, v34, v34 row_shr:4 row_mask:0xf bank_mask:0xf bound_ctrl:1
	v_mov_b32_dpp v46, v86 row_newbcast:15 row_mask:0xf bank_mask:0xf bound_ctrl:1
	s_nop 0
; __device__ __forceinline__ float scan16(float x) { x += dpp_shr<1>(x); x += dpp_shr<2>(x); x += dpp_shr<4>(x); x += dpp_shr<8>(x); return x; }
; __device__ __forceinline__ float clamp80(float x) { return fminf(fmaxf(x, -80.f), 80.f); }
;     __device__ __forceinline__ void operator()(const f32x4 (&acc)[2][2][4][2], const pg8::Unit& u, int wr, int wc, int fr, int fq) const {
;     ...
;                             { const float z = acc[ai][0][m][1][j]; const float e = __expf(fminf(-z, 30.f)); const float s = __builtin_amdgcn_rcpf(1.f + e); lfF[m] = __logf(lbF[j] + (1.f - lbF[j]) * s); kkF[m] = (1.f - lbF[j]) * e * s; }
;                             { const float z = acc[ai][1][m][0][j]; const float e = __expf(fminf(-z, 30.f)); const float s = __builtin_amdgcn_rcpf(1.f + e); lfB[m] = __logf(lbB[j] + (1.f - lbB[j]) * s); kkB[m] = (1.f - lbB[j]) * e * s; }
;                             pF[m] = scan16(lfF[m]); pB[m] = scan16(lfB[m]);
;                             tF[m] = __int_as_float(__builtin_amdgcn_update_dpp(0, __float_as_int(pF[m]), 0x15F, 0xf, 0xf, true));
;                             tB[m] = __int_as_float(__builtin_amdgcn_update_dpp(0, __float_as_int(pB[m]), 0x15F, 0xf, 0xf, true));
;                         }
;                         const float rF = tF[0] + tF[1], blF = rF + tF[2] + tF[3];
;                         const float rB = tB[2] + tB[3], blB = rB + tB[0] + tB[1];
;                         float cF = 0.f, cB = 0.f;
; #pragma unroll
;                         for (int m = 0; m < 4; ++m) {
;                             const float bF = pF[m] + cF; cF += tF[m];
;                             const float bB = blB - (pB[m] + cB) + lfB[m]; cB += tB[m];
;                             const float xF = clamp80(bF - rF), xB = clamp80(bB - rB);
;                             const float q = acc[ai][0][m][0][j];
;                             vQF[m][jj] = q * __expf(xF); vKF[m][jj] = kkF[m] * __expf(-xF);
;                             vQB[m][jj] = q * __expf(xB); vKB[m][jj] = kkB[m] * __expf(-xB);
;                         }
	v_add_f32_dpp v110, v34, v34 row_shr:8 row_mask:0xf bank_mask:0xf bound_ctrl:1
	v_add_f32_dpp v34, v107, v107 row_shr:1 row_mask:0xf bank_mask:0xf bound_ctrl:1
	v_max_f32_e32 v52, 0xc1f00000, v52
	v_mul_f32_e32 v52, 0xbfb8aa3b, v52
	v_add_f32_dpp v34, v34, v34 row_shr:2 row_mask:0xf bank_mask:0xf bound_ctrl:1
	v_exp_f32_e32 v52, v52
	s_nop 0
	v_add_f32_dpp v34, v34, v34 row_shr:4 row_mask:0xf bank_mask:0xf bound_ctrl:1
	v_max_f32_e32 v44, 0xc1f00000, v44
	v_mul_f32_e32 v44, 0xbfb8aa3b, v44
	v_add_f32_dpp v111, v34, v34 row_shr:8 row_mask:0xf bank_mask:0xf bound_ctrl:1
	v_pk_add_f32 v[34:35], v[58:59], v[66:67]
	v_add_f32_e32 v58, 0, v58
	v_sub_f32_e32 v39, v88, v34
	v_med3_f32 v39, v39, s96, v190
	v_mul_f32_e32 v47, 0x3fb8aa3b, v39
	v_exp_f32_e32 v51, v47
	v_add_f32_e32 v50, v58, v50
	v_sub_f32_e32 v50, v50, v34
	v_mul_f32_e32 v39, 0xbfb8aa3b, v39
	v_med3_f32 v50, v50, s96, v190
	v_mul_f32_e32 v88, v30, v51
	v_exp_f32_e32 v39, v39
	v_mul_f32_e32 v51, 0x3fb8aa3b, v50
	v_mul_f32_e32 v50, 0xbfb8aa3b, v50
	v_exp_f32_e32 v50, v50
	v_mul_f32_e32 v74, v74, v39
	v_add_f32_e32 v39, v58, v66
	v_exp_f32_e32 v51, v51
	v_mul_f32_e32 v66, v77, v50
	v_add_f32_e32 v50, v39, v82
	v_add_f32_e32 v39, v39, v42
	v_add_f32_e32 v39, v39, v86
	v_sub_f32_e32 v50, v50, v34
	v_sub_f32_e32 v39, v39, v34
	v_med3_f32 v50, v50, s96, v190
	v_med3_f32 v39, v39, s96, v190
	v_mul_f32_e32 v58, v26, v51
	v_mul_f32_e32 v51, 0x3fb8aa3b, v50
	v_mul_f32_e32 v50, 0xbfb8aa3b, v50
	v_mul_f32_e32 v77, 0x3fb8aa3b, v39
	v_mul_f32_e32 v39, 0xbfb8aa3b, v39
	v_exp_f32_e32 v50, v50
	v_exp_f32_e32 v39, v39
	v_exp_f32_e32 v51, v51
	v_mov_b32_dpp v71, v111 row_newbcast:15 row_mask:0xf bank_mask:0xf bound_ctrl:1
	v_mul_f32_e32 v81, v81, v50
	v_mul_f32_e32 v113, v38, v39
	v_pk_add_f32 v[38:39], v[68:69], v[70:71]
	v_add_f32_e32 v50, 0, v54
	v_mul_f32_e32 v112, v22, v51
	v_add_f32_e32 v68, v50, v78
	v_add_f32_e32 v71, v50, v62
	v_pk_add_f32 v[50:51], v[38:39], v[54:55]
	v_add_f32_e32 v70, v71, v70
	v_pk_add_f32 v[50:51], v[50:51], v[62:63]
	v_add_f32_e32 v70, v70, v87
	v_sub_f32_e32 v54, v50, v89
	v_sub_f32_e32 v68, v50, v68
	v_add_f32_e32 v54, v73, v54
	v_add_f32_e32 v68, v76, v68
	v_sub_f32_e32 v54, v54, v38
	v_sub_f32_e32 v68, v68, v38
	v_med3_f32 v54, v54, s96, v190
	v_med3_f32 v68, v68, s96, v190
	v_mul_f32_e32 v62, 0x3fb8aa3b, v54
	v_mul_f32_e32 v73, 0x3fb8aa3b, v68
	v_mul_f32_e32 v68, 0xbfb8aa3b, v68
	v_exp_f32_e32 v62, v62
	v_exp_f32_e32 v68, v68
	v_mul_f32_e32 v54, 0xbfb8aa3b, v54
	v_exp_f32_e32 v54, v54
	v_sub_f32_e32 v70, v50, v70
	v_add_f32_e32 v78, v71, v83
	v_add_f32_e32 v70, v85, v70
	v_mul_f32_e32 v30, v30, v62
	v_mul_f32_e32 v62, v75, v68
	v_sub_f32_e32 v68, v50, v78
	v_sub_f32_e32 v70, v70, v38
	v_add_f32_e32 v68, v80, v68
	v_med3_f32 v70, v70, s96, v190
	v_mul_f32_e32 v54, v72, v54
	v_sub_f32_e32 v68, v68, v38
	v_mul_f32_e32 v72, 0x3fb8aa3b, v70
	v_exp_f32_e32 v77, v77
	v_med3_f32 v68, v68, s96, v190
	v_exp_f32_e32 v72, v72
	v_mul_f32_e32 v71, 0x3fb8aa3b, v68
	v_mul_f32_e32 v70, 0xbfb8aa3b, v70
	v_exp_f32_e32 v71, v71
	v_exp_f32_e32 v70, v70
	v_mul_f32_e32 v77, v18, v77
	v_mul_f32_e32 v18, v18, v72
	v_add_f32_e32 v72, 0, v96
	v_exp_f32_e32 v73, v73
	v_sub_f32_e32 v72, v51, v72
	v_mul_f32_e32 v22, v22, v71
	v_mul_f32_e32 v71, v84, v70
	v_add_f32_e32 v70, 0, v93
	v_add_f32_e32 v72, v90, v72
	v_sub_f32_e32 v70, v70, v35
	v_sub_f32_e32 v72, v72, v39
	v_med3_f32 v70, v70, s96, v190
	v_med3_f32 v72, v72, s96, v190
	v_mul_f32_e32 v26, v26, v73
	v_mul_f32_e32 v73, 0x3fb8aa3b, v70
	v_mul_f32_e32 v75, 0x3fb8aa3b, v72
	v_exp_f32_e32 v73, v73
	v_exp_f32_e32 v75, v75
	v_add_f32_e32 v59, 0, v59
	v_add_f32_e32 v55, 0, v55
	v_mul_f32_e32 v73, v31, v73
	v_mul_f32_e32 v31, v31, v75
	v_add_f32_e32 v75, v59, v100
	v_add_f32_e32 v59, v59, v67
	v_add_f32_e32 v67, v55, v101
	v_sub_f32_e32 v67, v51, v67
	v_add_f32_e32 v67, v97, v67
	v_add_f32_e32 v55, v55, v63
	v_sub_f32_e32 v63, v75, v35
	v_sub_f32_e32 v67, v67, v39
	v_med3_f32 v63, v63, s96, v190
	v_med3_f32 v67, v67, s96, v190
	v_mul_f32_e32 v75, 0x3fb8aa3b, v63
	v_mul_f32_e32 v76, 0x3fb8aa3b, v67
	v_exp_f32_e32 v75, v75
	v_exp_f32_e32 v76, v76
	v_add_f32_e32 v78, v55, v106
	v_sub_f32_e32 v78, v51, v78
	v_mul_f32_e32 v75, v27, v75
	v_mul_f32_e32 v27, v27, v76
	v_add_f32_e32 v76, v59, v105
	v_add_f32_e32 v55, v55, v69
	v_sub_f32_e32 v69, v76, v35
	v_add_f32_e32 v78, v102, v78
	v_med3_f32 v69, v69, s96, v190
	v_sub_f32_e32 v76, v78, v39
	v_mul_f32_e32 v78, 0x3fb8aa3b, v69
	v_add_f32_e32 v59, v59, v43
	v_exp_f32_e32 v78, v78
	v_add_f32_e32 v59, v59, v110
	v_sub_f32_e32 v59, v59, v35
	v_med3_f32 v59, v59, s96, v190
	v_mul_f32_e32 v68, 0xbfb8aa3b, v68
	v_mul_f32_e32 v70, 0xbfb8aa3b, v70
	v_mul_f32_e32 v72, 0xbfb8aa3b, v72
	v_mul_f32_e32 v83, v23, v78
	v_mul_f32_e32 v78, 0x3fb8aa3b, v59
	v_exp_f32_e32 v68, v68
	v_exp_f32_e32 v70, v70
	v_exp_f32_e32 v72, v72
	v_exp_f32_e32 v78, v78
	v_med3_f32 v76, v76, s96, v190
	v_mul_f32_e32 v68, v79, v68
	v_mul_f32_e32 v70, v91, v70
	v_mul_f32_e32 v72, v92, v72
	v_mul_f32_e32 v79, 0x3fb8aa3b, v76
	v_add_f32_e32 v55, v55, v111
	v_mul_f32_e32 v85, v19, v78
	v_cvt_pk_bf16_f32 v90, v88, v73
	v_cvt_pk_bf16_f32 v86, v30, v31
	v_cvt_pk_bf16_f32 v82, v74, v70
	v_cvt_pk_bf16_f32 v78, v54, v72
	v_cvt_pk_bf16_f32 v92, v58, v75
	v_cvt_pk_bf16_f32 v88, v26, v27
	v_exp_f32_e32 v79, v79
	v_sub_f32_e32 v55, v51, v55
	v_max_f32_e32 v26, 0xc1f00000, v64
	v_mul_f32_e32 v63, 0xbfb8aa3b, v63
	v_mul_f32_e32 v67, 0xbfb8aa3b, v67
	v_add_f32_e32 v55, v107, v55
	v_mul_f32_e32 v26, 0xbfb8aa3b, v26
	v_exp_f32_e32 v63, v63
	v_exp_f32_e32 v67, v67
	v_sub_f32_e32 v55, v55, v39
	v_exp_f32_e32 v26, v26
	v_med3_f32 v55, v55, s96, v190
; __device__ __forceinline__ unsigned cvt_pk_bf16(float lo, float hi) { unsigned r; asm volatile("v_cvt_pk_bf16_f32 %0, %1, %2" : "=v"(r) : "v"(lo), "v"(hi)); return r; }
;     __device__ __forceinline__ void operator()(const f32x4 (&acc)[2][2][4][2], const pg8::Unit& u, int wr, int wc, int fr, int fq) const {
;     ...
;                             { const float z = acc[ai][0][m][1][j]; const float e = __expf(fminf(-z, 30.f)); const float s = __builtin_amdgcn_rcpf(1.f + e); lfF[m] = __logf(lbF[j] + (1.f - lbF[j]) * s); kkF[m] = (1.f - lbF[j]) * e * s; }
;                             { const float z = acc[ai][1][m][0][j]; const float e = __expf(fminf(-z, 30.f)); const float s = __builtin_amdgcn_rcpf(1.f + e); lfB[m] = __logf(lbB[j] + (1.f - lbB[j]) * s); kkB[m] = (1.f - lbB[j]) * e * s; }
;                             pF[m] = scan16(lfF[m]); pB[m] = scan16(lfB[m]);
;                             tF[m] = __int_as_float(__builtin_amdgcn_update_dpp(0, __float_as_int(pF[m]), 0x15F, 0xf, 0xf, true));
;                             tB[m] = __int_as_float(__builtin_amdgcn_update_dpp(0, __float_as_int(pB[m]), 0x15F, 0xf, 0xf, true));
;                         }
;                         const float rF = tF[0] + tF[1], blF = rF + tF[2] + tF[3];
;                         const float rB = tB[2] + tB[3], blB = rB + tB[0] + tB[1];
;                         float cF = 0.f, cB = 0.f;
; #pragma unroll
;                         for (int m = 0; m < 4; ++m) {
;                             const float bF = pF[m] + cF; cF += tF[m];
;                             const float bB = blB - (pB[m] + cB) + lfB[m]; cB += tB[m];
;                             const float xF = clamp80(bF - rF), xB = clamp80(bB - rB);
;                             const float q = acc[ai][0][m][0][j];
;                             vQF[m][jj] = q * __expf(xF); vKF[m][jj] = kkF[m] * __expf(-xF);
;                             vQB[m][jj] = q * __expf(xB); vKB[m][jj] = kkB[m] * __expf(-xB);
;                         }
;                         rtv[0][j] = rF; rtv[1][j] = rB; rtv[2][j] = blF - rF; rtv[3][j] = blB - rB;
;                     }
; #pragma unroll
;                     for (int m = 0; m < 4; ++m) { oQF[m][jp] = cvt_pk_bf16(vQF[m][0], vQF[m][1]); oQB[m][jp] = cvt_pk_bf16(vQB[m][0], vQB[m][1]); oKF[m][jp] = cvt_pk_bf16(vKF[m][0], vKF[m][1]); oKB[m][jp] = cvt_pk_bf16(vKB[m][0], vKB[m][1]); }
	v_mul_f32_e32 v76, 0xbfb8aa3b, v76
	v_mul_f32_e32 v23, v23, v79
	v_mul_f32_e32 v79, 0x3fb8aa3b, v55
	v_mul_f32_e32 v69, 0xbfb8aa3b, v69
	v_exp_f32_e32 v76, v76
	v_exp_f32_e32 v79, v79
	v_mul_f32_e32 v63, v98, v63
	v_mul_f32_e32 v67, v99, v67
	v_exp_f32_e32 v69, v69
	v_cvt_pk_bf16_f32 v84, v66, v63
	v_cvt_pk_bf16_f32 v80, v62, v67
	v_cvt_pk_bf16_f32 v74, v112, v83
	v_cvt_pk_bf16_f32 v70, v22, v23
	v_add_f32_e32 v22, 1.0, v26
	v_rcp_f32_e32 v22, v22
	v_mul_f32_e32 v76, v104, v76
	v_mul_f32_e32 v19, v19, v79
	v_mul_f32_e32 v69, v103, v69
	v_cvt_pk_bf16_f32 v66, v81, v69
	v_cvt_pk_bf16_f32 v62, v68, v76
	v_cvt_pk_bf16_f32 v76, v77, v85
	v_cvt_pk_bf16_f32 v72, v18, v19
	v_fma_f32 v23, v22, v122, v177
	v_max_f32_e32 v19, 0xc1f00000, v60
	v_mul_f32_e32 v19, 0xbfb8aa3b, v19
	v_exp_f32_e32 v19, v19
	v_log_f32_e32 v23, v23
	v_add_f32_e32 v27, 1.0, v19
	v_rcp_f32_e32 v27, v27
	v_mul_f32_e32 v19, v19, v123
	v_fma_f32 v30, v27, v123, v192
	v_mul_f32_e32 v58, v27, v19
	v_mul_f32_e32 v18, 0x3f317218, v23
	v_mul_f32_e32 v59, 0xbfb8aa3b, v59
	v_log_f32_e32 v30, v30
	v_mul_f32_e32 v23, v26, v122
	v_max_f32_e32 v19, 0xc1f00000, v56
	v_exp_f32_e32 v59, v59
	v_mul_f32_e32 v60, v22, v23
	v_mul_f32_e32 v19, 0xbfb8aa3b, v19
	v_exp_f32_e32 v19, v19
	v_add_f32_dpp v18, v18, v18 row_shr:1 row_mask:0xf bank_mask:0xf bound_ctrl:1
	s_nop 1
	v_add_f32_dpp v18, v18, v18 row_shr:2 row_mask:0xf bank_mask:0xf bound_ctrl:1
	v_mul_f32_e32 v59, v108, v59
	v_mul_f32_e32 v22, 0x3f317218, v30
	v_add_f32_dpp v18, v18, v18 row_shr:4 row_mask:0xf bank_mask:0xf bound_ctrl:1
	v_cvt_pk_bf16_f32 v68, v113, v59
	v_mov_b32_e32 v59, v22
	v_mul_f32_e32 v55, 0xbfb8aa3b, v55
	v_add_f32_dpp v23, v18, v18 row_shr:8 row_mask:0xf bank_mask:0xf bound_ctrl:1
	v_add_f32_e32 v18, 1.0, v19
	v_rcp_f32_e32 v26, v18
	v_exp_f32_e32 v55, v55
	v_add_f32_e32 v54, 1.0, v52
	v_rcp_f32_e32 v54, v54
	v_fma_f32 v22, v26, v122, v177
	v_mul_f32_e32 v55, v109, v55
	v_cvt_pk_bf16_f32 v64, v71, v55
	v_fma_f32 v55, v54, v123, v192
	v_log_f32_e32 v27, v22
	v_mul_f32_e32 v19, v19, v122
	v_exp_f32_e32 v44, v44
	v_max_f32_e32 v36, 0xc1f00000, v36
	v_mul_f32_e32 v36, 0xbfb8aa3b, v36
	v_mul_f32_e32 v27, 0x3f317218, v27
	v_exp_f32_e32 v36, v36
	v_log_f32_e32 v55, v55
	v_mul_f32_e32 v56, v26, v19
	v_add_f32_dpp v18, v59, v59 row_shr:1 row_mask:0xf bank_mask:0xf bound_ctrl:1
	s_nop 1
	v_add_f32_dpp v18, v18, v18 row_shr:2 row_mask:0xf bank_mask:0xf bound_ctrl:1
	v_mov_b32_dpp v22, v23 row_newbcast:15 row_mask:0xf bank_mask:0xf bound_ctrl:1
	v_mul_f32_e32 v19, 0x3f317218, v55
	v_mov_b32_e32 v67, v19
	v_max_f32_e32 v26, 0xc1f00000, v48
	v_mul_f32_e32 v26, 0xbfb8aa3b, v26
	v_mul_f32_e32 v19, v52, v123
	v_exp_f32_e32 v26, v26
	v_mul_f32_e32 v63, v54, v19
	v_add_f32_dpp v19, v27, v27 row_shr:1 row_mask:0xf bank_mask:0xf bound_ctrl:1
	v_add_f32_dpp v27, v67, v67 row_shr:1 row_mask:0xf bank_mask:0xf bound_ctrl:1
	v_add_f32_e32 v54, 1.0, v44
	v_add_f32_dpp v19, v19, v19 row_shr:2 row_mask:0xf bank_mask:0xf bound_ctrl:1
	v_add_f32_dpp v27, v27, v27 row_shr:2 row_mask:0xf bank_mask:0xf bound_ctrl:1
	v_rcp_f32_e32 v54, v54
	v_add_f32_dpp v19, v19, v19 row_shr:4 row_mask:0xf bank_mask:0xf bound_ctrl:1
	v_add_f32_dpp v27, v27, v27 row_shr:4 row_mask:0xf bank_mask:0xf bound_ctrl:1
	v_add_f32_dpp v18, v18, v18 row_shr:4 row_mask:0xf bank_mask:0xf bound_ctrl:1
	v_add_f32_dpp v69, v19, v19 row_shr:8 row_mask:0xf bank_mask:0xf bound_ctrl:1
	v_add_f32_e32 v19, 1.0, v26
	v_rcp_f32_e32 v19, v19
	v_add_f32_dpp v71, v27, v27 row_shr:8 row_mask:0xf bank_mask:0xf bound_ctrl:1
	v_fma_f32 v55, v54, v123, v192
	v_mul_f32_e32 v26, v26, v122
	v_fma_f32 v30, v19, v122, v177
	v_add_f32_dpp v31, v18, v18 row_shr:8 row_mask:0xf bank_mask:0xf bound_ctrl:1
	v_add_f32_e32 v89, 0, v31
	v_log_f32_e32 v52, v30
	v_mov_b32_dpp v18, v31 row_newbcast:15 row_mask:0xf bank_mask:0xf bound_ctrl:1
	v_max_f32_e32 v31, 0xc1f00000, v61
	v_mul_f32_e32 v31, 0xbfb8aa3b, v31
	v_exp_f32_e32 v31, v31
	v_mul_f32_e32 v27, 0x3f317218, v52
	v_add_f32_e32 v61, 1.0, v31
	v_log_f32_e32 v55, v55
	v_mul_f32_e32 v73, v19, v26
	v_rcp_f32_e32 v61, v61
	s_nop 0
	v_fma_f32 v91, v61, v201, v191
	v_mul_f32_e32 v19, 0x3f317218, v55
	v_mov_b32_e32 v75, v19
	v_max_f32_e32 v26, 0xc1f00000, v40
	v_mul_f32_e32 v19, v44, v123
	v_mul_f32_e32 v26, 0xbfb8aa3b, v26
	v_mul_f32_e32 v77, v54, v19
	v_add_f32_dpp v19, v27, v27 row_shr:1 row_mask:0xf bank_mask:0xf bound_ctrl:1
	v_exp_f32_e32 v27, v26
	v_add_f32_e32 v55, 1.0, v36
	v_add_f32_dpp v19, v19, v19 row_shr:2 row_mask:0xf bank_mask:0xf bound_ctrl:1
	v_rcp_f32_e32 v55, v55
	v_max_f32_e32 v53, 0xc1f00000, v53
	v_add_f32_dpp v19, v19, v19 row_shr:4 row_mask:0xf bank_mask:0xf bound_ctrl:1
	v_mul_f32_e32 v53, 0xbfb8aa3b, v53
	v_fmac_f32_e32 v192, v55, v123
	v_add_f32_dpp v40, v19, v19 row_shr:8 row_mask:0xf bank_mask:0xf bound_ctrl:1
	v_add_f32_e32 v19, 1.0, v27
	v_rcp_f32_e32 v19, v19
	v_mul_f32_e32 v27, v27, v122
	v_exp_f32_e32 v53, v53
	v_fmac_f32_e32 v177, v19, v122
	v_mul_f32_e32 v83, v19, v27
	v_add_f32_e32 v98, 1.0, v53
	v_log_f32_e32 v44, v177
	v_rcp_f32_e32 v98, v98
	v_max_f32_e32 v45, 0xc1f00000, v45
	v_mul_f32_e32 v45, 0xbfb8aa3b, v45
	v_fma_f32 v99, v98, v201, v191
	v_exp_f32_e32 v45, v45
	v_mul_f32_e32 v44, 0x3f317218, v44
	v_add_f32_e32 v103, 1.0, v45
	v_log_f32_e32 v81, v192
	v_rcp_f32_e32 v103, v103
	s_nop 0
	v_fma_f32 v104, v103, v201, v191
	v_max_f32_e32 v37, 0xc1f00000, v37
	v_mul_f32_e32 v19, 0x3f317218, v81
	v_mov_b32_e32 v81, v19
	v_max_f32_e32 v27, 0xc1f00000, v65
	v_mul_f32_e32 v27, 0xbfb8aa3b, v27
	v_exp_f32_e32 v27, v27
	v_mul_f32_e32 v19, v36, v123
	v_mul_f32_e32 v85, v55, v19
	v_add_f32_e32 v55, 0, v23
; __device__ __forceinline__ float scan16(float x) { x += dpp_shr<1>(x); x += dpp_shr<2>(x); x += dpp_shr<4>(x); x += dpp_shr<8>(x); return x; }
;     __device__ __forceinline__ void operator()(const f32x4 (&acc)[2][2][4][2], const pg8::Unit& u, int wr, int wc, int fr, int fq) const {
;     ...
;                             { const float z = acc[ai][0][m][1][j]; const float e = __expf(fminf(-z, 30.f)); const float s = __builtin_amdgcn_rcpf(1.f + e); lfF[m] = __logf(lbF[j] + (1.f - lbF[j]) * s); kkF[m] = (1.f - lbF[j]) * e * s; }
;                             { const float z = acc[ai][1][m][0][j]; const float e = __expf(fminf(-z, 30.f)); const float s = __builtin_amdgcn_rcpf(1.f + e); lfB[m] = __logf(lbB[j] + (1.f - lbB[j]) * s); kkB[m] = (1.f - lbB[j]) * e * s; }
;                             pF[m] = scan16(lfF[m]); pB[m] = scan16(lfB[m]);
;                             tF[m] = __int_as_float(__builtin_amdgcn_update_dpp(0, __float_as_int(pF[m]), 0x15F, 0xf, 0xf, true));
;                             tB[m] = __int_as_float(__builtin_amdgcn_update_dpp(0, __float_as_int(pB[m]), 0x15F, 0xf, 0xf, true));
	v_add_f32_dpp v19, v44, v44 row_shr:1 row_mask:0xf bank_mask:0xf bound_ctrl:1
	v_add_f32_e32 v36, 1.0, v27
	v_rcp_f32_e32 v36, v36
	v_add_f32_dpp v19, v19, v19 row_shr:2 row_mask:0xf bank_mask:0xf bound_ctrl:1
	v_mul_f32_e32 v37, 0xbfb8aa3b, v37
	v_exp_f32_e32 v37, v37
	v_add_f32_dpp v19, v19, v19 row_shr:4 row_mask:0xf bank_mask:0xf bound_ctrl:1
	v_mov_b32_dpp v47, v110 row_newbcast:15 row_mask:0xf bank_mask:0xf bound_ctrl:1
	v_mov_b32_dpp v48, v69 row_newbcast:15 row_mask:0xf bank_mask:0xf bound_ctrl:1
	v_add_f32_dpp v65, v19, v19 row_shr:8 row_mask:0xf bank_mask:0xf bound_ctrl:1
	v_add_f32_dpp v19, v81, v81 row_shr:1 row_mask:0xf bank_mask:0xf bound_ctrl:1
	v_add_f32_e32 v108, 1.0, v37
	v_rcp_f32_e32 v108, v108
	v_add_f32_dpp v19, v19, v19 row_shr:2 row_mask:0xf bank_mask:0xf bound_ctrl:1
	v_add_f32_dpp v26, v75, v75 row_shr:1 row_mask:0xf bank_mask:0xf bound_ctrl:1
	v_mov_b32_dpp v44, v65 row_newbcast:15 row_mask:0xf bank_mask:0xf bound_ctrl:1
	v_add_f32_dpp v19, v19, v19 row_shr:4 row_mask:0xf bank_mask:0xf bound_ctrl:1
	v_fmac_f32_e32 v191, v108, v201
	v_add_f32_dpp v26, v26, v26 row_shr:2 row_mask:0xf bank_mask:0xf bound_ctrl:1
	v_add_f32_dpp v87, v19, v19 row_shr:8 row_mask:0xf bank_mask:0xf bound_ctrl:1
	v_fma_f32 v19, v36, v124, v173
	v_add_f32_dpp v26, v26, v26 row_shr:4 row_mask:0xf bank_mask:0xf bound_ctrl:1
	v_mov_b32_dpp v30, v71 row_newbcast:15 row_mask:0xf bank_mask:0xf bound_ctrl:1
	v_log_f32_e32 v19, v19
	v_add_f32_dpp v79, v26, v26 row_shr:8 row_mask:0xf bank_mask:0xf bound_ctrl:1
	v_mov_b32_dpp v26, v40 row_newbcast:15 row_mask:0xf bank_mask:0xf bound_ctrl:1
	v_mov_b32_dpp v52, v87 row_newbcast:15 row_mask:0xf bank_mask:0xf bound_ctrl:1
	v_mov_b32_dpp v54, v79 row_newbcast:15 row_mask:0xf bank_mask:0xf bound_ctrl:1
	s_addk_i32 s45, 0x80
	v_mul_f32_e32 v19, 0x3f317218, v19
	v_mul_f32_e32 v23, v27, v124
	v_log_f32_e32 v91, v91
	v_mul_f32_e32 v93, v36, v23
	v_add_f32_dpp v19, v19, v19 row_shr:1 row_mask:0xf bank_mask:0xf bound_ctrl:1
	s_nop 1
	v_add_f32_dpp v19, v19, v19 row_shr:2 row_mask:0xf bank_mask:0xf bound_ctrl:1
	s_nop 0
	v_mul_f32_e32 v23, 0x3f317218, v91
	v_mov_b32_e32 v91, v23
	v_mul_f32_e32 v23, v31, v201
	v_mul_f32_e32 v61, v61, v23
	v_max_f32_e32 v23, 0xc1f00000, v57
	v_mul_f32_e32 v23, 0xbfb8aa3b, v23
	v_exp_f32_e32 v27, v23
	v_add_f32_dpp v19, v19, v19 row_shr:4 row_mask:0xf bank_mask:0xf bound_ctrl:1
	s_nop 1
	v_add_f32_dpp v96, v19, v19 row_shr:8 row_mask:0xf bank_mask:0xf bound_ctrl:1
	v_add_f32_e32 v19, 1.0, v27
	v_rcp_f32_e32 v31, v19
	v_mul_f32_e32 v27, v27, v124
	v_add_f32_dpp v19, v91, v91 row_shr:1 row_mask:0xf bank_mask:0xf bound_ctrl:1
	v_fma_f32 v23, v31, v124, v173
	s_nop 0
	v_add_f32_dpp v19, v19, v19 row_shr:2 row_mask:0xf bank_mask:0xf bound_ctrl:1
	s_nop 0
	v_log_f32_e32 v36, v23
	v_add_f32_dpp v19, v19, v19 row_shr:4 row_mask:0xf bank_mask:0xf bound_ctrl:1
	v_mov_b32_dpp v23, v96 row_newbcast:15 row_mask:0xf bank_mask:0xf bound_ctrl:1
	s_nop 0
	v_add_f32_dpp v97, v19, v19 row_shr:8 row_mask:0xf bank_mask:0xf bound_ctrl:1
	s_nop 0
	v_mul_f32_e32 v36, 0x3f317218, v36
	v_mov_b32_dpp v19, v97 row_newbcast:15 row_mask:0xf bank_mask:0xf bound_ctrl:1
	v_log_f32_e32 v99, v99
	v_mul_f32_e32 v100, v31, v27
	s_nop 1
	v_mul_f32_e32 v27, 0x3f317218, v99
	v_mov_b32_e32 v99, v27
	v_max_f32_e32 v31, 0xc1f00000, v49
	v_mul_f32_e32 v27, v53, v201
	v_mul_f32_e32 v31, 0xbfb8aa3b, v31
	v_mul_f32_e32 v98, v98, v27
	v_add_f32_dpp v27, v36, v36 row_shr:1 row_mask:0xf bank_mask:0xf bound_ctrl:1
	v_exp_f32_e32 v36, v31
	v_add_f32_dpp v31, v99, v99 row_shr:1 row_mask:0xf bank_mask:0xf bound_ctrl:1
	v_add_f32_dpp v27, v27, v27 row_shr:2 row_mask:0xf bank_mask:0xf bound_ctrl:1
	s_nop 0
	v_add_f32_dpp v31, v31, v31 row_shr:2 row_mask:0xf bank_mask:0xf bound_ctrl:1
	v_add_f32_dpp v27, v27, v27 row_shr:4 row_mask:0xf bank_mask:0xf bound_ctrl:1
	s_nop 0
	v_add_f32_dpp v31, v31, v31 row_shr:4 row_mask:0xf bank_mask:0xf bound_ctrl:1
	v_add_f32_dpp v101, v27, v27 row_shr:8 row_mask:0xf bank_mask:0xf bound_ctrl:1
	v_add_f32_e32 v27, 1.0, v36
	v_rcp_f32_e32 v27, v27
	v_mul_f32_e32 v36, v36, v124
	v_add_f32_dpp v102, v31, v31 row_shr:8 row_mask:0xf bank_mask:0xf bound_ctrl:1
	v_fma_f32 v49, v27, v124, v173
	s_nop 0
	v_mov_b32_dpp v31, v102 row_newbcast:15 row_mask:0xf bank_mask:0xf bound_ctrl:1
	s_nop 0
	v_log_f32_e32 v53, v49
	s_nop 0
	v_mov_b32_dpp v49, v101 row_newbcast:15 row_mask:0xf bank_mask:0xf bound_ctrl:1
	s_nop 1
	v_mul_f32_e32 v53, 0x3f317218, v53
	s_nop 0
	v_log_f32_e32 v104, v104
	v_mul_f32_e32 v105, v27, v36
	s_nop 1
	v_mul_f32_e32 v27, 0x3f317218, v104
	v_mov_b32_e32 v104, v27
	v_max_f32_e32 v36, 0xc1f00000, v41
	v_mul_f32_e32 v36, 0xbfb8aa3b, v36
	v_mul_f32_e32 v27, v45, v201
	v_exp_f32_e32 v36, v36
	v_mul_f32_e32 v103, v103, v27
	v_add_f32_dpp v27, v53, v53 row_shr:1 row_mask:0xf bank_mask:0xf bound_ctrl:1
	s_nop 1
	v_add_f32_dpp v27, v27, v27 row_shr:2 row_mask:0xf bank_mask:0xf bound_ctrl:1
	s_nop 1
	v_add_f32_dpp v27, v27, v27 row_shr:4 row_mask:0xf bank_mask:0xf bound_ctrl:1
	s_nop 1
	v_add_f32_dpp v106, v27, v27 row_shr:8 row_mask:0xf bank_mask:0xf bound_ctrl:1
	v_add_f32_e32 v27, 1.0, v36
	v_rcp_f32_e32 v41, v27
	v_mul_f32_e32 v36, v36, v124
	v_add_f32_dpp v27, v104, v104 row_shr:1 row_mask:0xf bank_mask:0xf bound_ctrl:1
	v_fmac_f32_e32 v173, v41, v124
	v_mul_f32_e32 v110, v41, v36
	v_add_f32_dpp v27, v27, v27 row_shr:2 row_mask:0xf bank_mask:0xf bound_ctrl:1
	v_log_f32_e32 v45, v173
	s_nop 0
	v_add_f32_dpp v27, v27, v27 row_shr:4 row_mask:0xf bank_mask:0xf bound_ctrl:1
	s_nop 1
	v_add_f32_dpp v107, v27, v27 row_shr:8 row_mask:0xf bank_mask:0xf bound_ctrl:1
; __device__ __forceinline__ unsigned cvt_pk_bf16(float lo, float hi) { unsigned r; asm volatile("v_cvt_pk_bf16_f32 %0, %1, %2" : "=v"(r) : "v"(lo), "v"(hi)); return r; }
;     __device__ __forceinline__ void operator()(const f32x4 (&acc)[2][2][4][2], const pg8::Unit& u, int wr, int wc, int fr, int fq) const {
;     ...
;                             { const float z = acc[ai][0][m][1][j]; const float e = __expf(fminf(-z, 30.f)); const float s = __builtin_amdgcn_rcpf(1.f + e); lfF[m] = __logf(lbF[j] + (1.f - lbF[j]) * s); kkF[m] = (1.f - lbF[j]) * e * s; }
;                             { const float z = acc[ai][1][m][0][j]; const float e = __expf(fminf(-z, 30.f)); const float s = __builtin_amdgcn_rcpf(1.f + e); lfB[m] = __logf(lbB[j] + (1.f - lbB[j]) * s); kkB[m] = (1.f - lbB[j]) * e * s; }
;                             pF[m] = scan16(lfF[m]); pB[m] = scan16(lfB[m]);
;                             tF[m] = __int_as_float(__builtin_amdgcn_update_dpp(0, __float_as_int(pF[m]), 0x15F, 0xf, 0xf, true));
;                             tB[m] = __int_as_float(__builtin_amdgcn_update_dpp(0, __float_as_int(pB[m]), 0x15F, 0xf, 0xf, true));
;                         }
;                         const float rF = tF[0] + tF[1], blF = rF + tF[2] + tF[3];
;                         const float rB = tB[2] + tB[3], blB = rB + tB[0] + tB[1];
;                         float cF = 0.f, cB = 0.f;
; #pragma unroll
;                         for (int m = 0; m < 4; ++m) {
;                             const float bF = pF[m] + cF; cF += tF[m];
;                             const float bB = blB - (pB[m] + cB) + lfB[m]; cB += tB[m];
;                             const float xF = clamp80(bF - rF), xB = clamp80(bB - rB);
;                             const float q = acc[ai][0][m][0][j];
;                             vQF[m][jj] = q * __expf(xF); vKF[m][jj] = kkF[m] * __expf(-xF);
;                             vQB[m][jj] = q * __expf(xB); vKB[m][jj] = kkB[m] * __expf(-xB);
;                         }
;                         rtv[0][j] = rF; rtv[1][j] = rB; rtv[2][j] = blF - rF; rtv[3][j] = blB - rB;
;                     }
; #pragma unroll
;                     for (int m = 0; m < 4; ++m) { oQF[m][jp] = cvt_pk_bf16(vQF[m][0], vQF[m][1]); oQB[m][jp] = cvt_pk_bf16(vQB[m][0], vQB[m][1]); oKF[m][jp] = cvt_pk_bf16(vKF[m][0], vKF[m][1]); oKB[m][jp] = cvt_pk_bf16(vKB[m][0], vKB[m][1]); }
	v_mov_b32_dpp v27, v106 row_newbcast:15 row_mask:0xf bank_mask:0xf bound_ctrl:1
	v_mul_f32_e32 v45, 0x3f317218, v45
	v_mov_b32_dpp v53, v107 row_newbcast:15 row_mask:0xf bank_mask:0xf bound_ctrl:1
	v_log_f32_e32 v109, v191
	s_nop 1
	v_mul_f32_e32 v36, 0x3f317218, v109
	v_mov_b32_e32 v109, v36
	v_mul_f32_e32 v36, v37, v201
	v_mul_f32_e32 v108, v108, v36
	s_nop 0
	v_add_f32_dpp v36, v45, v45 row_shr:1 row_mask:0xf bank_mask:0xf bound_ctrl:1
	s_nop 1
	v_add_f32_dpp v36, v36, v36 row_shr:2 row_mask:0xf bank_mask:0xf bound_ctrl:1
	s_nop 1
	v_add_f32_dpp v36, v36, v36 row_shr:4 row_mask:0xf bank_mask:0xf bound_ctrl:1
	s_nop 1
	v_add_f32_dpp v111, v36, v36 row_shr:8 row_mask:0xf bank_mask:0xf bound_ctrl:1
	v_add_f32_dpp v36, v109, v109 row_shr:1 row_mask:0xf bank_mask:0xf bound_ctrl:1
	s_nop 1
	v_add_f32_dpp v36, v36, v36 row_shr:2 row_mask:0xf bank_mask:0xf bound_ctrl:1
	s_nop 1
	v_add_f32_dpp v36, v36, v36 row_shr:4 row_mask:0xf bank_mask:0xf bound_ctrl:1
	s_nop 1
	v_add_f32_dpp v112, v36, v36 row_shr:8 row_mask:0xf bank_mask:0xf bound_ctrl:1
	v_pk_add_f32 v[36:37], v[22:23], v[48:49]
	v_add_f32_e32 v22, 0, v22
	v_sub_f32_e32 v41, v55, v36
	v_med3_f32 v41, v41, s96, v190
	v_mul_f32_e32 v45, 0x3fb8aa3b, v41
	v_exp_f32_e32 v57, v45
	v_mul_f32_e32 v41, 0xbfb8aa3b, v41
	v_exp_f32_e32 v41, v41
	v_mov_b32_dpp v55, v112 row_newbcast:15 row_mask:0xf bank_mask:0xf bound_ctrl:1
	v_mul_f32_e32 v113, v32, v57
	v_add_f32_e32 v57, v22, v69
	v_sub_f32_e32 v57, v57, v36
	v_med3_f32 v57, v57, s96, v190
	v_mul_f32_e32 v69, 0x3fb8aa3b, v57
	v_mul_f32_e32 v57, 0xbfb8aa3b, v57
	v_add_f32_e32 v22, v22, v48
	v_exp_f32_e32 v69, v69
	v_exp_f32_e32 v57, v57
	v_add_f32_e32 v40, v22, v40
	v_add_f32_e32 v22, v22, v26
	v_sub_f32_e32 v40, v40, v36
	v_add_f32_e32 v22, v22, v65
	v_med3_f32 v40, v40, s96, v190
	v_sub_f32_e32 v22, v22, v36
	v_mul_f32_e32 v60, v60, v41
	v_mul_f32_e32 v41, 0x3fb8aa3b, v40
	v_mul_f32_e32 v40, 0xbfb8aa3b, v40
	v_med3_f32 v22, v22, s96, v190
	v_mul_f32_e32 v48, v28, v69
	v_mul_f32_e32 v69, v56, v57
	v_exp_f32_e32 v41, v41
	v_exp_f32_e32 v40, v40
	v_mul_f32_e32 v56, 0x3fb8aa3b, v22
	v_exp_f32_e32 v56, v56
	v_mul_f32_e32 v65, v24, v41
	v_mul_f32_e32 v73, v73, v40
	v_pk_add_f32 v[40:41], v[52:53], v[54:55]
	v_mul_f32_e32 v114, v20, v56
	v_pk_add_f32 v[56:57], v[40:41], v[18:19]
	v_add_f32_e32 v52, 0, v18
	v_pk_add_f32 v[56:57], v[56:57], v[30:31]
	v_add_f32_e32 v55, v52, v71
	v_sub_f32_e32 v18, v56, v89
	v_add_f32_e32 v18, v59, v18
	v_add_f32_e32 v52, v52, v30
	v_sub_f32_e32 v18, v18, v40
	v_add_f32_e32 v71, v52, v79
	v_med3_f32 v18, v18, s96, v190
	v_sub_f32_e32 v55, v56, v55
	v_add_f32_e32 v52, v52, v54
	v_mul_f32_e32 v30, 0x3fb8aa3b, v18
	v_mul_f32_e32 v18, 0xbfb8aa3b, v18
	v_add_f32_e32 v55, v67, v55
	v_add_f32_e32 v52, v52, v87
	v_exp_f32_e32 v18, v18
	v_sub_f32_e32 v55, v55, v40
	v_sub_f32_e32 v52, v56, v52
	v_med3_f32 v55, v55, s96, v190
	v_add_f32_e32 v52, v81, v52
	v_mul_f32_e32 v59, 0x3fb8aa3b, v55
	v_mul_f32_e32 v55, 0xbfb8aa3b, v55
	v_sub_f32_e32 v52, v52, v40
	v_exp_f32_e32 v30, v30
	v_exp_f32_e32 v55, v55
	v_med3_f32 v52, v52, s96, v190
	v_mul_f32_e32 v18, v58, v18
	v_mul_f32_e32 v58, 0x3fb8aa3b, v52
	v_exp_f32_e32 v58, v58
	v_mul_f32_e32 v30, v32, v30
	v_mul_f32_e32 v32, v63, v55
	v_sub_f32_e32 v55, v56, v71
	v_add_f32_e32 v55, v75, v55
	v_sub_f32_e32 v54, v55, v40
	v_mul_f32_e32 v20, v20, v58
	v_add_f32_e32 v58, 0, v97
	v_med3_f32 v54, v54, s96, v190
	v_sub_f32_e32 v58, v57, v58
	v_mul_f32_e32 v55, 0x3fb8aa3b, v54
	v_add_f32_e32 v58, v91, v58
	v_exp_f32_e32 v55, v55
	v_sub_f32_e32 v58, v58, v41
	v_med3_f32 v58, v58, s96, v190
	v_mul_f32_e32 v63, 0x3fb8aa3b, v58
	v_mul_f32_e32 v58, 0xbfb8aa3b, v58
	v_exp_f32_e32 v59, v59
	v_exp_f32_e32 v58, v58
	v_mul_f32_e32 v24, v24, v55
	v_add_f32_e32 v55, 0, v96
	v_sub_f32_e32 v55, v55, v37
	v_add_f32_e32 v23, 0, v23
	v_add_f32_e32 v19, 0, v19
	v_med3_f32 v55, v55, s96, v190
	v_mul_f32_e32 v28, v28, v59
	v_mul_f32_e32 v59, 0x3fb8aa3b, v55
	v_mul_f32_e32 v58, v61, v58
	v_add_f32_e32 v61, v23, v101
	v_add_f32_e32 v23, v23, v49
	v_add_f32_e32 v49, v19, v102
	v_exp_f32_e32 v59, v59
	v_exp_f32_e32 v63, v63
	v_sub_f32_e32 v49, v57, v49
	v_add_f32_e32 v49, v99, v49
	v_add_f32_e32 v19, v19, v31
	v_sub_f32_e32 v31, v61, v37
	v_sub_f32_e32 v49, v49, v41
	v_med3_f32 v31, v31, s96, v190
	v_med3_f32 v49, v49, s96, v190
	v_mul_f32_e32 v59, v33, v59
	v_mul_f32_e32 v33, v33, v63
	v_mul_f32_e32 v61, 0x3fb8aa3b, v31
	v_mul_f32_e32 v63, 0x3fb8aa3b, v49
	v_exp_f32_e32 v61, v61
	v_exp_f32_e32 v63, v63
	v_add_f32_e32 v67, v19, v107
	v_sub_f32_e32 v67, v57, v67
	v_mul_f32_e32 v61, v29, v61
	v_mul_f32_e32 v29, v29, v63
	v_add_f32_e32 v63, v23, v106
	v_add_f32_e32 v67, v104, v67
	v_add_f32_e32 v19, v19, v53
	v_sub_f32_e32 v53, v63, v37
	v_sub_f32_e32 v63, v67, v41
	v_med3_f32 v53, v53, s96, v190
	v_med3_f32 v63, v63, s96, v190
	v_mul_f32_e32 v67, 0x3fb8aa3b, v53
	v_mul_f32_e32 v71, 0x3fb8aa3b, v63
	v_add_f32_e32 v23, v23, v27
	v_exp_f32_e32 v67, v67
	v_exp_f32_e32 v71, v71
	v_add_f32_e32 v19, v19, v112
	v_add_f32_e32 v23, v23, v111
	v_sub_f32_e32 v19, v57, v19
	v_add_f32_e32 v19, v109, v19
	v_sub_f32_e32 v23, v23, v37
	v_med3_f32 v23, v23, s96, v190
	v_sub_f32_e32 v19, v19, v41
	v_mul_f32_e32 v54, 0xbfb8aa3b, v54
	v_mul_f32_e32 v63, 0xbfb8aa3b, v63
	v_mul_f32_e32 v67, v25, v67
	v_mul_f32_e32 v25, v25, v71
	v_med3_f32 v19, v19, s96, v190
	v_mul_f32_e32 v71, 0x3fb8aa3b, v23
	v_mul_f32_e32 v22, 0xbfb8aa3b, v22
	v_exp_f32_e32 v54, v54
	v_mul_f32_e32 v52, 0xbfb8aa3b, v52
	v_mul_f32_e32 v55, 0xbfb8aa3b, v55
	v_mul_f32_e32 v31, 0xbfb8aa3b, v31
	v_mul_f32_e32 v49, 0xbfb8aa3b, v49
	v_mul_f32_e32 v53, 0xbfb8aa3b, v53
	v_exp_f32_e32 v63, v63
	v_exp_f32_e32 v71, v71
	v_mul_f32_e32 v23, 0xbfb8aa3b, v23
	v_mul_f32_e32 v75, 0x3fb8aa3b, v19
	v_mul_f32_e32 v19, 0xbfb8aa3b, v19
	v_exp_f32_e32 v22, v22
	v_exp_f32_e32 v52, v52
	v_exp_f32_e32 v55, v55
	v_exp_f32_e32 v31, v31
	v_exp_f32_e32 v49, v49
	v_exp_f32_e32 v53, v53
	v_exp_f32_e32 v23, v23
	v_exp_f32_e32 v75, v75
	v_exp_f32_e32 v19, v19
	v_mov_b32_dpp v45, v111 row_newbcast:15 row_mask:0xf bank_mask:0xf bound_ctrl:1
	v_mul_f32_e32 v54, v77, v54
	v_mul_f32_e32 v63, v103, v63
	v_mul_f32_e32 v77, v21, v71
	v_mul_f32_e32 v22, v83, v22
	v_mul_f32_e32 v52, v85, v52
	v_mul_f32_e32 v55, v93, v55
	v_mul_f32_e32 v31, v100, v31
	v_mul_f32_e32 v49, v98, v49
	v_mul_f32_e32 v53, v105, v53
	v_mul_f32_e32 v23, v110, v23
	v_mul_f32_e32 v21, v21, v75
	v_mul_f32_e32 v19, v108, v19
	v_cvt_pk_bf16_f32 v91, v113, v59
	v_cvt_pk_bf16_f32 v87, v30, v33
	v_cvt_pk_bf16_f32 v83, v60, v55
	v_cvt_pk_bf16_f32 v79, v18, v58
	v_cvt_pk_bf16_f32 v93, v48, v61
	v_cvt_pk_bf16_f32 v89, v28, v29
	v_cvt_pk_bf16_f32 v85, v69, v31
	v_cvt_pk_bf16_f32 v81, v32, v49
	v_cvt_pk_bf16_f32 v75, v65, v67
	v_cvt_pk_bf16_f32 v71, v24, v25
	v_cvt_pk_bf16_f32 v67, v73, v53
	v_cvt_pk_bf16_f32 v63, v54, v63
	v_cvt_pk_bf16_f32 v77, v114, v77
	v_cvt_pk_bf16_f32 v73, v20, v21
	v_cvt_pk_bf16_f32 v69, v22, v23
	v_cvt_pk_bf16_f32 v65, v52, v19
	s_and_saveexec_b64 s[10:11], s[6:7]
	s_cbranch_execz .LBB0_197
; __device__ __forceinline__ unsigned cvt_pk_bf16(float lo, float hi) { unsigned r; asm volatile("v_cvt_pk_bf16_f32 %0, %1, %2" : "=v"(r) : "v"(lo), "v"(hi)); return r; }
; #define WIDE_ST(P, x0a, x1a, x0b, x1b) do { const u32x2 s0 = __builtin_amdgcn_permlane16_swap((x0a), (x0b), false, false), s1 = __builtin_amdgcn_permlane16_swap((x1a), (x1b), false, false); \
;                         *(u32x4*)((P) + off) = (u32x4){s0[0], s1[0], s0[1], s1[1]}; } while (0)
;     __device__ __forceinline__ void operator()(const f32x4 (&acc)[2][2][4][2], const pg8::Unit& u, int wr, int wc, int fr, int fq) const {
;     ...
;                 if (fr == 0) {
; #pragma unroll
;                     for (int t = 0; t < 4; ++t) *(f32x4*)(RT + (size_t)t * NCHUNK * 512 + (size_t)cid * 512 + ch0) = rtv[t];
;                 }
; #pragma unroll
;                 for (int mp = 0; mp < 2; ++mp) {
;                     const int a = 2 * mp, bb = 2 * mp + 1, odd = fq & 1;
;                     const size_t off = (size_t)(rowc + 16 * (odd ? bb : a) + fr) * 512 + (ch0 - 4 * odd);
;                     const f32x4 va = acc[ai][1][a][1], vb = acc[ai][1][bb][1];
;                     const unsigned oVa0 = cvt_pk_bf16(va[0], va[1]), oVa1 = cvt_pk_bf16(va[2], va[3]), oVb0 = cvt_pk_bf16(vb[0], vb[1]), oVb1 = cvt_pk_bf16(vb[2], vb[3]);
;                     asm volatile("s_nop 1" ::: "memory");
;     ...
;                     WIDE_ST(QF, oQF[a][0], oQF[a][1], oQF[bb][0], oQF[bb][1]); WIDE_ST(QB, oQB[a][0], oQB[a][1], oQB[bb][0], oQB[bb][1]);
;                     WIDE_ST(KF, oKF[a][0], oKF[a][1], oKF[bb][0], oKF[bb][1]); WIDE_ST(KB, oKB[a][0], oKB[a][1], oKB[bb][0], oKB[bb][1]);
;                     WIDE_ST(V, oVa0, oVa1, oVb0, oVb1);
	s_ashr_i32 s12, s45, 6
	s_ashr_i32 s13, s12, 31
	s_lshl_b64 s[12:13], s[12:13], 11
	v_lshl_add_u64 v[22:23], v[174:175], 0, s[12:13]
	v_add_co_u32_e32 v18, vcc, 0x110000, v22
	v_pk_add_f32 v[20:21], v[34:35], v[42:43]
	s_nop 0
	v_addc_co_u32_e32 v19, vcc, 0, v23, vcc
	global_store_dwordx4 v[18:19], v[38:41], off
	v_pk_add_f32 v[18:19], v[36:37], v[26:27]
	v_pk_add_f32 v[24:25], v[20:21], v[46:47]
	v_pk_add_f32 v[18:19], v[18:19], v[44:45]
	global_store_dwordx4 v[22:23], v[34:37], off
	v_sub_f32_e32 v20, v18, v36
	v_sub_f32_e32 v18, v24, v34
	v_add_co_u32_e32 v24, vcc, 0x220000, v22
	v_sub_f32_e32 v21, v19, v37
	v_sub_f32_e32 v19, v25, v35
	v_addc_co_u32_e32 v25, vcc, 0, v23, vcc
	v_add_co_u32_e32 v22, vcc, 0x330000, v22
	global_store_dwordx4 v[24:25], v[18:21], off
	s_nop 0
	v_addc_co_u32_e32 v23, vcc, 0, v23, vcc
	v_pk_add_f32 v[18:19], v[50:51], v[38:39] neg_lo:[0,1] neg_hi:[0,1]
	v_pk_add_f32 v[20:21], v[56:57], v[40:41] neg_lo:[0,1] neg_hi:[0,1]
	global_store_dwordx4 v[22:23], v[18:21], off
.LBB0_197:
	s_or_b64 exec, exec, s[10:11]
	s_nop 0
	v_or_b32_e32 v20, s45, v1
	v_or_b32_e32 v18, v20, v181
	v_ashrrev_i32_e32 v19, 31, v18
	v_lshlrev_b64 v[18:19], 7, v[18:19]
	v_lshl_add_u64 v[18:19], v[18:19], 0, v[94:95]
	v_cvt_pk_bf16_f32 v14, v14, v15
	v_cvt_pk_bf16_f32 v15, v16, v17
	v_cvt_pk_bf16_f32 v16, v10, v11
	v_lshlrev_b64 v[10:11], 1, v[18:19]
	v_cvt_pk_bf16_f32 v17, v12, v13
	v_permlane16_swap_b32_e32 v90, v92
	v_permlane16_swap_b32_e32 v91, v93
	v_lshl_add_u64 v[12:13], s[24:25], 0, v[10:11]
	s_nop 1
	global_store_dwordx4 v[12:13], v[90:93], off
	v_permlane16_swap_b32_e32 v86, v88
	v_permlane16_swap_b32_e32 v87, v89
	v_lshl_add_u64 v[12:13], s[30:31], 0, v[10:11]
	global_store_dwordx4 v[12:13], v[86:89], off
	v_permlane16_swap_b32_e32 v82, v84
	v_permlane16_swap_b32_e32 v83, v85
	v_lshl_add_u64 v[12:13], s[26:27], 0, v[10:11]
	global_store_dwordx4 v[12:13], v[82:85], off
	v_lshl_add_u64 v[12:13], s[34:35], 0, v[10:11]
	v_permlane16_swap_b32_e32 v14, v16
	v_permlane16_swap_b32_e32 v15, v17
	v_lshl_add_u64 v[10:11], s[28:29], 0, v[10:11]
	global_store_dwordx4 v[10:11], v[14:17], off
	v_or_b32_e32 v10, v20, v179
	v_ashrrev_i32_e32 v11, 31, v10
	v_lshlrev_b64 v[10:11], 7, v[10:11]
	v_permlane16_swap_b32_e32 v78, v80
	v_permlane16_swap_b32_e32 v79, v81
	v_lshl_add_u64 v[10:11], v[10:11], 0, v[94:95]
	global_store_dwordx4 v[12:13], v[78:81], off
	v_cvt_pk_bf16_f32 v6, v6, v7
	v_cvt_pk_bf16_f32 v7, v8, v9
	v_cvt_pk_bf16_f32 v8, v2, v3
	v_lshlrev_b64 v[2:3], 1, v[10:11]
	v_cvt_pk_bf16_f32 v9, v4, v5
	v_permlane16_swap_b32_e32 v74, v76
	v_permlane16_swap_b32_e32 v75, v77
	v_lshl_add_u64 v[4:5], s[24:25], 0, v[2:3]
	s_nop 1
	global_store_dwordx4 v[4:5], v[74:77], off
	v_permlane16_swap_b32_e32 v70, v72
	v_permlane16_swap_b32_e32 v71, v73
	v_lshl_add_u64 v[4:5], s[30:31], 0, v[2:3]
	global_store_dwordx4 v[4:5], v[70:73], off
	v_permlane16_swap_b32_e32 v66, v68
	v_permlane16_swap_b32_e32 v67, v69
	v_lshl_add_u64 v[4:5], s[26:27], 0, v[2:3]
	global_store_dwordx4 v[4:5], v[66:69], off
	v_permlane16_swap_b32_e32 v62, v64
	v_permlane16_swap_b32_e32 v63, v65
	v_lshl_add_u64 v[4:5], s[34:35], 0, v[2:3]
	v_permlane16_swap_b32_e32 v6, v8
	v_permlane16_swap_b32_e32 v7, v9
	v_lshl_add_u64 v[2:3], s[28:29], 0, v[2:3]
	global_store_dwordx4 v[4:5], v[62:65], off
	global_store_dwordx4 v[2:3], v[6:9], off
	s_setprio 0
	s_and_b64 vcc, exec, s[8:9]
	s_cbranch_vccnz .LBB0_169

; #define SCAN_BAR() asm volatile("s_waitcnt lgkmcnt(0)\n\ts_barrier" ::: "memory")
; __device__ void scan_phase(LAS unsigned char* lds, const Params& p) {
;     ...
;     for (int item = blockIdx.x; item < 256; item += gridDim.x) {
;         const int seq = (item & 7) + 8 * (item >> 5), es = (item >> 3) & 3;
;         const int dir = seq & 1, h = (seq >> 1) & 3, b = seq >> 3;
;         const char* Qx = (const char*)((const bf16_t*)(p.ws + (dir ? WS_QB : WS_QF)) + h * 128);
;         const char* Kx = (const char*)((const bf16_t*)(p.ws + (dir ? WS_KB : WS_KF)) + h * 128);
;         const char* Vx = (const char*)((const bf16_t*)(p.ws + WS_V) + h * 128 + es * 32);
;         const char* Rx = (const char*)(RT + (size_t)dir * NCHUNK * 512 + h * 128);
;         const char* Tx = (const char*)(RT + (size_t)(2 + dir) * NCHUNK * 512 + h * 128);
;         const unsigned qoff0 = (unsigned)((dir ? 63 - (tid >> 4) : (tid >> 4)) * 1024 + (tid & 15) * 16), qstep = dir ? (unsigned)-32768 : 32768u;
;         const unsigned voff = (unsigned)((dir ? 63 - (tid >> 3) : (tid >> 3)) * 1024 + (tid & 7) * 8), roff = (unsigned)(tid & 127) * 4u;
;         f32x4 S[2] = {(f32x4){0.f, 0.f, 0.f, 0.f}, (f32x4){0.f, 0.f, 0.f, 0.f}};
;         float tailp = 0.f;
;         u32x4 k4A[2], k4B[2], k4C[2], k4D[2]; u32x4 q4A[2], q4B[2], q4C[2], q4D[2]; u32x2 v4A, v4B, v4C, v4D; float rvA, tlA, rvB, tlB, rvC, tlC, rvD, tlD;
;     ...
;         SCAN_LOAD(0, k4A, q4A, v4A, rvA, tlA); SCAN_LOAD(1, k4B, q4B, v4B, rvB, tlB); SCAN_LOAD(2, k4C, q4C, v4C, rvC, tlC); SCAN_LOAD(3, k4D, q4D, v4D, rvD, tlD);
;         SCAN_STAGE(0, k4A, q4A, v4A, rvA, tlA); SCAN_LOAD(4, k4A, q4A, v4A, rvA, tlA);
;         SCAN_BAR();
.Lsc5_item:
	s_and_b32 s10, s9, 1
	s_lshr_b32 s3, s9, 1
	s_and_b32 s3, s3, 3
	s_lshr_b32 s4, s9, 5
	s_lshr_b32 s5, s9, 3
	s_and_b32 s5, s5, 3
	s_cmp_eq_u32 s10, 0
	s_cselect_b32 s15, 1, -1
	s_cselect_b32 s64, 0, 3
	s_cselect_b32 s65, -4, 0x43
	s_lshl_b32 s16, s4, 2
	s_add_u32 s16, s16, 0x200
	s_lshl_b32 s17, s4, 6
	s_add_u32 s16, s16, s64
	s_add_i32 s17, s17, s65
	s_lshl_b32 s3, s3, 8
	s_lshl_b32 s5, s5, 6
	s_mul_i32 s4, s3, 34816
	s_cmp_eq_u32 s10, 0
	s_mov_b32 s65, 0x5100000
	s_cselect_b32 s64, s65, 0x7300000
	s_add_u32 s64, s64, s4
	s_add_u32 s18, s70, s64
	s_addc_u32 s19, s71, 0
	s_cmp_eq_u32 s10, 0
	s_mov_b32 s65, 0x9500000
	s_cselect_b32 s64, s65, 0xb700000
	s_add_u32 s64, s64, s4
	s_add_u32 s20, s70, s64
	s_addc_u32 s21, s71, 0
	s_add_u32 s64, s3, s5
	s_add_u32 s65, s4, s5
	s_add_u32 s65, s65, 0xd900000
	s_add_u32 s22, s70, s65
	s_addc_u32 s23, s71, 0
	s_lshl_b32 s65, s10, 25
	s_add_u32 s64, s64, s65
	s_add_u32 s28, s68, s64
	s_addc_u32 s29, s69, 0
	s_mul_i32 s64, s10, 0x110000
	s_lshl_b32 s65, s3, 1
	s_add_u32 s64, s64, s65
	s_add_u32 s64, s64, 0x15b00000
	s_add_u32 s24, s70, s64
	s_addc_u32 s25, s71, 0
	s_add_u32 s26, s24, 0x220000
	s_addc_u32 s27, s25, 0
	s_lshl_b32 s64, s9, 16
	s_add_u32 s64, s64, 0xd00000
	s_add_u32 s30, s70, s64
	s_addc_u32 s31, s71, 0
	s_mul_i32 s5, s10, 63
	s_lshl_b32 s3, s7, 4
	v_add_u32_e32 v1, s3, v58
	v_xor_b32_e32 v1, s5, v1
	v_lshlrev_b32_e32 v1, 10, v1
	s_lshl_b32 s3, s8, 5
	v_lshl_add_u32 v57, v59, 3, v1
	v_add_u32_e32 v57, s3, v57
	v_lshrrev_b32_e32 v1, 4, v0
	v_xor_b32_e32 v93, s5, v1
	v_lshlrev_b32_e32 v93, 8, v93
	v_lshl_add_u32 v53, v58, 4, v93
	v_add_u32_e32 v1, 32, v1
	v_xor_b32_e32 v93, s5, v1
	v_lshlrev_b32_e32 v93, 8, v93
	v_lshl_add_u32 v54, v58, 4, v93
	v_lshrrev_b32_e32 v1, 3, v0
	v_xor_b32_e32 v1, s5, v1
	v_lshlrev_b32_e32 v1, 8, v1
	v_and_b32_e32 v93, 7, v0
	v_lshl_add_u32 v55, v93, 3, v1
	v_mov_b32_e32 v42, 0
	v_mov_b32_e32 v43, 0
	v_mov_b32_e32 v44, 0
	v_mov_b32_e32 v45, 0
	v_mov_b32_e32 v46, 0
	v_mov_b32_e32 v47, 0
	v_mov_b32_e32 v48, 0
	v_mov_b32_e32 v49, 0
	v_mov_b32_e32 v52, 0
	v_mov_b32_e32 v160, 0
	v_mov_b32_e32 v161, 0
	v_mov_b32_e32 v162, 0
	v_mov_b32_e32 v163, 0
	v_mov_b32_e32 v176, 0
	v_mov_b32_e32 v177, 0
	s_mov_b32 s3, 0
	s_cmp_lt_u32 s3, 4
	s_cselect_b32 s4, s16, s17
	s_mul_i32 s5, s3, s15
	s_add_i32 s4, s4, s5
	s_lshl_b32 s5, s4, 14
	s_lshl_b32 s4, s4, 11
	s_add_u32 s40, s18, s5
	s_addc_u32 s41, s19, 0
	s_add_u32 s42, s20, s5
	s_addc_u32 s43, s21, 0
	s_add_u32 s44, s22, s5
	s_addc_u32 s45, s23, 0
	s_add_u32 s46, s24, s4
	s_addc_u32 s47, s25, 0
	s_add_u32 s50, s26, s4
	s_addc_u32 s51, s27, 0
	global_load_dwordx4 v[2:5], v53, s[40:41]
	global_load_dwordx4 v[6:9], v54, s[40:41]
	global_load_dwordx4 v[10:13], v53, s[42:43]
	global_load_dwordx4 v[14:17], v54, s[42:43]
	global_load_dwordx2 v[18:19], v55, s[44:45]
	global_load_dword v20, v56, s[46:47]
	global_load_dword v21, v56, s[50:51]
	s_mov_b32 s3, 1
	s_cmp_lt_u32 s3, 4
	s_cselect_b32 s4, s16, s17
	s_mul_i32 s5, s3, s15
	s_add_i32 s4, s4, s5
	s_lshl_b32 s5, s4, 14
	s_lshl_b32 s4, s4, 11
	s_add_u32 s40, s18, s5
	s_addc_u32 s41, s19, 0
	s_add_u32 s42, s20, s5
	s_addc_u32 s43, s21, 0
	s_add_u32 s44, s22, s5
	s_addc_u32 s45, s23, 0
	s_add_u32 s46, s24, s4
	s_addc_u32 s47, s25, 0
	s_add_u32 s50, s26, s4
	s_addc_u32 s51, s27, 0
	global_load_dwordx4 v[22:25], v53, s[40:41]
	global_load_dwordx4 v[26:29], v54, s[40:41]
	global_load_dwordx4 v[30:33], v53, s[42:43]
	global_load_dwordx4 v[34:37], v54, s[42:43]
	global_load_dwordx2 v[38:39], v55, s[44:45]
	global_load_dword v40, v56, s[46:47]
	global_load_dword v41, v56, s[50:51]
	s_waitcnt vmcnt(0)
	ds_write_b128 v60, v[2:5] offset:0
	ds_write_b128 v60, v[6:9] offset:8704
	ds_write_b128 v60, v[10:13] offset:17408
	ds_write_b128 v60, v[14:17] offset:26112
	ds_write_b64 v63, v[18:19] offset:34816
	v_add_f32_e32 v92, v20, v52
	v_mul_f32_e32 v92, 0x3fb8aa3b, v92
	v_exp_f32_e32 v92, v92
	v_mov_b32_e32 v52, v21
	ds_write_b32 v78, v92 offset:0
	ds_write_b128 v61, v[22:25] offset:0
	ds_write_b128 v61, v[26:29] offset:8704
	ds_write_b128 v61, v[30:33] offset:17408
	ds_write_b128 v61, v[34:37] offset:26112
	ds_write_b64 v64, v[38:39] offset:34816
	v_add_f32_e32 v92, v40, v52
	v_mul_f32_e32 v92, 0x3fb8aa3b, v92
	v_exp_f32_e32 v92, v92
	v_mov_b32_e32 v52, v41
	ds_write_b32 v78, v92 offset:512
	s_mov_b32 s3, 2
	s_cmp_lt_u32 s3, 4
	s_cselect_b32 s4, s16, s17
	s_mul_i32 s5, s3, s15
	s_add_i32 s4, s4, s5
	s_lshl_b32 s5, s4, 14
	s_lshl_b32 s4, s4, 11
	s_add_u32 s40, s18, s5
	s_addc_u32 s41, s19, 0
	s_add_u32 s42, s20, s5
	s_addc_u32 s43, s21, 0
	s_add_u32 s44, s22, s5
	s_addc_u32 s45, s23, 0
	s_add_u32 s46, s24, s4
	s_addc_u32 s47, s25, 0
	s_add_u32 s50, s26, s4
	s_addc_u32 s51, s27, 0
	global_load_dwordx4 v[180:183], v53, s[40:41]
	global_load_dwordx4 v[184:187], v54, s[40:41]
	global_load_dwordx4 v[188:191], v53, s[42:43]
	global_load_dwordx4 v[192:195], v54, s[42:43]
	global_load_dwordx2 v[196:197], v55, s[44:45]
	global_load_dword v198, v56, s[46:47]
	global_load_dword v199, v56, s[50:51]
	global_store_dwordx2 v57, v[176:177], s[30:31]
	s_mov_b32 s3, 3
	s_cmp_lt_u32 s3, 4
	s_cselect_b32 s4, s16, s17
	s_mul_i32 s5, s3, s15
	s_add_i32 s4, s4, s5
	s_lshl_b32 s5, s4, 14
	s_lshl_b32 s4, s4, 11
	s_add_u32 s40, s18, s5
	s_addc_u32 s41, s19, 0
	s_add_u32 s42, s20, s5
	s_addc_u32 s43, s21, 0
	s_add_u32 s44, s22, s5
	s_addc_u32 s45, s23, 0
	s_add_u32 s46, s24, s4
	s_addc_u32 s47, s25, 0
	s_add_u32 s50, s26, s4
	s_addc_u32 s51, s27, 0
	global_load_dwordx4 v[2:5], v53, s[40:41]
	global_load_dwordx4 v[6:9], v54, s[40:41]
	global_load_dwordx4 v[10:13], v53, s[42:43]
	global_load_dwordx4 v[14:17], v54, s[42:43]
	global_load_dwordx2 v[18:19], v55, s[44:45]
	global_load_dword v20, v56, s[46:47]
	global_load_dword v21, v56, s[50:51]
	global_store_dwordx2 v57, v[176:177], s[30:31]
	s_waitcnt lgkmcnt(0)
	s_barrier
	ds_read_b32 v50, v79 offset:0
	ds_read_b32 v51, v79 offset:64
	ds_read_b128 v[96:99], v66 offset:0
	ds_read_b128 v[100:103], v66 offset:64
	ds_read_b128 v[104:107], v66 offset:128
	ds_read_b128 v[108:111], v66 offset:192
	s_cmp_eq_u32 s13, 0
	s_cbranch_scc1 .Lsc5_nox_p
	ds_read_b128 v[216:219], v69 offset:17408
	ds_read_b128 v[220:223], v69 offset:17472
	ds_read_b128 v[224:227], v69 offset:17536
	ds_read_b128 v[228:231], v69 offset:17600

; #define SCAN_BAR() asm volatile("s_waitcnt lgkmcnt(0)\n\ts_barrier" ::: "memory")
; __device__ void scan_phase(LAS unsigned char* lds, const Params& p) {
;     ...
;         for (int n0 = 0; n0 < 68; n0 += 4) {
;             SCAN_STAGE(1, k4B, q4B, v4B, rvB, tlB); SCAN_LOAD(min(n0 + 5, 67), k4B, q4B, v4B, rvB, tlB); SCAN_MAT(0, n0); SCAN_BAR();
.Lsc5_loop:
	ds_read_b32 v50, v79 offset:512
	ds_read_b32 v51, v79 offset:576
	ds_read_b64_tr_b16 v[128:129], v72 offset:34816
	ds_read_b64_tr_b16 v[130:131], v72 offset:35968
	ds_read_b64_tr_b16 v[132:133], v72 offset:37120
	ds_read_b64_tr_b16 v[134:135], v72 offset:38272
	ds_read_b64_tr_b16 v[136:137], v75 offset:17408
	ds_read_b64_tr_b16 v[138:139], v75 offset:21760
	ds_read_b64_tr_b16 v[140:141], v75 offset:17440
	ds_read_b64_tr_b16 v[142:143], v75 offset:21792
	ds_read_b64_tr_b16 v[144:145], v75 offset:26112
	ds_read_b64_tr_b16 v[146:147], v75 offset:30464
	ds_read_b64_tr_b16 v[148:149], v75 offset:26144
	ds_read_b64_tr_b16 v[150:151], v75 offset:30496
	s_add_u32 s3, s34, 4
	s_min_u32 s3, s3, 67
	s_cmp_lt_u32 s3, 4
	s_cselect_b32 s4, s16, s17
	s_mul_i32 s5, s3, s15
	s_add_i32 s4, s4, s5
	s_lshl_b32 s5, s4, 14
	s_lshl_b32 s4, s4, 11
	s_add_u32 s40, s18, s5
	s_addc_u32 s41, s19, 0
	s_add_u32 s42, s20, s5
	s_addc_u32 s43, s21, 0
	s_add_u32 s44, s22, s5
	s_addc_u32 s45, s23, 0
	s_add_u32 s46, s24, s4
	s_addc_u32 s47, s25, 0
	s_add_u32 s50, s26, s4
	s_addc_u32 s51, s27, 0
	global_load_dwordx4 v[22:25], v53, s[40:41]
	global_load_dwordx4 v[26:29], v54, s[40:41]
	global_load_dwordx4 v[30:33], v53, s[42:43]
	global_load_dwordx4 v[34:37], v54, s[42:43]
	global_load_dwordx2 v[38:39], v55, s[44:45]
	global_load_dword v40, v56, s[46:47]
	global_load_dword v41, v56, s[50:51]
	s_waitcnt lgkmcnt(6)
	v_mfma_f32_16x16x32_bf16 v[42:45], v[128:131], v[136:139], v[42:45]
	ds_read_b64_tr_b16 v[112:113], v82 offset:0
	ds_read_b64_tr_b16 v[114:115], v82 offset:288
	ds_read_b64_tr_b16 v[116:117], v82 offset:2304
	ds_read_b64_tr_b16 v[118:119], v82 offset:2592
	s_waitcnt lgkmcnt(8)
	v_mfma_f32_16x16x32_bf16 v[46:49], v[128:131], v[140:143], v[46:49]
	ds_read_b64_tr_b16 v[120:121], v82 offset:4608
	ds_read_b64_tr_b16 v[122:123], v82 offset:4896
	ds_read_b64_tr_b16 v[124:125], v82 offset:6912
	ds_read_b64_tr_b16 v[126:127], v82 offset:7200
	s_waitcnt lgkmcnt(10)
	v_mfma_f32_16x16x32_bf16 v[42:45], v[132:135], v[144:147], v[42:45]
	ds_read_b128 v[164:167], v86
	ds_read_b128 v[168:171], v86 offset:1024
	s_waitcnt lgkmcnt(10)
	v_mfma_f32_16x16x32_bf16 v[46:49], v[132:135], v[148:151], v[46:49]
	s_waitcnt lgkmcnt(8)
	v_mfma_f32_16x16x32_bf16 v[172:175], v[112:115], v[96:99], 0
	ds_read_b128 v[200:203], v67 offset:0
	ds_read_b128 v[204:207], v67 offset:64
	s_waitcnt lgkmcnt(8)
	v_mfma_f32_16x16x32_bf16 v[172:175], v[116:119], v[100:103], v[172:175]
	ds_read_b128 v[208:211], v67 offset:128
	ds_read_b128 v[212:215], v67 offset:192
	s_waitcnt lgkmcnt(8)
	v_mfma_f32_16x16x32_bf16 v[172:175], v[120:123], v[104:107], v[172:175]
	s_cmp_eq_u32 s13, 0
	s_cbranch_scc1 .Lsc5_nox_0
	ds_read_b128 v[216:219], v70 offset:17408
	ds_read_b128 v[220:223], v70 offset:17472
	ds_read_b128 v[224:227], v70 offset:17536
	ds_read_b128 v[228:231], v70 offset:17600

; #define SCAN_BAR() asm volatile("s_waitcnt lgkmcnt(0)\n\ts_barrier" ::: "memory")
; __device__ void scan_phase(LAS unsigned char* lds, const Params& p) {
;     ...
;             SCAN_STAGE(1, k4B, q4B, v4B, rvB, tlB); SCAN_LOAD(min(n0 + 5, 67), k4B, q4B, v4B, rvB, tlB); SCAN_MAT(0, n0); SCAN_BAR();
;             SCAN_STAGE(0, k4C, q4C, v4C, rvC, tlC); SCAN_LOAD(min(n0 + 6, 67), k4C, q4C, v4C, rvC, tlC); SCAN_MAT(1, n0 + 1); SCAN_BAR();
.Lsc5_noy3_0:
	ds_write_b64 v85, v[160:161]
	ds_write_b64 v85, v[162:163] offset:1024
	s_waitcnt lgkmcnt(0)
	s_barrier
	ds_read_b32 v50, v79 offset:1024
	ds_read_b32 v51, v79 offset:1088
	ds_read_b64_tr_b16 v[128:129], v73 offset:34816
	ds_read_b64_tr_b16 v[130:131], v73 offset:35968
	ds_read_b64_tr_b16 v[132:133], v73 offset:37120
	ds_read_b64_tr_b16 v[134:135], v73 offset:38272
	ds_read_b64_tr_b16 v[136:137], v76 offset:17408
	ds_read_b64_tr_b16 v[138:139], v76 offset:21760
	ds_read_b64_tr_b16 v[140:141], v76 offset:17440
	ds_read_b64_tr_b16 v[142:143], v76 offset:21792
	ds_read_b64_tr_b16 v[144:145], v76 offset:26112
	ds_read_b64_tr_b16 v[146:147], v76 offset:30464
	ds_read_b64_tr_b16 v[148:149], v76 offset:26144
	ds_read_b64_tr_b16 v[150:151], v76 offset:30496
	s_add_u32 s3, s34, 5
	s_min_u32 s3, s3, 67
	s_cmp_lt_u32 s3, 4
	s_cselect_b32 s4, s16, s17
	s_mul_i32 s5, s3, s15
	s_add_i32 s4, s4, s5
	s_lshl_b32 s5, s4, 14
	s_lshl_b32 s4, s4, 11
	s_add_u32 s40, s18, s5
	s_addc_u32 s41, s19, 0
	s_add_u32 s42, s20, s5
	s_addc_u32 s43, s21, 0
	s_add_u32 s44, s22, s5
	s_addc_u32 s45, s23, 0
	s_add_u32 s46, s24, s4
	s_addc_u32 s47, s25, 0
	s_add_u32 s50, s26, s4
	s_addc_u32 s51, s27, 0
	global_load_dwordx4 v[180:183], v53, s[40:41]
	global_load_dwordx4 v[184:187], v54, s[40:41]
	global_load_dwordx4 v[188:191], v53, s[42:43]
	global_load_dwordx4 v[192:195], v54, s[42:43]
	global_load_dwordx2 v[196:197], v55, s[44:45]
	global_load_dword v198, v56, s[46:47]
	global_load_dword v199, v56, s[50:51]
	s_waitcnt lgkmcnt(6)
	v_mfma_f32_16x16x32_bf16 v[42:45], v[128:131], v[136:139], v[42:45]
	ds_read_b64_tr_b16 v[112:113], v83 offset:0
	ds_read_b64_tr_b16 v[114:115], v83 offset:288
	ds_read_b64_tr_b16 v[116:117], v83 offset:2304
	ds_read_b64_tr_b16 v[118:119], v83 offset:2592
	s_waitcnt lgkmcnt(8)
	v_mfma_f32_16x16x32_bf16 v[46:49], v[128:131], v[140:143], v[46:49]
	ds_read_b64_tr_b16 v[120:121], v83 offset:4608
	ds_read_b64_tr_b16 v[122:123], v83 offset:4896
	ds_read_b64_tr_b16 v[124:125], v83 offset:6912
	ds_read_b64_tr_b16 v[126:127], v83 offset:7200
	s_waitcnt lgkmcnt(10)
	v_mfma_f32_16x16x32_bf16 v[42:45], v[132:135], v[144:147], v[42:45]
	ds_read_b128 v[164:167], v87
	ds_read_b128 v[168:171], v87 offset:1024
	s_waitcnt lgkmcnt(10)
	v_mfma_f32_16x16x32_bf16 v[46:49], v[132:135], v[148:151], v[46:49]
	s_waitcnt lgkmcnt(8)
	v_mfma_f32_16x16x32_bf16 v[172:175], v[112:115], v[200:203], 0
	ds_read_b128 v[96:99], v68 offset:0
	ds_read_b128 v[100:103], v68 offset:64
	s_waitcnt lgkmcnt(8)
	v_mfma_f32_16x16x32_bf16 v[172:175], v[116:119], v[204:207], v[172:175]
	ds_read_b128 v[104:107], v68 offset:128
	ds_read_b128 v[108:111], v68 offset:192
	s_waitcnt lgkmcnt(8)
	v_mfma_f32_16x16x32_bf16 v[172:175], v[120:123], v[208:211], v[172:175]
	s_cmp_eq_u32 s13, 0
	s_cbranch_scc1 .Lsc5_nox_1
	ds_read_b128 v[216:219], v71 offset:17408
	ds_read_b128 v[220:223], v71 offset:17472
	ds_read_b128 v[224:227], v71 offset:17536
	ds_read_b128 v[228:231], v71 offset:17600

.Lsc5_noy3_1:
	ds_write_b64 v84, v[160:161]
	ds_write_b64 v84, v[162:163] offset:1024
	s_waitcnt lgkmcnt(0)
	s_barrier
	ds_read_b32 v50, v79 offset:0
	ds_read_b32 v51, v79 offset:64
	ds_read_b64_tr_b16 v[128:129], v74 offset:34816
	ds_read_b64_tr_b16 v[130:131], v74 offset:35968
	ds_read_b64_tr_b16 v[132:133], v74 offset:37120
	ds_read_b64_tr_b16 v[134:135], v74 offset:38272
	ds_read_b64_tr_b16 v[136:137], v77 offset:17408
	ds_read_b64_tr_b16 v[138:139], v77 offset:21760
	ds_read_b64_tr_b16 v[140:141], v77 offset:17440
	ds_read_b64_tr_b16 v[142:143], v77 offset:21792
	ds_read_b64_tr_b16 v[144:145], v77 offset:26112
	ds_read_b64_tr_b16 v[146:147], v77 offset:30464
	ds_read_b64_tr_b16 v[148:149], v77 offset:26144
	ds_read_b64_tr_b16 v[150:151], v77 offset:30496
	s_add_u32 s3, s34, 6
	s_min_u32 s3, s3, 67
	s_cmp_lt_u32 s3, 4
	s_cselect_b32 s4, s16, s17
	s_mul_i32 s5, s3, s15
	s_add_i32 s4, s4, s5
	s_lshl_b32 s5, s4, 14
	s_lshl_b32 s4, s4, 11
	s_add_u32 s40, s18, s5
	s_addc_u32 s41, s19, 0
	s_add_u32 s42, s20, s5
	s_addc_u32 s43, s21, 0
	s_add_u32 s44, s22, s5
	s_addc_u32 s45, s23, 0
	s_add_u32 s46, s24, s4
	s_addc_u32 s47, s25, 0
	s_add_u32 s50, s26, s4
	s_addc_u32 s51, s27, 0
	global_load_dwordx4 v[2:5], v53, s[40:41]
	global_load_dwordx4 v[6:9], v54, s[40:41]
	global_load_dwordx4 v[10:13], v53, s[42:43]
	global_load_dwordx4 v[14:17], v54, s[42:43]
	global_load_dwordx2 v[18:19], v55, s[44:45]
	global_load_dword v20, v56, s[46:47]
	global_load_dword v21, v56, s[50:51]
	s_waitcnt lgkmcnt(6)
	v_mfma_f32_16x16x32_bf16 v[42:45], v[128:131], v[136:139], v[42:45]
	ds_read_b64_tr_b16 v[112:113], v82 offset:0
	ds_read_b64_tr_b16 v[114:115], v82 offset:288
	ds_read_b64_tr_b16 v[116:117], v82 offset:2304
	ds_read_b64_tr_b16 v[118:119], v82 offset:2592
	s_waitcnt lgkmcnt(8)
	v_mfma_f32_16x16x32_bf16 v[46:49], v[128:131], v[140:143], v[46:49]
	ds_read_b64_tr_b16 v[120:121], v82 offset:4608
	ds_read_b64_tr_b16 v[122:123], v82 offset:4896
	ds_read_b64_tr_b16 v[124:125], v82 offset:6912
	ds_read_b64_tr_b16 v[126:127], v82 offset:7200
	s_waitcnt lgkmcnt(10)
	v_mfma_f32_16x16x32_bf16 v[42:45], v[132:135], v[144:147], v[42:45]
	ds_read_b128 v[164:167], v86
	ds_read_b128 v[168:171], v86 offset:1024
	s_waitcnt lgkmcnt(10)
	v_mfma_f32_16x16x32_bf16 v[46:49], v[132:135], v[148:151], v[46:49]
	s_waitcnt lgkmcnt(8)
	v_mfma_f32_16x16x32_bf16 v[172:175], v[112:115], v[96:99], 0
	ds_read_b128 v[200:203], v66 offset:0
	ds_read_b128 v[204:207], v66 offset:64
	s_waitcnt lgkmcnt(8)
	v_mfma_f32_16x16x32_bf16 v[172:175], v[116:119], v[100:103], v[172:175]
	ds_read_b128 v[208:211], v66 offset:128
	ds_read_b128 v[212:215], v66 offset:192
	s_waitcnt lgkmcnt(8)
	v_mfma_f32_16x16x32_bf16 v[172:175], v[120:123], v[104:107], v[172:175]
	s_cmp_eq_u32 s13, 0
	s_cbranch_scc1 .Lsc5_nox_2
	ds_read_b128 v[216:219], v69 offset:17408
	ds_read_b128 v[220:223], v69 offset:17472
	ds_read_b128 v[224:227], v69 offset:17536
	ds_read_b128 v[228:231], v69 offset:17600

.Lsc5_noy3_2:
	ds_write_b64 v85, v[160:161]
	ds_write_b64 v85, v[162:163] offset:1024
	s_waitcnt lgkmcnt(0)
	s_barrier
	ds_read_b32 v50, v79 offset:512
	ds_read_b32 v51, v79 offset:576
	ds_read_b64_tr_b16 v[128:129], v72 offset:34816
	ds_read_b64_tr_b16 v[130:131], v72 offset:35968
	ds_read_b64_tr_b16 v[132:133], v72 offset:37120
	ds_read_b64_tr_b16 v[134:135], v72 offset:38272
	ds_read_b64_tr_b16 v[136:137], v75 offset:17408
	ds_read_b64_tr_b16 v[138:139], v75 offset:21760
	ds_read_b64_tr_b16 v[140:141], v75 offset:17440
	ds_read_b64_tr_b16 v[142:143], v75 offset:21792
	ds_read_b64_tr_b16 v[144:145], v75 offset:26112
	ds_read_b64_tr_b16 v[146:147], v75 offset:30464
	ds_read_b64_tr_b16 v[148:149], v75 offset:26144
	ds_read_b64_tr_b16 v[150:151], v75 offset:30496
	s_add_u32 s3, s34, 7
	s_min_u32 s3, s3, 67
	s_cmp_lt_u32 s3, 4
	s_cselect_b32 s4, s16, s17
	s_mul_i32 s5, s3, s15
	s_add_i32 s4, s4, s5
	s_lshl_b32 s5, s4, 14
	s_lshl_b32 s4, s4, 11
	s_add_u32 s40, s18, s5
	s_addc_u32 s41, s19, 0
	s_add_u32 s42, s20, s5
	s_addc_u32 s43, s21, 0
	s_add_u32 s44, s22, s5
	s_addc_u32 s45, s23, 0
	s_add_u32 s46, s24, s4
	s_addc_u32 s47, s25, 0
	s_add_u32 s50, s26, s4
	s_addc_u32 s51, s27, 0
	global_load_dwordx4 v[22:25], v53, s[40:41]
	global_load_dwordx4 v[26:29], v54, s[40:41]
	global_load_dwordx4 v[30:33], v53, s[42:43]
	global_load_dwordx4 v[34:37], v54, s[42:43]
	global_load_dwordx2 v[38:39], v55, s[44:45]
	global_load_dword v40, v56, s[46:47]
	global_load_dword v41, v56, s[50:51]
	s_waitcnt lgkmcnt(6)
	v_mfma_f32_16x16x32_bf16 v[42:45], v[128:131], v[136:139], v[42:45]
	ds_read_b64_tr_b16 v[112:113], v83 offset:0
	ds_read_b64_tr_b16 v[114:115], v83 offset:288
	ds_read_b64_tr_b16 v[116:117], v83 offset:2304
	ds_read_b64_tr_b16 v[118:119], v83 offset:2592
	s_waitcnt lgkmcnt(8)
	v_mfma_f32_16x16x32_bf16 v[46:49], v[128:131], v[140:143], v[46:49]
	ds_read_b64_tr_b16 v[120:121], v83 offset:4608
	ds_read_b64_tr_b16 v[122:123], v83 offset:4896
	ds_read_b64_tr_b16 v[124:125], v83 offset:6912
	ds_read_b64_tr_b16 v[126:127], v83 offset:7200
	s_waitcnt lgkmcnt(10)
	v_mfma_f32_16x16x32_bf16 v[42:45], v[132:135], v[144:147], v[42:45]
	ds_read_b128 v[164:167], v87
	ds_read_b128 v[168:171], v87 offset:1024
	s_waitcnt lgkmcnt(10)
	v_mfma_f32_16x16x32_bf16 v[46:49], v[132:135], v[148:151], v[46:49]
	s_waitcnt lgkmcnt(8)
	v_mfma_f32_16x16x32_bf16 v[172:175], v[112:115], v[200:203], 0
	ds_read_b128 v[96:99], v67 offset:0
	ds_read_b128 v[100:103], v67 offset:64
	s_waitcnt lgkmcnt(8)
	v_mfma_f32_16x16x32_bf16 v[172:175], v[116:119], v[204:207], v[172:175]
	ds_read_b128 v[104:107], v67 offset:128
	ds_read_b128 v[108:111], v67 offset:192
	s_waitcnt lgkmcnt(8)
	v_mfma_f32_16x16x32_bf16 v[172:175], v[120:123], v[208:211], v[172:175]
	s_cmp_eq_u32 s13, 0
	s_cbranch_scc1 .Lsc5_nox_3
	ds_read_b128 v[216:219], v70 offset:17408
	ds_read_b128 v[220:223], v70 offset:17472
	ds_read_b128 v[224:227], v70 offset:17536
	ds_read_b128 v[228:231], v70 offset:17600

.Lsc5_noy3_3:
	ds_write_b64 v84, v[160:161]
	ds_write_b64 v84, v[162:163] offset:1024
	s_waitcnt lgkmcnt(0)
	s_barrier
	ds_read_b32 v50, v79 offset:1024
	ds_read_b32 v51, v79 offset:1088
	ds_read_b64_tr_b16 v[128:129], v73 offset:34816
	ds_read_b64_tr_b16 v[130:131], v73 offset:35968
	ds_read_b64_tr_b16 v[132:133], v73 offset:37120
	ds_read_b64_tr_b16 v[134:135], v73 offset:38272
	ds_read_b64_tr_b16 v[136:137], v76 offset:17408
	ds_read_b64_tr_b16 v[138:139], v76 offset:21760
	ds_read_b64_tr_b16 v[140:141], v76 offset:17440
	ds_read_b64_tr_b16 v[142:143], v76 offset:21792
	ds_read_b64_tr_b16 v[144:145], v76 offset:26112
	ds_read_b64_tr_b16 v[146:147], v76 offset:30464
	ds_read_b64_tr_b16 v[148:149], v76 offset:26144
	ds_read_b64_tr_b16 v[150:151], v76 offset:30496
	s_add_u32 s3, s34, 8
	s_min_u32 s3, s3, 67
	s_cmp_lt_u32 s3, 4
	s_cselect_b32 s4, s16, s17
	s_mul_i32 s5, s3, s15
	s_add_i32 s4, s4, s5
	s_lshl_b32 s5, s4, 14
	s_lshl_b32 s4, s4, 11
	s_add_u32 s40, s18, s5
	s_addc_u32 s41, s19, 0
	s_add_u32 s42, s20, s5
	s_addc_u32 s43, s21, 0
	s_add_u32 s44, s22, s5
	s_addc_u32 s45, s23, 0
	s_add_u32 s46, s24, s4
	s_addc_u32 s47, s25, 0
	s_add_u32 s50, s26, s4
	s_addc_u32 s51, s27, 0
	global_load_dwordx4 v[180:183], v53, s[40:41]
	global_load_dwordx4 v[184:187], v54, s[40:41]
	global_load_dwordx4 v[188:191], v53, s[42:43]
	global_load_dwordx4 v[192:195], v54, s[42:43]
	global_load_dwordx2 v[196:197], v55, s[44:45]
	global_load_dword v198, v56, s[46:47]
	global_load_dword v199, v56, s[50:51]
	s_waitcnt lgkmcnt(6)
	v_mfma_f32_16x16x32_bf16 v[42:45], v[128:131], v[136:139], v[42:45]
	ds_read_b64_tr_b16 v[112:113], v82 offset:0
	ds_read_b64_tr_b16 v[114:115], v82 offset:288
	ds_read_b64_tr_b16 v[116:117], v82 offset:2304
	ds_read_b64_tr_b16 v[118:119], v82 offset:2592
	s_waitcnt lgkmcnt(8)
	v_mfma_f32_16x16x32_bf16 v[46:49], v[128:131], v[140:143], v[46:49]
	ds_read_b64_tr_b16 v[120:121], v82 offset:4608
	ds_read_b64_tr_b16 v[122:123], v82 offset:4896
	ds_read_b64_tr_b16 v[124:125], v82 offset:6912
	ds_read_b64_tr_b16 v[126:127], v82 offset:7200
	s_waitcnt lgkmcnt(10)
	v_mfma_f32_16x16x32_bf16 v[42:45], v[132:135], v[144:147], v[42:45]
	ds_read_b128 v[164:167], v86
	ds_read_b128 v[168:171], v86 offset:1024
	s_waitcnt lgkmcnt(10)
	v_mfma_f32_16x16x32_bf16 v[46:49], v[132:135], v[148:151], v[46:49]
	s_waitcnt lgkmcnt(8)
	v_mfma_f32_16x16x32_bf16 v[172:175], v[112:115], v[96:99], 0
	ds_read_b128 v[200:203], v68 offset:0
	ds_read_b128 v[204:207], v68 offset:64
	s_waitcnt lgkmcnt(8)
	v_mfma_f32_16x16x32_bf16 v[172:175], v[116:119], v[100:103], v[172:175]
	ds_read_b128 v[208:211], v68 offset:128
	ds_read_b128 v[212:215], v68 offset:192
	s_waitcnt lgkmcnt(8)
	v_mfma_f32_16x16x32_bf16 v[172:175], v[120:123], v[104:107], v[172:175]
	s_cmp_eq_u32 s13, 0
	s_cbranch_scc1 .Lsc5_nox_4
	ds_read_b128 v[216:219], v71 offset:17408
	ds_read_b128 v[220:223], v71 offset:17472
	ds_read_b128 v[224:227], v71 offset:17536
	ds_read_b128 v[228:231], v71 offset:17600

.Lsc5_noy3_4:
	ds_write_b64 v85, v[160:161]
	ds_write_b64 v85, v[162:163] offset:1024
	s_waitcnt lgkmcnt(0)
	s_barrier
	ds_read_b32 v50, v79 offset:0
	ds_read_b32 v51, v79 offset:64
	ds_read_b64_tr_b16 v[128:129], v74 offset:34816
	ds_read_b64_tr_b16 v[130:131], v74 offset:35968
	ds_read_b64_tr_b16 v[132:133], v74 offset:37120
	ds_read_b64_tr_b16 v[134:135], v74 offset:38272
	ds_read_b64_tr_b16 v[136:137], v77 offset:17408
	ds_read_b64_tr_b16 v[138:139], v77 offset:21760
	ds_read_b64_tr_b16 v[140:141], v77 offset:17440
	ds_read_b64_tr_b16 v[142:143], v77 offset:21792
	ds_read_b64_tr_b16 v[144:145], v77 offset:26112
	ds_read_b64_tr_b16 v[146:147], v77 offset:30464
	ds_read_b64_tr_b16 v[148:149], v77 offset:26144
	ds_read_b64_tr_b16 v[150:151], v77 offset:30496
	s_add_u32 s3, s34, 9
	s_min_u32 s3, s3, 67
	s_cmp_lt_u32 s3, 4
	s_cselect_b32 s4, s16, s17
	s_mul_i32 s5, s3, s15
	s_add_i32 s4, s4, s5
	s_lshl_b32 s5, s4, 14
	s_lshl_b32 s4, s4, 11
	s_add_u32 s40, s18, s5
	s_addc_u32 s41, s19, 0
	s_add_u32 s42, s20, s5
	s_addc_u32 s43, s21, 0
	s_add_u32 s44, s22, s5
	s_addc_u32 s45, s23, 0
	s_add_u32 s46, s24, s4
	s_addc_u32 s47, s25, 0
	s_add_u32 s50, s26, s4
	s_addc_u32 s51, s27, 0
	global_load_dwordx4 v[2:5], v53, s[40:41]
	global_load_dwordx4 v[6:9], v54, s[40:41]
	global_load_dwordx4 v[10:13], v53, s[42:43]
	global_load_dwordx4 v[14:17], v54, s[42:43]
	global_load_dwordx2 v[18:19], v55, s[44:45]
	global_load_dword v20, v56, s[46:47]
	global_load_dword v21, v56, s[50:51]
	s_waitcnt lgkmcnt(6)
	v_mfma_f32_16x16x32_bf16 v[42:45], v[128:131], v[136:139], v[42:45]
	ds_read_b64_tr_b16 v[112:113], v83 offset:0
	ds_read_b64_tr_b16 v[114:115], v83 offset:288
	ds_read_b64_tr_b16 v[116:117], v83 offset:2304
	ds_read_b64_tr_b16 v[118:119], v83 offset:2592
	s_waitcnt lgkmcnt(8)
	v_mfma_f32_16x16x32_bf16 v[46:49], v[128:131], v[140:143], v[46:49]
	ds_read_b64_tr_b16 v[120:121], v83 offset:4608
	ds_read_b64_tr_b16 v[122:123], v83 offset:4896
	ds_read_b64_tr_b16 v[124:125], v83 offset:6912
	ds_read_b64_tr_b16 v[126:127], v83 offset:7200
	s_waitcnt lgkmcnt(10)
	v_mfma_f32_16x16x32_bf16 v[42:45], v[132:135], v[144:147], v[42:45]
	ds_read_b128 v[164:167], v87
	ds_read_b128 v[168:171], v87 offset:1024
	s_waitcnt lgkmcnt(10)
	v_mfma_f32_16x16x32_bf16 v[46:49], v[132:135], v[148:151], v[46:49]
	s_waitcnt lgkmcnt(8)
	v_mfma_f32_16x16x32_bf16 v[172:175], v[112:115], v[200:203], 0
	ds_read_b128 v[96:99], v66 offset:0
	ds_read_b128 v[100:103], v66 offset:64
	s_waitcnt lgkmcnt(8)
	v_mfma_f32_16x16x32_bf16 v[172:175], v[116:119], v[204:207], v[172:175]
	ds_read_b128 v[104:107], v66 offset:128
	ds_read_b128 v[108:111], v66 offset:192
	s_waitcnt lgkmcnt(8)
	v_mfma_f32_16x16x32_bf16 v[172:175], v[120:123], v[208:211], v[172:175]
	s_cmp_eq_u32 s13, 0
	s_cbranch_scc1 .Lsc5_nox_5
	ds_read_b128 v[216:219], v69 offset:17408
	ds_read_b128 v[220:223], v69 offset:17472
	ds_read_b128 v[224:227], v69 offset:17536
	ds_read_b128 v[228:231], v69 offset:17600

; #define SCAN_BAR() asm volatile("s_waitcnt lgkmcnt(0)\n\ts_barrier" ::: "memory")
; __device__ void scan_phase(LAS unsigned char* lds, const Params& p) {
;     ...
;         SCAN_LOAD(0, k4A, q4A, v4A, rvA, tlA); SCAN_LOAD(1, k4B, q4B, v4B, rvB, tlB); SCAN_LOAD(2, k4C, q4C, v4C, rvC, tlC); SCAN_LOAD(3, k4D, q4D, v4D, rvD, tlD);
;         SCAN_STAGE(0, k4A, q4A, v4A, rvA, tlA); SCAN_LOAD(4, k4A, q4A, v4A, rvA, tlA);
;         SCAN_BAR();
; #pragma unroll 1
;         for (int n0 = 0; n0 < 68; n0 += 4) {
;             SCAN_STAGE(1, k4B, q4B, v4B, rvB, tlB); SCAN_LOAD(min(n0 + 5, 67), k4B, q4B, v4B, rvB, tlB); SCAN_MAT(0, n0); SCAN_BAR();
;             SCAN_STAGE(0, k4C, q4C, v4C, rvC, tlC); SCAN_LOAD(min(n0 + 6, 67), k4C, q4C, v4C, rvC, tlC); SCAN_MAT(1, n0 + 1); SCAN_BAR();
;             SCAN_STAGE(1, k4D, q4D, v4D, rvD, tlD); SCAN_LOAD(min(n0 + 7, 67), k4D, q4D, v4D, rvD, tlD); SCAN_MAT(0, n0 + 2); SCAN_BAR();
;             SCAN_STAGE(0, k4A, q4A, v4A, rvA, tlA); SCAN_LOAD(min(n0 + 8, 67), k4A, q4A, v4A, rvA, tlA); SCAN_MAT(1, n0 + 3); SCAN_BAR();
.Lsc5_noy3_5:
	ds_write_b64 v84, v[160:161]
	ds_write_b64 v84, v[162:163] offset:1024
	s_waitcnt lgkmcnt(0)
	s_barrier
	s_add_u32 s34, s34, 6
	s_cmp_lt_u32 s34, 66
	s_cbranch_scc1 .Lsc5_loop
	ds_read_b32 v50, v79 offset:512
	ds_read_b32 v51, v79 offset:576
	ds_read_b64_tr_b16 v[128:129], v72 offset:34816
	ds_read_b64_tr_b16 v[130:131], v72 offset:35968
	ds_read_b64_tr_b16 v[132:133], v72 offset:37120
	ds_read_b64_tr_b16 v[134:135], v72 offset:38272
	ds_read_b64_tr_b16 v[136:137], v75 offset:17408
	ds_read_b64_tr_b16 v[138:139], v75 offset:21760
	ds_read_b64_tr_b16 v[140:141], v75 offset:17440
	ds_read_b64_tr_b16 v[142:143], v75 offset:21792
	ds_read_b64_tr_b16 v[144:145], v75 offset:26112
	ds_read_b64_tr_b16 v[146:147], v75 offset:30464
	ds_read_b64_tr_b16 v[148:149], v75 offset:26144
	ds_read_b64_tr_b16 v[150:151], v75 offset:30496
	s_add_u32 s3, s34, 4
	s_min_u32 s3, s3, 67
	s_cmp_lt_u32 s3, 4
	s_cselect_b32 s4, s16, s17
	s_mul_i32 s5, s3, s15
	s_add_i32 s4, s4, s5
	s_lshl_b32 s5, s4, 14
	s_lshl_b32 s4, s4, 11
	s_add_u32 s40, s18, s5
	s_addc_u32 s41, s19, 0
	s_add_u32 s42, s20, s5
	s_addc_u32 s43, s21, 0
	s_add_u32 s44, s22, s5
	s_addc_u32 s45, s23, 0
	s_add_u32 s46, s24, s4
	s_addc_u32 s47, s25, 0
	s_add_u32 s50, s26, s4
	s_addc_u32 s51, s27, 0
	global_load_dwordx4 v[22:25], v53, s[40:41]
	global_load_dwordx4 v[26:29], v54, s[40:41]
	global_load_dwordx4 v[30:33], v53, s[42:43]
	global_load_dwordx4 v[34:37], v54, s[42:43]
	global_load_dwordx2 v[38:39], v55, s[44:45]
	global_load_dword v40, v56, s[46:47]
	global_load_dword v41, v56, s[50:51]
	s_waitcnt lgkmcnt(6)
	v_mfma_f32_16x16x32_bf16 v[42:45], v[128:131], v[136:139], v[42:45]
	ds_read_b64_tr_b16 v[112:113], v82 offset:0
	ds_read_b64_tr_b16 v[114:115], v82 offset:288
	ds_read_b64_tr_b16 v[116:117], v82 offset:2304
	ds_read_b64_tr_b16 v[118:119], v82 offset:2592
	s_waitcnt lgkmcnt(8)
	v_mfma_f32_16x16x32_bf16 v[46:49], v[128:131], v[140:143], v[46:49]
	ds_read_b64_tr_b16 v[120:121], v82 offset:4608
	ds_read_b64_tr_b16 v[122:123], v82 offset:4896
	ds_read_b64_tr_b16 v[124:125], v82 offset:6912
	ds_read_b64_tr_b16 v[126:127], v82 offset:7200
	s_waitcnt lgkmcnt(10)
	v_mfma_f32_16x16x32_bf16 v[42:45], v[132:135], v[144:147], v[42:45]
	ds_read_b128 v[164:167], v86
	ds_read_b128 v[168:171], v86 offset:1024
	s_waitcnt lgkmcnt(10)
	v_mfma_f32_16x16x32_bf16 v[46:49], v[132:135], v[148:151], v[46:49]
	s_waitcnt lgkmcnt(8)
	v_mfma_f32_16x16x32_bf16 v[172:175], v[112:115], v[96:99], 0
	ds_read_b128 v[200:203], v67 offset:0
	ds_read_b128 v[204:207], v67 offset:64
	s_waitcnt lgkmcnt(8)
	v_mfma_f32_16x16x32_bf16 v[172:175], v[116:119], v[100:103], v[172:175]
	ds_read_b128 v[208:211], v67 offset:128
	ds_read_b128 v[212:215], v67 offset:192
	s_waitcnt lgkmcnt(8)
	v_mfma_f32_16x16x32_bf16 v[172:175], v[120:123], v[104:107], v[172:175]
	s_cmp_eq_u32 s13, 0
	s_cbranch_scc1 .Lsc5_nox_t0
	ds_read_b128 v[216:219], v70 offset:17408
	ds_read_b128 v[220:223], v70 offset:17472
	ds_read_b128 v[224:227], v70 offset:17536
	ds_read_b128 v[228:231], v70 offset:17600

.Lsc5_noy3_t0:
	ds_write_b64 v85, v[160:161]
	ds_write_b64 v85, v[162:163] offset:1024
	s_waitcnt lgkmcnt(0)
	s_barrier
	ds_read_b64_tr_b16 v[128:129], v73 offset:34816
	ds_read_b64_tr_b16 v[130:131], v73 offset:35968
	ds_read_b64_tr_b16 v[132:133], v73 offset:37120
	ds_read_b64_tr_b16 v[134:135], v73 offset:38272
	ds_read_b64_tr_b16 v[136:137], v76 offset:17408
	ds_read_b64_tr_b16 v[138:139], v76 offset:21760
	ds_read_b64_tr_b16 v[140:141], v76 offset:17440
	ds_read_b64_tr_b16 v[142:143], v76 offset:21792
	ds_read_b64_tr_b16 v[144:145], v76 offset:26112
	ds_read_b64_tr_b16 v[146:147], v76 offset:30464
	ds_read_b64_tr_b16 v[148:149], v76 offset:26144
	ds_read_b64_tr_b16 v[150:151], v76 offset:30496
	s_add_u32 s3, s34, 5
	s_min_u32 s3, s3, 67
	s_cmp_lt_u32 s3, 4
	s_cselect_b32 s4, s16, s17
	s_mul_i32 s5, s3, s15
	s_add_i32 s4, s4, s5
	s_lshl_b32 s5, s4, 14
	s_lshl_b32 s4, s4, 11
	s_add_u32 s40, s18, s5
	s_addc_u32 s41, s19, 0
	s_add_u32 s42, s20, s5
	s_addc_u32 s43, s21, 0
	s_add_u32 s44, s22, s5
	s_addc_u32 s45, s23, 0
	s_add_u32 s46, s24, s4
	s_addc_u32 s47, s25, 0
	s_add_u32 s50, s26, s4
	s_addc_u32 s51, s27, 0
	global_load_dwordx4 v[180:183], v53, s[40:41]
	global_load_dwordx4 v[184:187], v54, s[40:41]
	global_load_dwordx4 v[188:191], v53, s[42:43]
	global_load_dwordx4 v[192:195], v54, s[42:43]
	global_load_dwordx2 v[196:197], v55, s[44:45]
	global_load_dword v198, v56, s[46:47]
	global_load_dword v199, v56, s[50:51]
	s_waitcnt lgkmcnt(6)
	v_mfma_f32_16x16x32_bf16 v[42:45], v[128:131], v[136:139], v[42:45]
	ds_read_b64_tr_b16 v[112:113], v83 offset:0
	ds_read_b64_tr_b16 v[114:115], v83 offset:288
	ds_read_b64_tr_b16 v[116:117], v83 offset:2304
	ds_read_b64_tr_b16 v[118:119], v83 offset:2592
	s_waitcnt lgkmcnt(8)
	v_mfma_f32_16x16x32_bf16 v[46:49], v[128:131], v[140:143], v[46:49]
	ds_read_b64_tr_b16 v[120:121], v83 offset:4608
	ds_read_b64_tr_b16 v[122:123], v83 offset:4896
	ds_read_b64_tr_b16 v[124:125], v83 offset:6912
	ds_read_b64_tr_b16 v[126:127], v83 offset:7200
	s_waitcnt lgkmcnt(10)
	v_mfma_f32_16x16x32_bf16 v[42:45], v[132:135], v[144:147], v[42:45]
	ds_read_b128 v[164:167], v87
	ds_read_b128 v[168:171], v87 offset:1024
	s_waitcnt lgkmcnt(10)
	v_mfma_f32_16x16x32_bf16 v[46:49], v[132:135], v[148:151], v[46:49]
	s_waitcnt lgkmcnt(8)
	v_mfma_f32_16x16x32_bf16 v[172:175], v[112:115], v[200:203], 0
	s_waitcnt lgkmcnt(6)
	v_mfma_f32_16x16x32_bf16 v[172:175], v[116:119], v[204:207], v[172:175]
	s_waitcnt lgkmcnt(4)
	v_mfma_f32_16x16x32_bf16 v[172:175], v[120:123], v[208:211], v[172:175]
	s_waitcnt lgkmcnt(2)
	v_mfma_f32_16x16x32_bf16 v[172:175], v[124:127], v[212:215], v[172:175]
	s_waitcnt lgkmcnt(1)
	v_mfma_f32_16x16x32_bf16 v[172:175], v[128:131], v[164:167], v[172:175]
	s_waitcnt lgkmcnt(0)
	s_cmp_eq_u32 s11, 0
	s_cbranch_scc1 .Lsc5_nopv1_t1
	v_mfma_f32_16x16x32_bf16 v[172:175], v[132:135], v[168:171], v[172:175]
